# LN phases read g/b from an LDS copy (no per-step global loads / vmcnt(0) store drains); GEMM unit-boundary edits; first seam uses xcd barrier
# speedup vs baseline: 1.0017x; 1.0017x over previous
; __device__ __forceinline__ void xcd_barrier(const XcdBarrier& b) {
;     asm volatile("s_waitcnt vmcnt(0)" ::: "memory");
;     __syncthreads();
;     if (threadIdx.x == 0) {
;         unsigned* bar = b.bar;
;         __builtin_amdgcn_s_waitcnt(0);
;         unsigned nloc = b.st[0], nx = b.st[1];
;         if (nloc == 0u) { xcd_barrier_complete(bar, b.x, nloc, nx); b.st[0] = nloc; b.st[1] = nx; }
; __global__ void __launch_bounds__(512, 2) fwd_megakernel(Args a) {
;     ...
;     for (int ph = a.ph_lo; ph < a.ph_hi; ++ph) {
;         if (ph == a.ph_lo + 1) cg::this_grid().sync();
;         else if (ph > a.ph_lo) xcd_barrier(bar);
.LBB0_9:
	v_readlane_b32 s0, v252, 10
	s_mov_b64 s[2:3], 0
	s_cmp_lg_u32 s8, s0
	s_mov_b64 s[0:1], -1
	v_writelane_b32 v251, s8, 1
	v_readlane_b32 s2, v252, 6
	v_readlane_b32 s3, v252, 7
	v_readlane_b32 s3, v251, 1
	s_mov_b64 s[0:1], 0
	s_cmp_gt_i32 s3, s2
	s_mov_b64 s[2:3], 0
	s_cbranch_scc0 .LBB0_64
	s_waitcnt vmcnt(0)
	s_barrier
	s_mov_b64 s[2:3], exec
	v_readlane_b32 s4, v252, 4
	v_readlane_b32 s5, v252, 5
	s_and_b64 s[4:5], s[2:3], s[4:5]
	s_mov_b64 exec, s[4:5]
	s_cbranch_execz .LBB0_63
	v_readlane_b32 s4, v254, 4
	s_waitcnt vmcnt(0) expcnt(0) lgkmcnt(0)
	s_nop 0
	v_mov_b32_e32 v1, s4
	ds_read_b32 v3, v1
	v_readlane_b32 s4, v254, 5
	s_waitcnt lgkmcnt(0)
	v_cmp_ne_u32_e32 vcc, 0, v3
	v_mov_b32_e32 v1, s4
	ds_read_b32 v2, v1
	s_cbranch_vccnz .LBB0_27
	v_readlane_b32 s6, v252, 2
	v_readlane_b32 s7, v252, 3
	s_load_dwordx2 s[4:5], s[6:7], 0x4
	s_waitcnt lgkmcnt(0)
	s_mul_i32 s4, s4, s29
	s_mul_i32 s4, s4, s5
	s_mov_b32 s5, 1
	s_branch .LBB0_15

; __global__ void __launch_bounds__(512, 2) fwd_megakernel(Args a) {
;     ...
;         if (ph == a.ph_lo + 1) cg::this_grid().sync();
;         else if (ph > a.ph_lo) xcd_barrier(bar);
.LBB0_64:
.LBB0_76:
	s_and_b64 vcc, exec, s[2:3]
	s_cbranch_vccz .LBB0_78

; #define LAS __attribute__((address_space(3)))
; __device__ __forceinline__ int ltid() { int t = threadIdx.x; asm volatile("" : "+v"(t)); return t; }
; template <int NR>
; __device__ __forceinline__ void ln_comb(bf16_t* h, const bf16_t* sb, float scale, const float* g, const float* b, int lane) {
;     u32x4 hv[NR][4], sv[NR][4]; f32x4 v[NR][4][2]; float sm[NR];
; #pragma unroll
;     for (int i = 0; i < NR; ++i)
; #pragma unroll
;         for (int j = 0; j < 4; ++j) { hv[i][j] = *(const u32x4*)(h + (size_t)i * D + 8 * lane + 512 * j); sv[i][j] = *(const u32x4*)(sb + (size_t)i * D + 8 * lane + 512 * j); }
; template <int MODE>
; __device__ __forceinline__ void ln_phase(const Args& a, const float* g, const float* b, int nrows, float scale) {
;     ...
;         const bf16_t* sbuf = (const bf16_t*)a.out;
;         for (int r = 3 * gw; r < NTOK; r += 3 * NGW) ln_comb<3>(hb + (size_t)r * D, sbuf + (size_t)r * D, scale, g, b, lane);
; __device__ __forceinline__ void fill_gb(LAS unsigned char* lds, const float* g, const float* b) {
;     const int tid = ltid(); LAS float* gb = (LAS float*)(lds + LDS_GB);
;     *(LAS f32x4*)(gb + 4 * tid) = *(const f32x4*)(g + 4 * tid); *(LAS f32x4*)(gb + D + 4 * tid) = *(const f32x4*)(b + 4 * tid) * ALPHA;
;     __syncthreads();
; }
.LBB0_88:
	v_readlane_b32 s0, v251, 6
	v_readlane_b32 s1, v251, 7
	s_lshl_b64 s[0:1], s[0:1], 2
	s_add_u32 s20, s66, s0
	s_addc_u32 s21, s67, s1
	v_readlane_b32 s2, v254, 9
	v_readlane_b32 s3, v254, 10
	s_add_u32 s30, s2, s0
	v_mov_b32_e32 v1, v155
	s_mov_b32 s0, s22
	s_addc_u32 s31, s3, s1
	s_lshl_b32 s36, s0, 3
	v_ashrrev_i32_e32 v34, 6, v1
	v_and_b32_e32 v109, 63, v1
	v_add_u32_e32 v35, s36, v34
	v_cmp_gt_i32_e32 vcc, s79, v35
	v_lshlrev_b32_e32 v36, 4, v109
	v_lshlrev_b32_e32 v2, 4, v155
	global_load_dwordx4 v[6:9], v2, s[20:21]
	global_load_dwordx4 v[14:17], v2, s[30:31]
	v_add_u32_e32 v2, 0x20000, v2
	s_waitcnt vmcnt(0)
	ds_write_b128 v2, v[6:9]
	ds_write_b128 v2, v[14:17] offset:8192
	s_waitcnt lgkmcnt(0)
	s_barrier
	s_and_saveexec_b64 s[2:3], vcc
	s_cbranch_execz .LBB0_91
	v_xor_b32_e32 v1, 1, v201
	v_cmp_lt_i32_e32 vcc, v1, v202
	v_lshl_add_u32 v38, v35, 1, v35
	v_lshlrev_b32_e32 v2, 5, v109
	v_cndmask_b32_e32 v1, v201, v1, vcc
	v_lshlrev_b32_e32 v111, 2, v1
	v_xor_b32_e32 v1, 2, v201
	v_cmp_lt_i32_e32 vcc, v1, v202
	v_mov_b32_e32 v3, v0
	v_add_u32_e32 v40, 0x20000, v2
	v_cndmask_b32_e32 v1, v201, v1, vcc
	v_lshlrev_b32_e32 v113, 2, v1
	v_xor_b32_e32 v1, 4, v201
	v_cmp_lt_i32_e32 vcc, v1, v202
	v_or_b32_e32 v4, 0x1000, v2
	v_cndmask_b32_e32 v1, v201, v1, vcc
	v_lshlrev_b32_e32 v148, 2, v1
	v_xor_b32_e32 v1, 8, v201
	v_cmp_lt_i32_e32 vcc, v1, v202
	v_or_b32_e32 v2, 0x1800, v2
	v_ashrrev_i32_e32 v39, 31, v38
	v_cndmask_b32_e32 v1, v201, v1, vcc
	v_lshlrev_b32_e32 v149, 2, v1
	v_xor_b32_e32 v1, 16, v201
	v_cmp_lt_i32_e32 vcc, v1, v202
	v_readlane_b32 s4, v253, 58
	v_mov_b32_e32 v5, v0
	v_cndmask_b32_e32 v1, v201, v1, vcc
	v_lshlrev_b32_e32 v150, 2, v1
	v_xor_b32_e32 v1, 32, v201
	v_cmp_lt_i32_e32 vcc, v1, v202
	v_cndmask_b32_e32 v1, v201, v1, vcc
	v_lshlrev_b64 v[2:3], 12, v[38:39]
	v_readlane_b32 s8, v253, 62
	v_readlane_b32 s9, v253, 63
	v_readlane_b32 s10, v254, 0
	v_readlane_b32 s11, v254, 1
	v_lshlrev_b32_e32 v151, 2, v1
	v_mov_b32_e32 v37, v0
	s_waitcnt vmcnt(0)
	v_lshl_add_u64 v[52:53], s[10:11], 0, v[2:3]
	v_lshl_add_u64 v[54:55], s[8:9], 0, v[2:3]
	s_mov_b64 s[46:47], 0
	v_readlane_b32 s5, v253, 59
	v_readlane_b32 s6, v253, 60
	v_readlane_b32 s7, v253, 61
.LBB0_90:
	v_lshl_add_u64 v[60:61], v[52:53], 0, v[36:37]
	v_lshl_add_u64 v[2:3], v[54:55], 0, v[36:37]
	global_load_dwordx4 v[62:65], v[60:61], off
	global_load_dwordx4 v[66:69], v[2:3], off
	global_load_dwordx4 v[70:73], v[60:61], off offset:1024
	global_load_dwordx4 v[74:77], v[2:3], off offset:1024
	global_load_dwordx4 v[78:81], v[60:61], off offset:2048
	global_load_dwordx4 v[82:85], v[2:3], off offset:2048
	global_load_dwordx4 v[86:89], v[60:61], off offset:3072
	global_load_dwordx4 v[90:93], v[2:3], off offset:3072
	v_add_co_u32_e32 v56, vcc, 0x1000, v60
	v_add_u32_e32 v38, s96, v38
	s_nop 0
	v_addc_co_u32_e32 v57, vcc, 0, v61, vcc
	global_load_dwordx4 v[100:103], v[56:57], off
	v_add_co_u32_e32 v4, vcc, 0x1000, v2
	v_lshl_add_u64 v[52:53], v[52:53], 0, s[16:17]
	s_nop 0
	v_addc_co_u32_e32 v5, vcc, 0, v3, vcc
	global_load_dwordx4 v[104:107], v[4:5], off
	global_load_dwordx4 v[114:117], v[56:57], off offset:1024
	global_load_dwordx4 v[118:121], v[4:5], off offset:1024
	global_load_dwordx4 v[140:143], v[56:57], off offset:2048
	global_load_dwordx4 v[144:147], v[4:5], off offset:2048
	global_load_dwordx4 v[160:163], v[56:57], off offset:3072
	global_load_dwordx4 v[164:167], v[4:5], off offset:3072
	v_add_co_u32_e32 v58, vcc, 0x2000, v60
	v_lshl_add_u64 v[54:55], v[54:55], 0, s[16:17]
	s_nop 0
	v_addc_co_u32_e32 v59, vcc, 0, v61, vcc
	global_load_dwordx4 v[30:33], v[58:59], off
	v_add_co_u32_e32 v2, vcc, 0x2000, v2
	v_addc_co_u32_e32 v3, vcc, 0, v3, vcc
	global_load_dwordx4 v[26:29], v[2:3], off
	global_load_dwordx4 v[22:25], v[58:59], off offset:1024
	global_load_dwordx4 v[18:21], v[2:3], off offset:1024
	global_load_dwordx4 v[14:17], v[58:59], off offset:2048
	global_load_dwordx4 v[10:13], v[2:3], off offset:2048
	global_load_dwordx4 v[6:9], v[58:59], off offset:3072
	s_nop 0
	global_load_dwordx4 v[2:5], v[2:3], off offset:3072
	s_waitcnt vmcnt(23)
	v_lshlrev_b32_e32 v94, 16, v62
	v_and_b32_e32 v95, 0xffff0000, v62
	v_lshlrev_b32_e32 v96, 16, v64
	v_and_b32_e32 v97, 0xffff0000, v64
	s_waitcnt vmcnt(22)
	v_lshlrev_b32_e32 v98, 16, v66
	v_and_b32_e32 v99, 0xffff0000, v66
	v_lshlrev_b32_e32 v122, 16, v68
	v_and_b32_e32 v123, 0xffff0000, v68
	v_lshlrev_b32_e32 v62, 16, v63
	v_and_b32_e32 v63, 0xffff0000, v63
	v_lshlrev_b32_e32 v64, 16, v65
	v_and_b32_e32 v65, 0xffff0000, v65
	v_lshlrev_b32_e32 v66, 16, v67
	v_and_b32_e32 v67, 0xffff0000, v67
	v_lshlrev_b32_e32 v68, 16, v69
	v_and_b32_e32 v69, 0xffff0000, v69
	v_pk_fma_f32 v[130:131], v[94:95], s[24:25], v[98:99] op_sel_hi:[1,0,1]
	v_pk_fma_f32 v[126:127], v[96:97], s[24:25], v[122:123] op_sel_hi:[1,0,1]
	v_pk_fma_f32 v[128:129], v[62:63], s[24:25], v[66:67] op_sel_hi:[1,0,1]
	v_pk_fma_f32 v[124:125], v[64:65], s[24:25], v[68:69] op_sel_hi:[1,0,1]
	v_mov_b32_e32 v62, v130
	v_mov_b32_e32 v63, v126
	v_mov_b32_e32 v64, v131
	v_mov_b32_e32 v65, v127
	v_pk_add_f32 v[62:63], v[62:63], v[64:65]
	v_mov_b32_e32 v64, v128
	v_mov_b32_e32 v65, v124
	v_mov_b32_e32 v66, v129
	v_mov_b32_e32 v67, v125
	v_pk_add_f32 v[64:65], v[64:65], v[66:67]
	s_waitcnt vmcnt(21)
	v_lshlrev_b32_e32 v66, 16, v72
	v_pk_add_f32 v[62:63], v[62:63], v[64:65]
	v_lshlrev_b32_e32 v64, 16, v71
	v_pk_add_f32 v[132:133], v[62:63], v[62:63] op_sel:[0,1] op_sel_hi:[1,0]
	v_lshlrev_b32_e32 v62, 16, v70
	v_and_b32_e32 v63, 0xffff0000, v70
	v_and_b32_e32 v65, 0xffff0000, v71
	v_and_b32_e32 v67, 0xffff0000, v72
	v_lshlrev_b32_e32 v68, 16, v73
	v_and_b32_e32 v69, 0xffff0000, v73
	s_waitcnt vmcnt(20)
; __device__ __forceinline__ void unpack8v(const u32x4 w, f32x4& lo, f32x4& hi) { lo = (f32x4){bf_lo(w.x), bf_hi(w.x), bf_lo(w.y), bf_hi(w.y)}; hi = (f32x4){bf_lo(w.z), bf_hi(w.z), bf_lo(w.w), bf_hi(w.w)}; }
; template <int NR>
; __device__ __forceinline__ void ln_comb(bf16_t* h, const bf16_t* sb, float scale, const float* g, const float* b, int lane) {
;     ...
; #pragma unroll
;     for (int i = 0; i < NR; ++i) { float s = 0.f;
; #pragma unroll
;         for (int j = 0; j < 4; ++j) { f32x4 h0, h1, s0, s1; unpack8v(hv[i][j], h0, h1); unpack8v(sv[i][j], s0, s1);
;             v[i][j][0] = h0 * ALPHA + s0 * scale; v[i][j][1] = h1 * ALPHA + s1 * scale;
;             s += ((v[i][j][0].x + v[i][j][0].y) + (v[i][j][0].z + v[i][j][0].w)) + ((v[i][j][1].x + v[i][j][1].y) + (v[i][j][1].z + v[i][j][1].w)); }
;         sm[i] = s; }
	v_lshlrev_b32_e32 v70, 16, v74
	v_and_b32_e32 v71, 0xffff0000, v74
	v_lshlrev_b32_e32 v72, 16, v75
	v_and_b32_e32 v73, 0xffff0000, v75
	v_pk_fma_f32 v[98:99], v[64:65], s[24:25], v[72:73] op_sel_hi:[1,0,1]
	v_pk_fma_f32 v[122:123], v[62:63], s[24:25], v[70:71] op_sel_hi:[1,0,1]
	v_lshlrev_b32_e32 v74, 16, v76
	v_and_b32_e32 v75, 0xffff0000, v76
	v_lshlrev_b32_e32 v76, 16, v77
	v_and_b32_e32 v77, 0xffff0000, v77
	v_pk_mov_b32 v[62:63], v[122:123], v[98:99] op_sel:[1,0]
	v_mov_b32_e32 v64, v122
	v_mov_b32_e32 v65, v99
	v_pk_fma_f32 v[94:95], v[68:69], s[24:25], v[76:77] op_sel_hi:[1,0,1]
	v_pk_fma_f32 v[96:97], v[66:67], s[24:25], v[74:75] op_sel_hi:[1,0,1]
	v_pk_add_f32 v[62:63], v[62:63], v[64:65]
	v_mov_b32_e32 v64, v96
	v_pk_add_f32 v[70:71], v[62:63], v[62:63] op_sel:[0,1] op_sel_hi:[1,0]
	v_pk_mov_b32 v[62:63], v[96:97], v[94:95] op_sel:[1,0]
	v_mov_b32_e32 v65, v95
	v_pk_add_f32 v[62:63], v[62:63], v[64:65]
	s_waitcnt vmcnt(19)
	v_lshlrev_b32_e32 v64, 16, v79
	v_pk_add_f32 v[72:73], v[62:63], v[62:63] op_sel:[0,1] op_sel_hi:[1,0]
	v_lshlrev_b32_e32 v62, 16, v78
	v_and_b32_e32 v63, 0xffff0000, v78
	v_and_b32_e32 v65, 0xffff0000, v79
	v_lshlrev_b32_e32 v66, 16, v80
	v_and_b32_e32 v67, 0xffff0000, v80
	v_lshlrev_b32_e32 v68, 16, v81
	v_and_b32_e32 v69, 0xffff0000, v81
	s_waitcnt vmcnt(18)
	v_lshlrev_b32_e32 v74, 16, v82
	v_and_b32_e32 v75, 0xffff0000, v82
	v_lshlrev_b32_e32 v76, 16, v83
	v_and_b32_e32 v77, 0xffff0000, v83
	v_lshlrev_b32_e32 v80, 16, v84
	v_and_b32_e32 v81, 0xffff0000, v84
	v_lshlrev_b32_e32 v78, 16, v85
	v_and_b32_e32 v79, 0xffff0000, v85
	v_pk_fma_f32 v[82:83], v[64:65], s[24:25], v[76:77] op_sel_hi:[1,0,1]
	v_pk_fma_f32 v[84:85], v[62:63], s[24:25], v[74:75] op_sel_hi:[1,0,1]
	v_pk_fma_f32 v[78:79], v[68:69], s[24:25], v[78:79] op_sel_hi:[1,0,1]
	v_pk_fma_f32 v[80:81], v[66:67], s[24:25], v[80:81] op_sel_hi:[1,0,1]
	s_waitcnt vmcnt(17)
	v_lshlrev_b32_e32 v62, 16, v86
	v_and_b32_e32 v63, 0xffff0000, v86
	v_lshlrev_b32_e32 v64, 16, v87
	v_and_b32_e32 v65, 0xffff0000, v87
	v_lshlrev_b32_e32 v86, 16, v88
	v_and_b32_e32 v87, 0xffff0000, v88
	v_lshlrev_b32_e32 v88, 16, v89
	v_and_b32_e32 v89, 0xffff0000, v89
	s_waitcnt vmcnt(16)
	v_lshlrev_b32_e32 v68, 16, v90
	v_and_b32_e32 v69, 0xffff0000, v90
	v_lshlrev_b32_e32 v66, 16, v91
	v_and_b32_e32 v67, 0xffff0000, v91
	v_lshlrev_b32_e32 v90, 16, v92
	v_and_b32_e32 v91, 0xffff0000, v92
	v_lshlrev_b32_e32 v92, 16, v93
	v_and_b32_e32 v93, 0xffff0000, v93
	v_pk_fma_f32 v[66:67], v[64:65], s[24:25], v[66:67] op_sel_hi:[1,0,1]
	v_pk_fma_f32 v[68:69], v[62:63], s[24:25], v[68:69] op_sel_hi:[1,0,1]
	v_pk_fma_f32 v[62:63], v[88:89], s[24:25], v[92:93] op_sel_hi:[1,0,1]
	v_pk_fma_f32 v[64:65], v[86:87], s[24:25], v[90:91] op_sel_hi:[1,0,1]
	v_add_f32_e32 v74, v84, v85
	v_add_f32_e32 v76, v82, v83
	v_add_f32_e32 v134, v80, v81
	v_add_f32_e32 v136, v78, v79
	v_mov_b32_e32 v133, v68
	v_mov_b32_e32 v1, v69
	v_mov_b32_e32 v71, v66
	v_mov_b32_e32 v73, v67
	v_mov_b32_e32 v75, v64
	v_mov_b32_e32 v77, v65
	v_mov_b32_e32 v135, v62
	v_mov_b32_e32 v137, v63
	v_pk_add_f32 v[86:87], v[132:133], v[0:1]
	v_pk_add_f32 v[70:71], v[70:71], v[72:73]
	v_pk_add_f32 v[72:73], v[74:75], v[76:77]
	v_pk_add_f32 v[74:75], v[134:135], v[136:137]
	v_pk_add_f32 v[70:71], v[86:87], v[70:71]
	v_pk_add_f32 v[72:73], v[72:73], v[74:75]
	s_waitcnt vmcnt(15)
	v_lshlrev_b32_e32 v74, 16, v102
	v_pk_add_f32 v[70:71], v[70:71], v[72:73]
	v_and_b32_e32 v75, 0xffff0000, v102
	v_add_f32_e32 v39, v70, v71
	v_lshlrev_b32_e32 v70, 16, v100
	v_and_b32_e32 v71, 0xffff0000, v100
	s_waitcnt vmcnt(14)
	v_lshlrev_b32_e32 v86, 16, v104
	v_and_b32_e32 v87, 0xffff0000, v104
	v_lshlrev_b32_e32 v90, 16, v106
	v_and_b32_e32 v91, 0xffff0000, v106
	v_lshlrev_b32_e32 v72, 16, v101
	v_and_b32_e32 v73, 0xffff0000, v101
	v_lshlrev_b32_e32 v76, 16, v103
	v_and_b32_e32 v77, 0xffff0000, v103
	v_lshlrev_b32_e32 v88, 16, v105
	v_and_b32_e32 v89, 0xffff0000, v105
	v_lshlrev_b32_e32 v92, 16, v107
	v_and_b32_e32 v93, 0xffff0000, v107
	v_pk_fma_f32 v[138:139], v[70:71], s[24:25], v[86:87] op_sel_hi:[1,0,1]
	v_pk_fma_f32 v[136:137], v[74:75], s[24:25], v[90:91] op_sel_hi:[1,0,1]
	v_pk_fma_f32 v[134:135], v[72:73], s[24:25], v[88:89] op_sel_hi:[1,0,1]
	v_pk_fma_f32 v[132:133], v[76:77], s[24:25], v[92:93] op_sel_hi:[1,0,1]
	v_mov_b32_e32 v70, v138
	v_mov_b32_e32 v71, v136
	v_mov_b32_e32 v72, v139
	v_mov_b32_e32 v73, v137
	v_pk_add_f32 v[70:71], v[70:71], v[72:73]
	v_mov_b32_e32 v72, v134
	v_mov_b32_e32 v73, v132
	v_mov_b32_e32 v74, v135
	v_mov_b32_e32 v75, v133
	v_pk_add_f32 v[72:73], v[72:73], v[74:75]
	s_waitcnt vmcnt(12)
	v_lshlrev_b32_e32 v86, 16, v118
	v_pk_add_f32 v[70:71], v[70:71], v[72:73]
	v_lshlrev_b32_e32 v72, 16, v115
	v_pk_add_f32 v[152:153], v[70:71], v[70:71] op_sel:[0,1] op_sel_hi:[1,0]
	v_lshlrev_b32_e32 v70, 16, v114
	v_and_b32_e32 v71, 0xffff0000, v114
	v_and_b32_e32 v73, 0xffff0000, v115
	v_and_b32_e32 v87, 0xffff0000, v118
	v_lshlrev_b32_e32 v88, 16, v119
	v_and_b32_e32 v89, 0xffff0000, v119
	v_pk_fma_f32 v[104:105], v[72:73], s[24:25], v[88:89] op_sel_hi:[1,0,1]
	v_pk_fma_f32 v[106:107], v[70:71], s[24:25], v[86:87] op_sel_hi:[1,0,1]
	v_lshlrev_b32_e32 v74, 16, v116
	v_and_b32_e32 v75, 0xffff0000, v116
	v_lshlrev_b32_e32 v76, 16, v117
	v_and_b32_e32 v77, 0xffff0000, v117
	v_lshlrev_b32_e32 v90, 16, v120
	v_and_b32_e32 v91, 0xffff0000, v120
	v_lshlrev_b32_e32 v92, 16, v121
	v_and_b32_e32 v93, 0xffff0000, v121
	v_pk_mov_b32 v[70:71], v[106:107], v[104:105] op_sel:[1,0]
	v_mov_b32_e32 v72, v106
	v_mov_b32_e32 v73, v105
	v_pk_fma_f32 v[100:101], v[76:77], s[24:25], v[92:93] op_sel_hi:[1,0,1]
	v_pk_fma_f32 v[102:103], v[74:75], s[24:25], v[90:91] op_sel_hi:[1,0,1]
	v_pk_add_f32 v[70:71], v[70:71], v[72:73]
	v_mov_b32_e32 v72, v102
	v_pk_add_f32 v[114:115], v[70:71], v[70:71] op_sel:[0,1] op_sel_hi:[1,0]
	v_pk_mov_b32 v[70:71], v[102:103], v[100:101] op_sel:[1,0]
	v_mov_b32_e32 v73, v101
	v_pk_add_f32 v[70:71], v[70:71], v[72:73]
	s_waitcnt vmcnt(11)
; __device__ __forceinline__ void unpack8v(const u32x4 w, f32x4& lo, f32x4& hi) { lo = (f32x4){bf_lo(w.x), bf_hi(w.x), bf_lo(w.y), bf_hi(w.y)}; hi = (f32x4){bf_lo(w.z), bf_hi(w.z), bf_lo(w.w), bf_hi(w.w)}; }
; template <int NR>
; __device__ __forceinline__ void ln_comb(bf16_t* h, const bf16_t* sb, float scale, const float* g, const float* b, int lane) {
;     ...
; #pragma unroll
;     for (int i = 0; i < NR; ++i) { float s = 0.f;
; #pragma unroll
;         for (int j = 0; j < 4; ++j) { f32x4 h0, h1, s0, s1; unpack8v(hv[i][j], h0, h1); unpack8v(sv[i][j], s0, s1);
;             v[i][j][0] = h0 * ALPHA + s0 * scale; v[i][j][1] = h1 * ALPHA + s1 * scale;
;             s += ((v[i][j][0].x + v[i][j][0].y) + (v[i][j][0].z + v[i][j][0].w)) + ((v[i][j][1].x + v[i][j][1].y) + (v[i][j][1].z + v[i][j][1].w)); }
;         sm[i] = s; }
	v_lshlrev_b32_e32 v72, 16, v141
	v_pk_add_f32 v[116:117], v[70:71], v[70:71] op_sel:[0,1] op_sel_hi:[1,0]
	v_lshlrev_b32_e32 v70, 16, v140
	v_and_b32_e32 v71, 0xffff0000, v140
	v_and_b32_e32 v73, 0xffff0000, v141
	v_lshlrev_b32_e32 v74, 16, v142
	v_and_b32_e32 v75, 0xffff0000, v142
	v_lshlrev_b32_e32 v76, 16, v143
	v_and_b32_e32 v77, 0xffff0000, v143
	s_waitcnt vmcnt(10)
	v_lshlrev_b32_e32 v86, 16, v144
	v_and_b32_e32 v87, 0xffff0000, v144
	v_lshlrev_b32_e32 v88, 16, v145
	v_and_b32_e32 v89, 0xffff0000, v145
	v_lshlrev_b32_e32 v118, 16, v146
	v_and_b32_e32 v119, 0xffff0000, v146
	v_lshlrev_b32_e32 v120, 16, v147
	v_and_b32_e32 v121, 0xffff0000, v147
	v_pk_fma_f32 v[90:91], v[72:73], s[24:25], v[88:89] op_sel_hi:[1,0,1]
	v_pk_fma_f32 v[92:93], v[70:71], s[24:25], v[86:87] op_sel_hi:[1,0,1]
	v_pk_fma_f32 v[86:87], v[76:77], s[24:25], v[120:121] op_sel_hi:[1,0,1]
	v_pk_fma_f32 v[88:89], v[74:75], s[24:25], v[118:119] op_sel_hi:[1,0,1]
	s_waitcnt vmcnt(9)
	v_lshlrev_b32_e32 v70, 16, v160
	v_and_b32_e32 v71, 0xffff0000, v160
	v_lshlrev_b32_e32 v72, 16, v161
	v_and_b32_e32 v73, 0xffff0000, v161
	v_lshlrev_b32_e32 v144, 16, v162
	v_and_b32_e32 v145, 0xffff0000, v162
	v_lshlrev_b32_e32 v146, 16, v163
	v_and_b32_e32 v147, 0xffff0000, v163
	s_waitcnt vmcnt(8)
	v_lshlrev_b32_e32 v76, 16, v164
	v_and_b32_e32 v77, 0xffff0000, v164
	v_lshlrev_b32_e32 v74, 16, v165
	v_and_b32_e32 v75, 0xffff0000, v165
	v_lshlrev_b32_e32 v160, 16, v166
	v_and_b32_e32 v161, 0xffff0000, v166
	v_lshlrev_b32_e32 v162, 16, v167
	v_and_b32_e32 v163, 0xffff0000, v167
	v_pk_fma_f32 v[74:75], v[72:73], s[24:25], v[74:75] op_sel_hi:[1,0,1]
	v_pk_fma_f32 v[76:77], v[70:71], s[24:25], v[76:77] op_sel_hi:[1,0,1]
	v_pk_fma_f32 v[70:71], v[146:147], s[24:25], v[162:163] op_sel_hi:[1,0,1]
	v_pk_fma_f32 v[72:73], v[144:145], s[24:25], v[160:161] op_sel_hi:[1,0,1]
	v_add_f32_e32 v118, v92, v93
	v_add_f32_e32 v120, v90, v91
	v_add_f32_e32 v140, v88, v89
	v_add_f32_e32 v142, v86, v87
	v_mov_b32_e32 v153, v76
	v_mov_b32_e32 v1, v77
	v_mov_b32_e32 v115, v74
	v_mov_b32_e32 v117, v75
	v_mov_b32_e32 v119, v72
	v_mov_b32_e32 v121, v73
	v_mov_b32_e32 v141, v70
	v_mov_b32_e32 v143, v71
	v_pk_add_f32 v[144:145], v[152:153], v[0:1]
	v_pk_add_f32 v[114:115], v[114:115], v[116:117]
	v_pk_add_f32 v[116:117], v[118:119], v[120:121]
	v_pk_add_f32 v[118:119], v[140:141], v[142:143]
	v_pk_add_f32 v[114:115], v[144:145], v[114:115]
	v_pk_add_f32 v[116:117], v[116:117], v[118:119]
	s_waitcnt vmcnt(6)
	v_lshlrev_b32_e32 v118, 16, v26
	v_pk_add_f32 v[114:115], v[114:115], v[116:117]
	v_lshlrev_b32_e32 v116, 16, v32
	v_add_f32_e32 v108, v114, v115
	v_lshlrev_b32_e32 v114, 16, v30
	v_and_b32_e32 v115, 0xffff0000, v30
	v_and_b32_e32 v117, 0xffff0000, v32
	v_and_b32_e32 v119, 0xffff0000, v26
	v_lshlrev_b32_e32 v120, 16, v28
	v_and_b32_e32 v121, 0xffff0000, v28
	v_lshlrev_b32_e32 v30, 16, v31
	v_and_b32_e32 v31, 0xffff0000, v31
	v_lshlrev_b32_e32 v32, 16, v33
	v_and_b32_e32 v33, 0xffff0000, v33
	v_lshlrev_b32_e32 v26, 16, v27
	v_and_b32_e32 v27, 0xffff0000, v27
	v_lshlrev_b32_e32 v28, 16, v29
	v_and_b32_e32 v29, 0xffff0000, v29
	v_pk_fma_f32 v[146:147], v[114:115], s[24:25], v[118:119] op_sel_hi:[1,0,1]
	v_pk_fma_f32 v[144:145], v[116:117], s[24:25], v[120:121] op_sel_hi:[1,0,1]
	v_pk_fma_f32 v[142:143], v[30:31], s[24:25], v[26:27] op_sel_hi:[1,0,1]
	v_pk_fma_f32 v[140:141], v[32:33], s[24:25], v[28:29] op_sel_hi:[1,0,1]
	v_mov_b32_e32 v26, v146
	v_mov_b32_e32 v27, v144
	v_mov_b32_e32 v28, v147
	v_mov_b32_e32 v29, v145
	v_pk_add_f32 v[26:27], v[26:27], v[28:29]
	v_mov_b32_e32 v28, v142
	v_mov_b32_e32 v29, v140
	v_mov_b32_e32 v30, v143
	v_mov_b32_e32 v31, v141
	v_pk_add_f32 v[28:29], v[28:29], v[30:31]
	s_waitcnt vmcnt(4)
	v_lshlrev_b32_e32 v30, 16, v18
	v_pk_add_f32 v[26:27], v[26:27], v[28:29]
	v_and_b32_e32 v31, 0xffff0000, v18
	v_pk_add_f32 v[152:153], v[26:27], v[26:27] op_sel:[0,1] op_sel_hi:[1,0]
	v_lshlrev_b32_e32 v26, 16, v22
	v_and_b32_e32 v27, 0xffff0000, v22
	v_lshlrev_b32_e32 v22, 16, v23
	v_and_b32_e32 v23, 0xffff0000, v23
	v_lshlrev_b32_e32 v18, 16, v19
	v_and_b32_e32 v19, 0xffff0000, v19
	v_lshlrev_b32_e32 v28, 16, v24
	v_and_b32_e32 v29, 0xffff0000, v24
	v_lshlrev_b32_e32 v24, 16, v25
	v_and_b32_e32 v25, 0xffff0000, v25
	v_lshlrev_b32_e32 v32, 16, v20
	v_and_b32_e32 v33, 0xffff0000, v20
	v_lshlrev_b32_e32 v20, 16, v21
	v_and_b32_e32 v21, 0xffff0000, v21
	v_pk_fma_f32 v[118:119], v[22:23], s[24:25], v[18:19] op_sel_hi:[1,0,1]
	v_pk_fma_f32 v[120:121], v[26:27], s[24:25], v[30:31] op_sel_hi:[1,0,1]
	v_pk_fma_f32 v[114:115], v[24:25], s[24:25], v[20:21] op_sel_hi:[1,0,1]
	v_pk_mov_b32 v[18:19], v[120:121], v[118:119] op_sel:[1,0]
	v_mov_b32_e32 v20, v120
	v_mov_b32_e32 v21, v119
	v_pk_fma_f32 v[116:117], v[28:29], s[24:25], v[32:33] op_sel_hi:[1,0,1]
	v_pk_add_f32 v[18:19], v[18:19], v[20:21]
	v_mov_b32_e32 v20, v116
	v_pk_add_f32 v[160:161], v[18:19], v[18:19] op_sel:[0,1] op_sel_hi:[1,0]
	v_pk_mov_b32 v[18:19], v[116:117], v[114:115] op_sel:[1,0]
	v_mov_b32_e32 v21, v115
	v_pk_add_f32 v[18:19], v[18:19], v[20:21]
	s_waitcnt vmcnt(3)
	v_lshlrev_b32_e32 v20, 16, v16
	v_pk_add_f32 v[162:163], v[18:19], v[18:19] op_sel:[0,1] op_sel_hi:[1,0]
	v_lshlrev_b32_e32 v18, 16, v14
	v_and_b32_e32 v19, 0xffff0000, v14
	v_and_b32_e32 v21, 0xffff0000, v16
	s_waitcnt vmcnt(2)
	v_lshlrev_b32_e32 v22, 16, v10
	v_and_b32_e32 v23, 0xffff0000, v10
	v_lshlrev_b32_e32 v24, 16, v12
	v_and_b32_e32 v25, 0xffff0000, v12
	v_pk_fma_f32 v[32:33], v[18:19], s[24:25], v[22:23] op_sel_hi:[1,0,1]
	v_pk_fma_f32 v[28:29], v[20:21], s[24:25], v[24:25] op_sel_hi:[1,0,1]
	s_waitcnt vmcnt(1)
; template <int NR>
; __device__ __forceinline__ void ln_comb(bf16_t* h, const bf16_t* sb, float scale, const float* g, const float* b, int lane) {
;     ...
;             s += ((v[i][j][0].x + v[i][j][0].y) + (v[i][j][0].z + v[i][j][0].w)) + ((v[i][j][1].x + v[i][j][1].y) + (v[i][j][1].z + v[i][j][1].w)); }
;         sm[i] = s; }
; #pragma unroll
;     for (int o = 1; o < 64; o <<= 1) {
; #pragma unroll
;         for (int i = 0; i < NR; ++i) sm[i] += __shfl_xor(sm[i], o); }
;     float q[NR], rstd[NR];
; #pragma unroll
;     for (int i = 0; i < NR; ++i) { const float mean = sm[i] * (1.f / D); float s2 = 0.f;
; #pragma unroll
;         for (int j = 0; j < 4; ++j)
; #pragma unroll
;             for (int e = 0; e < 2; ++e) { v[i][j][e] = v[i][j][e] - mean; s2 += (v[i][j][e].x * v[i][j][e].x + v[i][j][e].y * v[i][j][e].y) + (v[i][j][e].z * v[i][j][e].z + v[i][j][e].w * v[i][j][e].w); }
	v_lshlrev_b32_e32 v18, 16, v6
	v_and_b32_e32 v19, 0xffff0000, v6
	v_lshlrev_b32_e32 v6, 16, v7
	v_and_b32_e32 v7, 0xffff0000, v7
	s_waitcnt vmcnt(0)
	v_lshlrev_b32_e32 v24, 16, v2
	v_and_b32_e32 v25, 0xffff0000, v2
	v_lshlrev_b32_e32 v2, 16, v3
	v_and_b32_e32 v3, 0xffff0000, v3
	v_lshlrev_b32_e32 v14, 16, v15
	v_and_b32_e32 v15, 0xffff0000, v15
	v_lshlrev_b32_e32 v16, 16, v17
	v_and_b32_e32 v17, 0xffff0000, v17
	v_lshlrev_b32_e32 v10, 16, v11
	v_and_b32_e32 v11, 0xffff0000, v11
	v_lshlrev_b32_e32 v12, 16, v13
	v_and_b32_e32 v13, 0xffff0000, v13
	v_lshlrev_b32_e32 v20, 16, v8
	v_and_b32_e32 v21, 0xffff0000, v8
	v_lshlrev_b32_e32 v8, 16, v9
	v_and_b32_e32 v9, 0xffff0000, v9
	v_lshlrev_b32_e32 v164, 16, v4
	v_and_b32_e32 v165, 0xffff0000, v4
	v_lshlrev_b32_e32 v4, 16, v5
	v_and_b32_e32 v5, 0xffff0000, v5
	v_pk_fma_f32 v[22:23], v[6:7], s[24:25], v[2:3] op_sel_hi:[1,0,1]
	v_pk_fma_f32 v[24:25], v[18:19], s[24:25], v[24:25] op_sel_hi:[1,0,1]
	v_pk_fma_f32 v[30:31], v[14:15], s[24:25], v[10:11] op_sel_hi:[1,0,1]
	v_pk_fma_f32 v[26:27], v[16:17], s[24:25], v[12:13] op_sel_hi:[1,0,1]
	v_pk_fma_f32 v[18:19], v[8:9], s[24:25], v[4:5] op_sel_hi:[1,0,1]
	v_pk_fma_f32 v[20:21], v[20:21], s[24:25], v[164:165] op_sel_hi:[1,0,1]
	v_mov_b32_e32 v153, v24
	v_mov_b32_e32 v1, v25
	v_mov_b32_e32 v161, v22
	v_mov_b32_e32 v163, v23
	v_add_f32_e32 v10, v32, v33
	v_add_f32_e32 v12, v30, v31
	v_add_f32_e32 v14, v28, v29
	v_add_f32_e32 v16, v26, v27
	v_pk_add_f32 v[2:3], v[152:153], v[0:1]
	v_pk_add_f32 v[4:5], v[160:161], v[162:163]
	v_mov_b32_e32 v11, v20
	v_mov_b32_e32 v13, v21
	v_mov_b32_e32 v15, v18
	v_mov_b32_e32 v17, v19
	v_pk_add_f32 v[2:3], v[2:3], v[4:5]
	v_pk_add_f32 v[4:5], v[10:11], v[12:13]
	v_pk_add_f32 v[6:7], v[14:15], v[16:17]
	s_nop 0
	v_pk_add_f32 v[4:5], v[4:5], v[6:7]
	s_nop 0
	v_pk_add_f32 v[2:3], v[2:3], v[4:5]
	s_nop 0
	v_add_f32_e32 v1, v2, v3
	ds_bpermute_b32 v2, v111, v39
	ds_bpermute_b32 v4, v111, v1
	ds_bpermute_b32 v3, v111, v108
	s_waitcnt lgkmcnt(2)
	v_add_f32_e32 v2, v39, v2
	s_waitcnt lgkmcnt(1)
	v_add_f32_e32 v1, v1, v4
	ds_bpermute_b32 v4, v113, v2
	s_waitcnt lgkmcnt(1)
	v_add_f32_e32 v3, v108, v3
	s_waitcnt lgkmcnt(0)
	v_add_f32_e32 v2, v2, v4
	ds_bpermute_b32 v4, v113, v3
	s_waitcnt lgkmcnt(0)
	v_add_f32_e32 v3, v3, v4
	ds_bpermute_b32 v4, v113, v1
	s_waitcnt lgkmcnt(0)
	v_add_f32_e32 v1, v1, v4
	ds_bpermute_b32 v4, v148, v2
	s_waitcnt lgkmcnt(0)
	v_add_f32_e32 v2, v2, v4
	ds_bpermute_b32 v4, v148, v3
	s_waitcnt lgkmcnt(0)
	v_add_f32_e32 v3, v3, v4
	ds_bpermute_b32 v4, v148, v1
	s_waitcnt lgkmcnt(0)
	v_add_f32_e32 v1, v1, v4
	ds_bpermute_b32 v4, v149, v2
	s_waitcnt lgkmcnt(0)
	v_add_f32_e32 v2, v2, v4
	ds_bpermute_b32 v4, v149, v3
	s_waitcnt lgkmcnt(0)
	v_add_f32_e32 v3, v3, v4
	ds_bpermute_b32 v4, v149, v1
	s_waitcnt lgkmcnt(0)
	v_add_f32_e32 v1, v1, v4
	ds_bpermute_b32 v4, v150, v2
	s_waitcnt lgkmcnt(0)
	v_add_f32_e32 v2, v2, v4
	ds_bpermute_b32 v4, v150, v3
	s_waitcnt lgkmcnt(0)
	v_add_f32_e32 v3, v3, v4
	ds_bpermute_b32 v4, v150, v1
	s_waitcnt lgkmcnt(0)
	v_add_f32_e32 v1, v1, v4
	ds_bpermute_b32 v4, v151, v2
	s_waitcnt lgkmcnt(0)
	v_add_f32_e32 v10, v2, v4
	ds_bpermute_b32 v2, v151, v3
	v_fmamk_f32 v131, v10, 0xba000000, v131
	v_fmamk_f32 v127, v10, 0xba000000, v127
	v_fmamk_f32 v129, v10, 0xba000000, v129
	v_fmac_f32_e32 v130, 0xba000000, v10
	s_waitcnt lgkmcnt(0)
	v_add_f32_e32 v11, v3, v2
	ds_bpermute_b32 v2, v151, v1
	v_fmamk_f32 v125, v10, 0xba000000, v125
	v_fmac_f32_e32 v126, 0xba000000, v10
	v_mov_b32_e32 v4, v131
	v_mov_b32_e32 v5, v127
	s_waitcnt lgkmcnt(0)
	v_add_f32_e32 v1, v1, v2
	v_fmac_f32_e32 v128, 0xba000000, v10
	v_fmac_f32_e32 v124, 0xba000000, v10
	v_mov_b32_e32 v2, v130
	v_mov_b32_e32 v3, v126
	v_pk_mul_f32 v[4:5], v[4:5], v[4:5]
	v_mov_b32_e32 v6, v129
	v_mov_b32_e32 v7, v125
	v_pk_fma_f32 v[2:3], v[2:3], v[2:3], v[4:5]
	v_mov_b32_e32 v4, v128
	v_mov_b32_e32 v5, v124
	v_pk_mul_f32 v[6:7], v[6:7], v[6:7]
	v_fmamk_f32 v123, v10, 0xba000000, v123
	v_pk_fma_f32 v[4:5], v[4:5], v[4:5], v[6:7]
	v_fmac_f32_e32 v122, 0xba000000, v10
	v_pk_add_f32 v[2:3], v[2:3], v[4:5]
	v_fmamk_f32 v99, v10, 0xba000000, v99
	v_fmac_f32_e32 v98, 0xba000000, v10
	v_pk_add_f32 v[2:3], v[2:3], v[2:3] op_sel_hi:[0,1]
	v_pk_mul_f32 v[4:5], v[98:99], v[98:99]
	v_pk_mul_f32 v[6:7], v[122:123], v[122:123]
	v_fmac_f32_e32 v96, 0xba000000, v10
	v_pk_mov_b32 v[8:9], v[6:7], v[4:5] op_sel:[1,0]
	v_mov_b32_e32 v7, v5
	v_fmamk_f32 v97, v10, 0xba000000, v97
	v_fmac_f32_e32 v94, 0xba000000, v10
	v_mul_f32_e32 v2, v96, v96
	v_pk_add_f32 v[4:5], v[8:9], v[6:7]
	v_fmamk_f32 v95, v10, 0xba000000, v95
	v_pk_fma_f32 v[6:7], v[96:97], v[96:97], v[2:3] op_sel_hi:[1,1,0]
	v_mul_f32_e32 v2, v94, v94
	v_pk_add_f32 v[4:5], v[4:5], v[4:5] op_sel_hi:[0,1]
	v_pk_fma_f32 v[8:9], v[94:95], v[94:95], v[2:3] op_sel_hi:[1,1,0]
	v_fmamk_f32 v83, v10, 0xba000000, v83
	v_fmac_f32_e32 v82, 0xba000000, v10
	v_fmamk_f32 v85, v10, 0xba000000, v85
	v_fmac_f32_e32 v84, 0xba000000, v10
	v_mul_f32_e32 v6, v84, v84
	v_mul_f32_e32 v8, v85, v85
	v_mul_f32_e32 v4, v82, v82
	v_mul_f32_e32 v2, v83, v83
	v_pk_add_f32 v[6:7], v[6:7], v[8:9]
	v_pk_add_f32 v[2:3], v[4:5], v[2:3]
	v_fmamk_f32 v81, v10, 0xba000000, v81
	v_pk_add_f32 v[2:3], v[6:7], v[2:3]
	v_fmac_f32_e32 v80, 0xba000000, v10
	v_fmamk_f32 v79, v10, 0xba000000, v79
	v_fmac_f32_e32 v78, 0xba000000, v10
	v_pk_add_f32 v[2:3], v[2:3], v[2:3] op_sel_hi:[0,1]
	v_pk_mul_f32 v[4:5], v[78:79], v[78:79]
	v_pk_mul_f32 v[6:7], v[80:81], v[80:81]
	v_fmac_f32_e32 v68, 0xba000000, v10
	v_pk_mov_b32 v[8:9], v[6:7], v[4:5] op_sel:[1,0]
	v_mov_b32_e32 v7, v5
	v_fmamk_f32 v69, v10, 0xba000000, v69
	v_fmac_f32_e32 v66, 0xba000000, v10
; template <int NR>
; __device__ __forceinline__ void ln_comb(bf16_t* h, const bf16_t* sb, float scale, const float* g, const float* b, int lane) {
;     ...
;     for (int i = 0; i < NR; ++i) { const float mean = sm[i] * (1.f / D); float s2 = 0.f;
; #pragma unroll
;         for (int j = 0; j < 4; ++j)
; #pragma unroll
;             for (int e = 0; e < 2; ++e) { v[i][j][e] = v[i][j][e] - mean; s2 += (v[i][j][e].x * v[i][j][e].x + v[i][j][e].y * v[i][j][e].y) + (v[i][j][e].z * v[i][j][e].z + v[i][j][e].w * v[i][j][e].w); }
;         q[i] = s2; }
	v_mul_f32_e32 v2, v68, v68
	v_pk_add_f32 v[4:5], v[8:9], v[6:7]
	v_fmamk_f32 v67, v10, 0xba000000, v67
	v_pk_fma_f32 v[6:7], v[68:69], v[68:69], v[2:3] op_sel_hi:[1,1,0]
	v_mul_f32_e32 v2, v66, v66
	v_pk_add_f32 v[4:5], v[4:5], v[4:5] op_sel_hi:[0,1]
	v_pk_fma_f32 v[8:9], v[66:67], v[66:67], v[2:3] op_sel_hi:[1,1,0]
	v_fmamk_f32 v63, v10, 0xba000000, v63
	v_fmac_f32_e32 v62, 0xba000000, v10
	v_fmamk_f32 v65, v10, 0xba000000, v65
	v_fmac_f32_e32 v64, 0xba000000, v10
	v_mul_f32_e32 v6, v64, v64
	v_mul_f32_e32 v8, v65, v65
	v_mul_f32_e32 v4, v62, v62
	v_mul_f32_e32 v2, v63, v63
	v_pk_add_f32 v[6:7], v[6:7], v[8:9]
	v_pk_add_f32 v[2:3], v[4:5], v[2:3]
	v_fmamk_f32 v139, v11, 0xba000000, v139
	v_fmamk_f32 v137, v11, 0xba000000, v137
	v_pk_add_f32 v[2:3], v[6:7], v[2:3]
	v_fmamk_f32 v135, v11, 0xba000000, v135
	v_fmac_f32_e32 v138, 0xba000000, v11
	v_fmamk_f32 v133, v11, 0xba000000, v133
	v_fmac_f32_e32 v136, 0xba000000, v11
	v_mov_b32_e32 v4, v139
	v_mov_b32_e32 v5, v137
	v_add_f32_e32 v12, v2, v3
	v_fmac_f32_e32 v134, 0xba000000, v11
	v_fmac_f32_e32 v132, 0xba000000, v11
	v_mov_b32_e32 v2, v138
	v_mov_b32_e32 v3, v136
	v_pk_mul_f32 v[4:5], v[4:5], v[4:5]
	v_mov_b32_e32 v6, v135
	v_mov_b32_e32 v7, v133
	v_pk_fma_f32 v[2:3], v[2:3], v[2:3], v[4:5]
	v_mov_b32_e32 v4, v134
	v_mov_b32_e32 v5, v132
	v_pk_mul_f32 v[6:7], v[6:7], v[6:7]
	v_fmamk_f32 v107, v11, 0xba000000, v107
	v_pk_fma_f32 v[4:5], v[4:5], v[4:5], v[6:7]
	v_fmac_f32_e32 v106, 0xba000000, v11
	v_pk_add_f32 v[2:3], v[2:3], v[4:5]
	v_fmamk_f32 v105, v11, 0xba000000, v105
	v_fmac_f32_e32 v104, 0xba000000, v11
	v_pk_add_f32 v[2:3], v[2:3], v[2:3] op_sel_hi:[0,1]
	v_pk_mul_f32 v[4:5], v[104:105], v[104:105]
	v_pk_mul_f32 v[6:7], v[106:107], v[106:107]
	v_fmac_f32_e32 v102, 0xba000000, v11
	v_pk_mov_b32 v[8:9], v[6:7], v[4:5] op_sel:[1,0]
	v_mov_b32_e32 v7, v5
	v_fmamk_f32 v103, v11, 0xba000000, v103
	v_fmac_f32_e32 v100, 0xba000000, v11
	v_mul_f32_e32 v2, v102, v102
	v_pk_add_f32 v[4:5], v[8:9], v[6:7]
	v_fmamk_f32 v101, v11, 0xba000000, v101
	v_pk_fma_f32 v[6:7], v[102:103], v[102:103], v[2:3] op_sel_hi:[1,1,0]
	v_mul_f32_e32 v2, v100, v100
	v_pk_add_f32 v[4:5], v[4:5], v[4:5] op_sel_hi:[0,1]
	v_pk_fma_f32 v[8:9], v[100:101], v[100:101], v[2:3] op_sel_hi:[1,1,0]
	v_fmamk_f32 v91, v11, 0xba000000, v91
	v_fmac_f32_e32 v90, 0xba000000, v11
	v_fmamk_f32 v93, v11, 0xba000000, v93
	v_fmac_f32_e32 v92, 0xba000000, v11
	v_mul_f32_e32 v6, v92, v92
	v_mul_f32_e32 v8, v93, v93
	v_mul_f32_e32 v4, v90, v90
	v_mul_f32_e32 v2, v91, v91
	v_pk_add_f32 v[6:7], v[6:7], v[8:9]
	v_pk_add_f32 v[2:3], v[4:5], v[2:3]
	v_fmamk_f32 v89, v11, 0xba000000, v89
	v_pk_add_f32 v[2:3], v[6:7], v[2:3]
	v_fmac_f32_e32 v88, 0xba000000, v11
	v_fmamk_f32 v87, v11, 0xba000000, v87
	v_fmac_f32_e32 v86, 0xba000000, v11
	v_pk_add_f32 v[2:3], v[2:3], v[2:3] op_sel_hi:[0,1]
	v_pk_mul_f32 v[4:5], v[86:87], v[86:87]
	v_pk_mul_f32 v[6:7], v[88:89], v[88:89]
	v_fmac_f32_e32 v76, 0xba000000, v11
	v_pk_mov_b32 v[8:9], v[6:7], v[4:5] op_sel:[1,0]
	v_mov_b32_e32 v7, v5
	v_fmamk_f32 v77, v11, 0xba000000, v77
	v_fmac_f32_e32 v74, 0xba000000, v11
	v_mul_f32_e32 v2, v76, v76
	v_pk_add_f32 v[4:5], v[8:9], v[6:7]
	v_fmamk_f32 v75, v11, 0xba000000, v75
	v_pk_fma_f32 v[6:7], v[76:77], v[76:77], v[2:3] op_sel_hi:[1,1,0]
	v_mul_f32_e32 v2, v74, v74
	v_pk_add_f32 v[4:5], v[4:5], v[4:5] op_sel_hi:[0,1]
	v_pk_fma_f32 v[8:9], v[74:75], v[74:75], v[2:3] op_sel_hi:[1,1,0]
	v_fmamk_f32 v71, v11, 0xba000000, v71
	v_fmac_f32_e32 v70, 0xba000000, v11
	v_fmamk_f32 v73, v11, 0xba000000, v73
	v_fmac_f32_e32 v72, 0xba000000, v11
	v_mul_f32_e32 v6, v72, v72
	v_mul_f32_e32 v8, v73, v73
	v_mul_f32_e32 v4, v70, v70
	v_mul_f32_e32 v2, v71, v71
	v_pk_add_f32 v[6:7], v[6:7], v[8:9]
	v_pk_add_f32 v[2:3], v[4:5], v[2:3]
	v_fmamk_f32 v147, v1, 0xba000000, v147
	v_fmamk_f32 v145, v1, 0xba000000, v145
	v_pk_add_f32 v[2:3], v[6:7], v[2:3]
	v_fmamk_f32 v143, v1, 0xba000000, v143
	v_fmac_f32_e32 v146, 0xba000000, v1
	v_fmamk_f32 v141, v1, 0xba000000, v141
	v_fmac_f32_e32 v144, 0xba000000, v1
	v_mov_b32_e32 v6, v147
	v_mov_b32_e32 v7, v145
	v_fmac_f32_e32 v142, 0xba000000, v1
	v_fmac_f32_e32 v140, 0xba000000, v1
	v_mov_b32_e32 v4, v146
	v_mov_b32_e32 v5, v144
	v_pk_mul_f32 v[6:7], v[6:7], v[6:7]
	v_mov_b32_e32 v8, v143
	v_mov_b32_e32 v9, v141
	v_pk_fma_f32 v[4:5], v[4:5], v[4:5], v[6:7]
	v_mov_b32_e32 v6, v142
	v_mov_b32_e32 v7, v140
	v_pk_mul_f32 v[8:9], v[8:9], v[8:9]
	v_fmamk_f32 v121, v1, 0xba000000, v121
	v_pk_fma_f32 v[6:7], v[6:7], v[6:7], v[8:9]
	v_fmac_f32_e32 v120, 0xba000000, v1
	v_pk_add_f32 v[4:5], v[4:5], v[6:7]
	v_fmamk_f32 v119, v1, 0xba000000, v119
	v_fmac_f32_e32 v118, 0xba000000, v1
	v_pk_add_f32 v[4:5], v[4:5], v[4:5] op_sel_hi:[0,1]
	v_pk_mul_f32 v[6:7], v[118:119], v[118:119]
	v_pk_mul_f32 v[8:9], v[120:121], v[120:121]
	v_fmac_f32_e32 v116, 0xba000000, v1
	v_pk_mov_b32 v[10:11], v[8:9], v[6:7] op_sel:[1,0]
	v_mov_b32_e32 v9, v7
	v_fmamk_f32 v117, v1, 0xba000000, v117
	v_fmac_f32_e32 v114, 0xba000000, v1
	v_mul_f32_e32 v4, v116, v116
	v_pk_add_f32 v[6:7], v[10:11], v[8:9]
	v_fmamk_f32 v115, v1, 0xba000000, v115
	v_pk_fma_f32 v[8:9], v[116:117], v[116:117], v[4:5] op_sel_hi:[1,1,0]
	v_mul_f32_e32 v4, v114, v114
	v_pk_add_f32 v[6:7], v[6:7], v[6:7] op_sel_hi:[0,1]
	v_pk_fma_f32 v[10:11], v[114:115], v[114:115], v[4:5] op_sel_hi:[1,1,0]
	v_fmamk_f32 v31, v1, 0xba000000, v31
	v_fmac_f32_e32 v30, 0xba000000, v1
	v_fmamk_f32 v33, v1, 0xba000000, v33
	v_fmac_f32_e32 v32, 0xba000000, v1
	v_mul_f32_e32 v8, v32, v32
	v_mul_f32_e32 v10, v33, v33
	v_mul_f32_e32 v6, v30, v30
	v_mul_f32_e32 v4, v31, v31
	v_pk_add_f32 v[8:9], v[8:9], v[10:11]
	v_pk_add_f32 v[4:5], v[6:7], v[4:5]
	v_fmamk_f32 v29, v1, 0xba000000, v29
	v_fmac_f32_e32 v28, 0xba000000, v1
	v_fmamk_f32 v27, v1, 0xba000000, v27
	v_fmac_f32_e32 v26, 0xba000000, v1
	v_fmamk_f32 v25, v1, 0xba000000, v25
	v_fmac_f32_e32 v24, 0xba000000, v1
	v_fmamk_f32 v23, v1, 0xba000000, v23
	v_fmac_f32_e32 v22, 0xba000000, v1
	v_fmamk_f32 v19, v1, 0xba000000, v19
	v_fmac_f32_e32 v18, 0xba000000, v1
	v_fmamk_f32 v21, v1, 0xba000000, v21
	v_fmac_f32_e32 v20, 0xba000000, v1
	ds_bpermute_b32 v1, v111, v12
	v_pk_add_f32 v[4:5], v[8:9], v[4:5]
	v_pk_mul_f32 v[6:7], v[26:27], v[26:27]
	v_pk_mul_f32 v[8:9], v[28:29], v[28:29]
	v_pk_add_f32 v[4:5], v[4:5], v[4:5] op_sel_hi:[0,1]
	v_pk_mov_b32 v[10:11], v[8:9], v[6:7] op_sel:[1,0]
	v_mov_b32_e32 v9, v7
	v_pk_add_f32 v[6:7], v[10:11], v[8:9]
	v_mul_f32_e32 v4, v24, v24
	v_pk_add_f32 v[6:7], v[6:7], v[6:7] op_sel_hi:[0,1]
	v_pk_fma_f32 v[8:9], v[24:25], v[24:25], v[4:5] op_sel_hi:[1,1,0]
	v_mul_f32_e32 v4, v22, v22
	v_pk_fma_f32 v[10:11], v[22:23], v[22:23], v[4:5] op_sel_hi:[1,1,0]
	v_mul_f32_e32 v6, v18, v18
	v_mul_f32_e32 v4, v19, v19
	s_waitcnt lgkmcnt(0)
; __device__ __forceinline__ unsigned cvt_pk_bf16(float lo, float hi) { unsigned r; asm volatile("v_cvt_pk_bf16_f32 %0, %1, %2" : "=v"(r) : "v"(lo), "v"(hi)); return r; }
; template <int NR>
; __device__ __forceinline__ void ln_comb(bf16_t* h, const bf16_t* sb, float scale, const float* g, const float* b, int lane) {
;     ...
;     for (int o = 1; o < 64; o <<= 1) {
; #pragma unroll
;         for (int i = 0; i < NR; ++i) q[i] += __shfl_xor(q[i], o); }
; #pragma unroll
;     for (int i = 0; i < NR; ++i) rstd[i] = rsqrtf(q[i] * (1.f / D) + LN_EPS);
; #pragma unroll
;     for (int j = 0; j < 4; ++j) {
;         const int c = 8 * lane + 512 * j;
;         const f32x4 g0 = *(const f32x4*)(g + c), g1 = *(const f32x4*)(g + c + 4), b0 = *(const f32x4*)(b + c), b1 = *(const f32x4*)(b + c + 4);
; #pragma unroll
;         for (int i = 0; i < NR; ++i) { const f32x4 y0 = v[i][j][0] * rstd[i] * g0 + b0, y1 = v[i][j][1] * rstd[i] * g1 + b1;
;             u32x4 w; w.x = cvt_pk_bf16(y0.x, y0.y); w.y = cvt_pk_bf16(y0.z, y0.w); w.z = cvt_pk_bf16(y1.x, y1.y); w.w = cvt_pk_bf16(y1.z, y1.w);
;             *(u32x4*)(h + (size_t)i * D + c) = w; }
	v_add_f32_e32 v1, v12, v1
	v_pk_add_f32 v[4:5], v[6:7], v[4:5]
	ds_bpermute_b32 v6, v113, v1
	v_mul_f32_e32 v8, v20, v20
	v_mul_f32_e32 v10, v21, v21
	v_pk_add_f32 v[8:9], v[8:9], v[10:11]
	v_mov_b32_e32 v7, v2
	s_waitcnt lgkmcnt(0)
	v_add_f32_e32 v1, v1, v6
	ds_bpermute_b32 v6, v148, v1
	v_pk_add_f32 v[4:5], v[8:9], v[4:5]
	s_waitcnt lgkmcnt(0)
	v_add_f32_e32 v1, v1, v6
	ds_bpermute_b32 v6, v149, v1
	v_mov_b32_e32 v2, v5
	s_waitcnt lgkmcnt(0)
	v_add_f32_e32 v1, v1, v6
	ds_bpermute_b32 v6, v150, v1
	s_waitcnt lgkmcnt(0)
	v_add_f32_e32 v1, v1, v6
	ds_bpermute_b32 v6, v151, v1
	s_waitcnt lgkmcnt(0)
	v_add_f32_e32 v1, v1, v6
	v_fmamk_f32 v1, v1, 0x3a000000, v154
	v_cmp_gt_f32_e32 vcc, s73, v1
	v_mul_f32_e32 v6, 0x4b800000, v1
	s_nop 0
	v_cndmask_b32_e32 v1, v1, v6, vcc
	v_rsq_f32_e32 v1, v1
	s_nop 0
	v_mul_f32_e32 v6, 0x45800000, v1
	v_cndmask_b32_e32 v108, v1, v6, vcc
	v_mov_b32_e32 v6, v4
	v_pk_add_f32 v[2:3], v[6:7], v[2:3]
	ds_bpermute_b32 v5, v111, v3
	ds_bpermute_b32 v4, v111, v2
	v_pk_mul_f32 v[126:127], v[126:127], v[108:109] op_sel_hi:[1,0]
	v_pk_mul_f32 v[130:131], v[130:131], v[108:109] op_sel_hi:[1,0]
	v_pk_mul_f32 v[128:129], v[128:129], v[108:109] op_sel_hi:[1,0]
	v_pk_mul_f32 v[124:125], v[124:125], v[108:109] op_sel_hi:[1,0]
	s_waitcnt lgkmcnt(0)
	v_pk_add_f32 v[2:3], v[2:3], v[4:5]
	ds_bpermute_b32 v5, v113, v3
	ds_bpermute_b32 v4, v113, v2
	v_pk_mul_f32 v[96:97], v[96:97], v[108:109] op_sel_hi:[1,0]
	v_pk_mul_f32 v[122:123], v[122:123], v[108:109] op_sel_hi:[1,0]
	v_pk_mul_f32 v[98:99], v[98:99], v[108:109] op_sel_hi:[1,0]
	v_pk_mul_f32 v[94:95], v[94:95], v[108:109] op_sel_hi:[1,0]
	s_waitcnt lgkmcnt(0)
	v_pk_add_f32 v[2:3], v[2:3], v[4:5]
	ds_bpermute_b32 v5, v148, v3
	ds_bpermute_b32 v4, v148, v2
	v_pk_mul_f32 v[80:81], v[80:81], v[108:109] op_sel_hi:[1,0]
	v_pk_mul_f32 v[84:85], v[84:85], v[108:109] op_sel_hi:[1,0]
	v_pk_mul_f32 v[82:83], v[82:83], v[108:109] op_sel_hi:[1,0]
	v_pk_mul_f32 v[78:79], v[78:79], v[108:109] op_sel_hi:[1,0]
	s_waitcnt lgkmcnt(0)
	v_pk_add_f32 v[2:3], v[2:3], v[4:5]
	ds_bpermute_b32 v5, v149, v3
	ds_bpermute_b32 v4, v149, v2
	s_waitcnt lgkmcnt(0)
	v_pk_add_f32 v[2:3], v[2:3], v[4:5]
	ds_bpermute_b32 v5, v150, v3
	ds_bpermute_b32 v4, v150, v2
	s_waitcnt lgkmcnt(0)
	v_pk_add_f32 v[2:3], v[2:3], v[4:5]
	ds_bpermute_b32 v5, v151, v3
	ds_bpermute_b32 v4, v151, v2
	s_waitcnt lgkmcnt(0)
	v_pk_add_f32 v[2:3], v[2:3], v[4:5]
	s_nop 0
	v_pk_fma_f32 v[2:3], v[2:3], s[70:71], v[154:155] op_sel_hi:[1,0,0]
	s_nop 0
	v_mul_f32_e32 v1, 0x4b800000, v3
	v_cmp_gt_f32_e64 s[40:41], s73, v3
	v_cmp_gt_f32_e32 vcc, s73, v2
	s_nop 0
	v_cndmask_b32_e64 v1, v3, v1, s[40:41]
	v_rsq_f32_e32 v1, v1
	s_nop 0
	v_mul_f32_e32 v3, 0x45800000, v1
	v_cndmask_b32_e64 v112, v1, v3, s[40:41]
	v_mul_f32_e32 v1, 0x4b800000, v2
	v_cndmask_b32_e32 v1, v2, v1, vcc
	v_rsq_f32_e32 v1, v1
	v_pk_mul_f32 v[100:101], v[100:101], v[112:113] op_sel_hi:[1,0]
	v_mul_f32_e32 v2, 0x45800000, v1
	v_cndmask_b32_e32 v110, v1, v2, vcc
	ds_read_b128 v[2:5], v40 offset:16
	ds_read_b128 v[10:13], v40
	ds_read_b128 v[6:9], v40 offset:8208
	ds_read_b128 v[14:17], v40 offset:8192
	v_pk_mul_f32 v[32:33], v[32:33], v[110:111] op_sel_hi:[1,0]
	v_pk_mul_f32 v[30:31], v[30:31], v[110:111] op_sel_hi:[1,0]
	v_pk_mul_f32 v[24:25], v[24:25], v[110:111] op_sel_hi:[1,0]
	v_pk_mul_f32 v[22:23], v[22:23], v[110:111] op_sel_hi:[1,0]
	v_cmp_lt_i32_e32 vcc, s69, v38
	s_or_b64 s[46:47], vcc, s[46:47]
	s_waitcnt lgkmcnt(1)
	v_pk_fma_f32 v[126:127], v[2:3], v[126:127], v[6:7]
	s_waitcnt lgkmcnt(0)
	v_pk_fma_f32 v[128:129], v[12:13], v[128:129], v[16:17]
	v_pk_fma_f32 v[130:131], v[10:11], v[130:131], v[14:15]
	v_pk_fma_f32 v[152:153], v[4:5], v[124:125], v[8:9]
	v_cvt_pk_bf16_f32 v124, v130, v131
	v_cvt_pk_bf16_f32 v125, v128, v129
	v_cvt_pk_bf16_f32 v126, v126, v127
	v_pk_mul_f32 v[128:129], v[136:137], v[112:113] op_sel_hi:[1,0]
	v_cvt_pk_bf16_f32 v127, v152, v153
	global_store_dwordx4 v[60:61], v[124:127], off
	v_pk_mul_f32 v[130:131], v[132:133], v[112:113] op_sel_hi:[1,0]
	v_pk_fma_f32 v[128:129], v[2:3], v[128:129], v[6:7]
	v_pk_mul_f32 v[124:125], v[138:139], v[112:113] op_sel_hi:[1,0]
	v_pk_mul_f32 v[126:127], v[134:135], v[112:113] op_sel_hi:[1,0]
	v_pk_fma_f32 v[124:125], v[10:11], v[124:125], v[14:15]
	v_pk_fma_f32 v[126:127], v[12:13], v[126:127], v[16:17]
	v_pk_fma_f32 v[130:131], v[4:5], v[130:131], v[8:9]
	v_cvt_pk_bf16_f32 v124, v124, v125
	v_cvt_pk_bf16_f32 v125, v126, v127
	v_cvt_pk_bf16_f32 v126, v128, v129
	s_nop 0
	v_cvt_pk_bf16_f32 v127, v130, v131
	global_store_dwordx4 v[56:57], v[124:127], off
	s_nop 1
	v_pk_mul_f32 v[124:125], v[146:147], v[110:111] op_sel_hi:[1,0]
	v_pk_mul_f32 v[126:127], v[142:143], v[110:111] op_sel_hi:[1,0]
	v_pk_fma_f32 v[10:11], v[10:11], v[124:125], v[14:15]
	v_pk_fma_f32 v[12:13], v[12:13], v[126:127], v[16:17]
	v_pk_mul_f32 v[14:15], v[144:145], v[110:111] op_sel_hi:[1,0]
	v_pk_mul_f32 v[16:17], v[140:141], v[110:111] op_sel_hi:[1,0]
	s_nop 0
	v_pk_fma_f32 v[8:9], v[4:5], v[16:17], v[8:9]
	v_pk_fma_f32 v[4:5], v[2:3], v[14:15], v[6:7]
	v_cvt_pk_bf16_f32 v2, v10, v11
	v_cvt_pk_bf16_f32 v3, v12, v13
	s_nop 0
	v_cvt_pk_bf16_f32 v4, v4, v5
	v_cvt_pk_bf16_f32 v5, v8, v9
	global_store_dwordx4 v[58:59], v[2:5], off
	s_nop 1
	ds_read_b128 v[2:5], v40 offset:2064
	s_nop 0
	ds_read_b128 v[10:13], v40 offset:2048
	ds_read_b128 v[6:9], v40 offset:10256
	ds_read_b128 v[14:17], v40 offset:10240
	s_waitcnt lgkmcnt(1)
; __device__ __forceinline__ unsigned cvt_pk_bf16(float lo, float hi) { unsigned r; asm volatile("v_cvt_pk_bf16_f32 %0, %1, %2" : "=v"(r) : "v"(lo), "v"(hi)); return r; }
; template <int NR>
; __device__ __forceinline__ void ln_comb(bf16_t* h, const bf16_t* sb, float scale, const float* g, const float* b, int lane) {
;     ...
; #pragma unroll
;     for (int j = 0; j < 4; ++j) {
;         const int c = 8 * lane + 512 * j;
;         const f32x4 g0 = *(const f32x4*)(g + c), g1 = *(const f32x4*)(g + c + 4), b0 = *(const f32x4*)(b + c), b1 = *(const f32x4*)(b + c + 4);
; #pragma unroll
;         for (int i = 0; i < NR; ++i) { const f32x4 y0 = v[i][j][0] * rstd[i] * g0 + b0, y1 = v[i][j][1] * rstd[i] * g1 + b1;
;             u32x4 w; w.x = cvt_pk_bf16(y0.x, y0.y); w.y = cvt_pk_bf16(y0.z, y0.w); w.z = cvt_pk_bf16(y1.x, y1.y); w.w = cvt_pk_bf16(y1.z, y1.w);
;             *(u32x4*)(h + (size_t)i * D + c) = w; }
	v_pk_fma_f32 v[96:97], v[96:97], v[2:3], v[6:7]
	s_waitcnt lgkmcnt(0)
	v_pk_fma_f32 v[98:99], v[98:99], v[12:13], v[16:17]
	v_pk_fma_f32 v[122:123], v[122:123], v[10:11], v[14:15]
	v_pk_fma_f32 v[124:125], v[94:95], v[4:5], v[8:9]
	v_cvt_pk_bf16_f32 v94, v122, v123
	v_cvt_pk_bf16_f32 v95, v98, v99
	v_cvt_pk_bf16_f32 v96, v96, v97
	v_pk_mul_f32 v[98:99], v[102:103], v[112:113] op_sel_hi:[1,0]
	v_cvt_pk_bf16_f32 v97, v124, v125
	global_store_dwordx4 v[60:61], v[94:97], off offset:1024
	v_pk_fma_f32 v[100:101], v[100:101], v[4:5], v[8:9]
	v_pk_fma_f32 v[98:99], v[98:99], v[2:3], v[6:7]
	v_pk_mul_f32 v[94:95], v[106:107], v[112:113] op_sel_hi:[1,0]
	v_pk_mul_f32 v[96:97], v[104:105], v[112:113] op_sel_hi:[1,0]
	v_pk_fma_f32 v[94:95], v[94:95], v[10:11], v[14:15]
	v_pk_fma_f32 v[96:97], v[96:97], v[12:13], v[16:17]
	v_cvt_pk_bf16_f32 v94, v94, v95
	s_nop 0
	v_cvt_pk_bf16_f32 v95, v96, v97
	v_cvt_pk_bf16_f32 v96, v98, v99
	v_cvt_pk_bf16_f32 v97, v100, v101
	global_store_dwordx4 v[56:57], v[94:97], off offset:1024
	s_nop 1
	v_pk_mul_f32 v[94:95], v[120:121], v[110:111] op_sel_hi:[1,0]
	v_pk_mul_f32 v[96:97], v[118:119], v[110:111] op_sel_hi:[1,0]
	v_pk_fma_f32 v[10:11], v[94:95], v[10:11], v[14:15]
	v_pk_fma_f32 v[12:13], v[96:97], v[12:13], v[16:17]
	v_pk_mul_f32 v[14:15], v[116:117], v[110:111] op_sel_hi:[1,0]
	v_pk_mul_f32 v[16:17], v[114:115], v[110:111] op_sel_hi:[1,0]
	s_nop 0
	v_pk_fma_f32 v[8:9], v[16:17], v[4:5], v[8:9]
	v_pk_fma_f32 v[4:5], v[14:15], v[2:3], v[6:7]
	v_cvt_pk_bf16_f32 v2, v10, v11
	v_cvt_pk_bf16_f32 v3, v12, v13
	s_nop 0
	v_cvt_pk_bf16_f32 v4, v4, v5
	v_cvt_pk_bf16_f32 v5, v8, v9
	global_store_dwordx4 v[58:59], v[2:5], off offset:1024
	s_nop 1
	ds_read_b128 v[2:5], v40 offset:4112
	s_nop 0
	ds_read_b128 v[6:9], v40 offset:4096
	ds_read_b128 v[10:13], v40 offset:12304
	ds_read_b128 v[14:17], v40 offset:12288
	s_waitcnt lgkmcnt(1)
	v_pk_fma_f32 v[80:81], v[80:81], v[2:3], v[10:11]
	s_waitcnt lgkmcnt(0)
	v_pk_fma_f32 v[82:83], v[82:83], v[8:9], v[16:17]
	v_pk_fma_f32 v[84:85], v[84:85], v[6:7], v[14:15]
	v_pk_fma_f32 v[94:95], v[78:79], v[4:5], v[12:13]
	v_cvt_pk_bf16_f32 v78, v84, v85
	v_cvt_pk_bf16_f32 v79, v82, v83
	v_cvt_pk_bf16_f32 v80, v80, v81
	v_pk_mul_f32 v[84:85], v[86:87], v[112:113] op_sel_hi:[1,0]
	v_cvt_pk_bf16_f32 v81, v94, v95
	global_store_dwordx4 v[60:61], v[78:81], off offset:2048
	v_pk_mul_f32 v[82:83], v[88:89], v[112:113] op_sel_hi:[1,0]
	v_pk_fma_f32 v[84:85], v[84:85], v[4:5], v[12:13]
	v_pk_mul_f32 v[78:79], v[92:93], v[112:113] op_sel_hi:[1,0]
	v_pk_mul_f32 v[80:81], v[90:91], v[112:113] op_sel_hi:[1,0]
	v_pk_fma_f32 v[78:79], v[78:79], v[6:7], v[14:15]
	v_pk_fma_f32 v[80:81], v[80:81], v[8:9], v[16:17]
	v_pk_fma_f32 v[8:9], v[30:31], v[8:9], v[16:17]
	v_pk_fma_f32 v[6:7], v[32:33], v[6:7], v[14:15]
	v_pk_mul_f32 v[14:15], v[28:29], v[110:111] op_sel_hi:[1,0]
	v_pk_mul_f32 v[16:17], v[26:27], v[110:111] op_sel_hi:[1,0]
	v_pk_fma_f32 v[82:83], v[82:83], v[2:3], v[10:11]
	v_pk_fma_f32 v[12:13], v[16:17], v[4:5], v[12:13]
	v_pk_fma_f32 v[4:5], v[14:15], v[2:3], v[10:11]
	v_cvt_pk_bf16_f32 v78, v78, v79
	v_cvt_pk_bf16_f32 v79, v80, v81
	v_cvt_pk_bf16_f32 v80, v82, v83
	v_cvt_pk_bf16_f32 v81, v84, v85
	global_store_dwordx4 v[56:57], v[78:81], off offset:2048
	v_cvt_pk_bf16_f32 v2, v6, v7
	v_cvt_pk_bf16_f32 v3, v8, v9
	v_cvt_pk_bf16_f32 v4, v4, v5
	v_cvt_pk_bf16_f32 v5, v12, v13
	global_store_dwordx4 v[58:59], v[2:5], off offset:2048
	s_nop 1
	ds_read_b128 v[2:5], v40 offset:6160
	s_nop 0
	ds_read_b128 v[6:9], v40 offset:6144
	ds_read_b128 v[10:13], v40 offset:14352
	ds_read_b128 v[14:17], v40 offset:14336
	v_pk_mul_f32 v[26:27], v[68:69], v[108:109] op_sel_hi:[1,0]
	v_pk_mul_f32 v[28:29], v[66:67], v[108:109] op_sel_hi:[1,0]
	v_pk_mul_f32 v[30:31], v[64:65], v[108:109] op_sel_hi:[1,0]
	v_pk_mul_f32 v[32:33], v[62:63], v[108:109] op_sel_hi:[1,0]
	s_waitcnt lgkmcnt(1)
	v_pk_fma_f32 v[30:31], v[30:31], v[2:3], v[10:11]
	s_waitcnt lgkmcnt(0)
	v_pk_fma_f32 v[28:29], v[28:29], v[8:9], v[16:17]
	v_pk_fma_f32 v[26:27], v[26:27], v[6:7], v[14:15]
	v_pk_fma_f32 v[32:33], v[32:33], v[4:5], v[12:13]
	v_cvt_pk_bf16_f32 v26, v26, v27
	v_cvt_pk_bf16_f32 v27, v28, v29
	v_cvt_pk_bf16_f32 v28, v30, v31
	v_pk_mul_f32 v[30:31], v[72:73], v[112:113] op_sel_hi:[1,0]
	v_cvt_pk_bf16_f32 v29, v32, v33
	global_store_dwordx4 v[60:61], v[26:29], off offset:3072
	v_pk_mul_f32 v[32:33], v[70:71], v[112:113] op_sel_hi:[1,0]
	v_pk_fma_f32 v[30:31], v[30:31], v[2:3], v[10:11]
	v_pk_mul_f32 v[26:27], v[76:77], v[112:113] op_sel_hi:[1,0]
	v_pk_mul_f32 v[28:29], v[74:75], v[112:113] op_sel_hi:[1,0]
	v_pk_fma_f32 v[26:27], v[26:27], v[6:7], v[14:15]
	v_pk_fma_f32 v[28:29], v[28:29], v[8:9], v[16:17]
	v_pk_fma_f32 v[8:9], v[22:23], v[8:9], v[16:17]
	v_pk_fma_f32 v[6:7], v[24:25], v[6:7], v[14:15]
	v_pk_mul_f32 v[14:15], v[20:21], v[110:111] op_sel_hi:[1,0]
	v_pk_mul_f32 v[16:17], v[18:19], v[110:111] op_sel_hi:[1,0]
	v_pk_fma_f32 v[32:33], v[32:33], v[4:5], v[12:13]
	v_pk_fma_f32 v[12:13], v[16:17], v[4:5], v[12:13]
	v_pk_fma_f32 v[4:5], v[14:15], v[2:3], v[10:11]
	v_cvt_pk_bf16_f32 v26, v26, v27
	v_cvt_pk_bf16_f32 v27, v28, v29
	v_cvt_pk_bf16_f32 v28, v30, v31
	v_cvt_pk_bf16_f32 v29, v32, v33
	global_store_dwordx4 v[56:57], v[26:29], off offset:3072
	v_cvt_pk_bf16_f32 v2, v6, v7
	v_cvt_pk_bf16_f32 v3, v8, v9
	v_cvt_pk_bf16_f32 v4, v4, v5
	v_cvt_pk_bf16_f32 v5, v12, v13
	global_store_dwordx4 v[58:59], v[2:5], off offset:3072
	s_andn2_b64 exec, exec, s[46:47]
	s_cbranch_execnz .LBB0_90

;     __device__ bool next(int i, Unit& u) const { const int idx = i * G + c; if (idx >= 64) return false; u.kp = idx & 3; u.pn = (idx >> 2) & 7; u.pm = 192 + (idx >> 5); return true; }
; #define PG8_STAGE(bufoff, gbase, voff) do { _Pragma("unroll") for (int _i = 0; _i < 2; ++_i) \
;         __builtin_amdgcn_global_load_lds((const unsigned*)((const char*)(gbase) + (voff)[_i]), (LAS unsigned*)(lds + (bufoff) + ldsw + _i * 8192), 16, 0, 0); } while (0)
; #define PG8_LDA(dst, b, h) do { _Pragma("unroll") for (int m = 0; m < 4; ++m) _Pragma("unroll") for (int k = 0; k < 2; ++k) dst[m][k] = *(const LAS bf16x8*)(lds + PG8_SA(b, h) + aoff + m * 2048 + k * 1024); } while (0)
; #define PG8_LDB(dst, b, h) do { _Pragma("unroll") for (int n = 0; n < 2; ++n) _Pragma("unroll") for (int k = 0; k < 2; ++k) dst[n][k] = *(const LAS bf16x8*)(lds + PG8_SB(b, h) + boff + n * 2048 + k * 1024); } while (0)
; #define PG8_BAR __builtin_amdgcn_s_barrier()
; template <class Epi, class Sched = StaticOrder, bool ALIGN_EPI = true>
; __device__ __forceinline__ void gemm_phase(LAS unsigned char* lds, const Gemm g, const Sched& S, const Epi& E) {
;     ...
;         const bool has_next = S.next(ui + 1, nxt);
;         const char* nA = has_next ? (const char*)g.A + (size_t)nxt.pm * tstep + (size_t)nxt.kp * K * 2 : cA; const char* nB = has_next ? (const char*)g.Bt + (size_t)nxt.pn * tstep + (size_t)nxt.kp * K * 2 : cB;
;         for (int t = 0; t < nt; t += 2) {
;             const bool last = (t == nt - 2);
;             const char* a1 = cA + (size_t)(t + 1) * kstep;
;             const char* a2 = last ? nA : cA + (size_t)(t + 2) * kstep; const char* b2 = last ? nB : cB + (size_t)(t + 2) * kstep;
;             const char* a3 = a2 + kstep; const char* b3 = b2 + kstep;
;             PG8_LDB(B0, 0, 0); PG8_LDB(B1, 0, 1); PG8_SCHED; PG8_LDA(At, 0, 0); PG8_STAGE(PG8_SA(1, 1), a1 + hstep, voffA);
;             PG8_WAIT_V(8); PG8_WAIT_L(0); PG8_BAR; PG8_MMA(0, 0, At, B0); PG8_MMA(0, 1, At, B1); PG8_BAR; PG8_SCHED;
;             PG8_LDA(At, 0, 1); PG8_STAGE(PG8_SB(0, 0), b2, voffB); PG8_STAGE(PG8_SB(0, 1), b2 + hstep, voffB); PG8_STAGE(PG8_SA(0, 0), a2, voffA);
;             PG8_WAIT_V(8); PG8_WAIT_L(0); PG8_BAR; PG8_MMA(1, 0, At, B0); PG8_MMA(1, 1, At, B1); PG8_BAR; PG8_SCHED;
;     ...
;         cur = nxt; cA = nA; cB = nB; ++ui;
;         if constexpr (ALIGN_EPI) { if (wr == 1) PG8_BAR; }
.LBB0_105:
	s_ashr_i32 s43, s42, 31
	s_lshl_b64 s[0:1], s[42:43], 20
	v_readlane_b32 s16, v253, 23
	v_readlane_b32 s17, v253, 24
	s_add_u32 s44, s16, s0
	s_addc_u32 s45, s17, s1
	s_and_b64 s[0:1], s[40:41], exec
	s_cselect_b32 s30, s45, s81
	s_cselect_b32 s31, s44, s80
	s_ashr_i32 s21, s20, 31
	s_lshl_b64 s[0:1], s[20:21], 20
	v_readlane_b32 s16, v253, 25
	s_add_u32 s0, s16, s0
	v_readlane_b32 s16, v253, 26
	s_addc_u32 s1, s16, s1
	s_and_b64 s[16:17], s[40:41], exec
	s_cselect_b32 s21, s1, s47
	s_cselect_b32 s36, s0, s46
	s_add_u32 s80, s80, 0x80080
	s_addc_u32 s81, s81, 0
	s_add_u32 s37, s46, 0x100
	s_addc_u32 s43, s47, 0
	s_mov_b32 s49, -2
	s_waitcnt vmcnt(0)
	s_cmp_eq_u32 s22, 1
	s_cbranch_scc1 .Lmy_nb_106
	s_cmp_eq_u64 s[2:3], 0
	s_cbranch_scc1 .Lmy_nb_106
	s_barrier
.Lmy_nb_106:
	s_add_u32 s16, s80, 0xfff80080
	s_addc_u32 s17, s81, -1
	s_add_i32 s33, 0, 0x10000
	s_cmp_eq_u32 s49, 28
	s_cselect_b32 vcc_hi, s30, s17
	s_cselect_b32 vcc_lo, s31, s16
	v_add_u32_e32 v142, s33, v144
	s_cselect_b32 s47, s21, s43
	s_cselect_b32 s46, s36, s37
	s_add_i32 s70, 0, 0x14000
	ds_read_b128 v[148:151], v142
	ds_read_b128 v[160:163], v142 offset:1024
	ds_read_b128 v[164:167], v142 offset:2048
	ds_read_b128 v[168:171], v142 offset:3072
	v_add_u32_e32 v142, s70, v144
	ds_read_b128 v[172:175], v142
	ds_read_b128 v[176:179], v142 offset:1024
	ds_read_b128 v[180:183], v142 offset:2048
	ds_read_b128 v[184:187], v142 offset:3072
	v_lshl_add_u64 v[142:143], s[80:81], 0, v[138:139]
	s_add_i32 m0, s7, 0xc000
	ds_read_b128 v[188:191], v146
	ds_read_b128 v[192:195], v146 offset:1024
	ds_read_b128 v[210:213], v146 offset:2048
	ds_read_b128 v[214:217], v146 offset:3072
	ds_read_b128 v[218:221], v146 offset:4096
	ds_read_b128 v[222:225], v146 offset:5120
	ds_read_b128 v[226:229], v146 offset:6144
	ds_read_b128 v[230:233], v146 offset:7168
	global_load_lds_dwordx4 v[142:143], off
	v_lshl_add_u64 v[142:143], s[80:81], 0, v[140:141]
	s_add_i32 m0, s7, 0xe000
	s_nop 0
	global_load_lds_dwordx4 v[142:143], off
	s_waitcnt vmcnt(8)
	s_waitcnt lgkmcnt(0)
	s_barrier
	s_setprio 1
	s_waitcnt lgkmcnt(0)
	v_mfma_f32_16x16x32_bf16 v[126:129], v[148:151], v[188:191], 0
	v_mfma_f32_16x16x32_bf16 v[122:125], v[164:167], v[188:191], 0
	v_mfma_f32_16x16x32_bf16 v[118:121], v[148:151], v[210:213], 0
	v_mfma_f32_16x16x32_bf16 v[110:113], v[164:167], v[210:213], 0
	v_mfma_f32_16x16x32_bf16 v[102:105], v[148:151], v[218:221], 0
	v_mfma_f32_16x16x32_bf16 v[94:97], v[164:167], v[218:221], 0
	v_mfma_f32_16x16x32_bf16 v[82:85], v[148:151], v[226:229], 0
	v_mfma_f32_16x16x32_bf16 v[74:77], v[164:167], v[226:229], 0
	v_mfma_f32_16x16x32_bf16 v[126:129], v[160:163], v[192:195], v[126:129]
	v_mfma_f32_16x16x32_bf16 v[122:125], v[168:171], v[192:195], v[122:125]
	v_mfma_f32_16x16x32_bf16 v[118:121], v[160:163], v[214:217], v[118:121]
	v_mfma_f32_16x16x32_bf16 v[110:113], v[168:171], v[214:217], v[110:113]
	v_mfma_f32_16x16x32_bf16 v[102:105], v[160:163], v[222:225], v[102:105]
	v_mfma_f32_16x16x32_bf16 v[94:97], v[168:171], v[222:225], v[94:97]
	v_mfma_f32_16x16x32_bf16 v[82:85], v[160:163], v[230:233], v[82:85]
	v_mfma_f32_16x16x32_bf16 v[74:77], v[168:171], v[230:233], v[74:77]
	s_setprio 0
	s_setprio 1
	v_mfma_f32_16x16x32_bf16 v[114:117], v[172:175], v[188:191], 0
	v_mfma_f32_16x16x32_bf16 v[106:109], v[180:183], v[188:191], 0
	v_mfma_f32_16x16x32_bf16 v[98:101], v[172:175], v[210:213], 0
	v_mfma_f32_16x16x32_bf16 v[90:93], v[180:183], v[210:213], 0
	v_mfma_f32_16x16x32_bf16 v[86:89], v[172:175], v[218:221], 0
	v_mfma_f32_16x16x32_bf16 v[78:81], v[180:183], v[218:221], 0
	v_mfma_f32_16x16x32_bf16 v[70:73], v[172:175], v[226:229], 0
	v_mfma_f32_16x16x32_bf16 v[66:69], v[180:183], v[226:229], 0
	v_mfma_f32_16x16x32_bf16 v[114:117], v[176:179], v[192:195], v[114:117]
	v_mfma_f32_16x16x32_bf16 v[106:109], v[184:187], v[192:195], v[106:109]
	v_mfma_f32_16x16x32_bf16 v[98:101], v[176:179], v[214:217], v[98:101]
	v_mfma_f32_16x16x32_bf16 v[90:93], v[184:187], v[214:217], v[90:93]
	v_mfma_f32_16x16x32_bf16 v[86:89], v[176:179], v[222:225], v[86:89]
	v_mfma_f32_16x16x32_bf16 v[78:81], v[184:187], v[222:225], v[78:81]
	v_mfma_f32_16x16x32_bf16 v[70:73], v[176:179], v[230:233], v[70:73]
	v_mfma_f32_16x16x32_bf16 v[66:69], v[184:187], v[230:233], v[66:69]
	s_setprio 0
	s_barrier
	s_add_i32 s16, s33, s5
	v_lshl_add_u64 v[142:143], s[46:47], 0, v[134:135]
	s_mov_b32 m0, s16
	ds_read_b128 v[188:191], v146 offset:16384
	ds_read_b128 v[192:195], v146 offset:17408
	ds_read_b128 v[210:213], v146 offset:18432
	ds_read_b128 v[214:217], v146 offset:19456
	ds_read_b128 v[218:221], v146 offset:20480
	ds_read_b128 v[222:225], v146 offset:21504
	ds_read_b128 v[226:229], v146 offset:22528
	ds_read_b128 v[230:233], v146 offset:23552
	global_load_lds_dwordx4 v[142:143], off
	s_add_i32 m0, s16, 0x2000
	s_add_u32 s16, s46, 0x80000
	v_lshl_add_u64 v[152:153], s[46:47], 0, v[130:131]
	s_addc_u32 s17, s47, 0
	s_add_i32 s33, s70, s5
	global_load_lds_dwordx4 v[152:153], off
	v_lshl_add_u64 v[196:197], s[16:17], 0, v[134:135]
	s_mov_b32 m0, s33
	v_lshl_add_u64 v[234:235], vcc, 0, v[132:133]
	global_load_lds_dwordx4 v[196:197], off
	v_lshl_add_u64 v[196:197], s[16:17], 0, v[130:131]
	s_add_i32 m0, s33, 0x2000
	s_nop 0
	global_load_lds_dwordx4 v[196:197], off
	v_lshl_add_u64 v[196:197], vcc, 0, v[136:137]
	s_mov_b32 m0, s7
	s_nop 0
	global_load_lds_dwordx4 v[196:197], off
	s_mov_b32 m0, s8
	s_nop 0
	global_load_lds_dwordx4 v[234:235], off
	s_waitcnt vmcnt(8)
	s_waitcnt lgkmcnt(0)
	s_barrier
; #define PG8_STAGE(bufoff, gbase, voff) do { _Pragma("unroll") for (int _i = 0; _i < 2; ++_i) \
;         __builtin_amdgcn_global_load_lds((const unsigned*)((const char*)(gbase) + (voff)[_i]), (LAS unsigned*)(lds + (bufoff) + ldsw + _i * 8192), 16, 0, 0); } while (0)
; #define PG8_LDA(dst, b, h) do { _Pragma("unroll") for (int m = 0; m < 4; ++m) _Pragma("unroll") for (int k = 0; k < 2; ++k) dst[m][k] = *(const LAS bf16x8*)(lds + PG8_SA(b, h) + aoff + m * 2048 + k * 1024); } while (0)
; #define PG8_LDB(dst, b, h) do { _Pragma("unroll") for (int n = 0; n < 2; ++n) _Pragma("unroll") for (int k = 0; k < 2; ++k) dst[n][k] = *(const LAS bf16x8*)(lds + PG8_SB(b, h) + boff + n * 2048 + k * 1024); } while (0)
; #define PG8_MMA(ai, bj, At, Bt) do { __builtin_amdgcn_s_setprio(1); _Pragma("unroll") for (int m = 0; m < 4; ++m) _Pragma("unroll") for (int n = 0; n < 2; ++n) _Pragma("unroll") for (int k = 0; k < 2; ++k) \
;         acc[ai][bj][m][n] = __builtin_amdgcn_mfma_f32_16x16x32_bf16(Bt[n][k], At[m][k], acc[ai][bj][m][n], 0, 0, 0); __builtin_amdgcn_s_setprio(0); } while (0)
; #define PG8_WAIT_V(n) asm volatile("s_waitcnt vmcnt(" #n ")" ::: "memory")
; #define PG8_WAIT_L(n) asm volatile("s_waitcnt lgkmcnt(" #n ")" ::: "memory")
; #define PG8_BAR __builtin_amdgcn_s_barrier()
; #define PG8_SCHED __builtin_amdgcn_sched_barrier(0)
; template <class Epi, class Sched = StaticOrder, bool ALIGN_EPI = true>
; __device__ __forceinline__ void gemm_phase(LAS unsigned char* lds, const Gemm g, const Sched& S, const Epi& E) {
;     ...
;             PG8_LDA(At, 0, 1); PG8_STAGE(PG8_SB(0, 0), b2, voffB); PG8_STAGE(PG8_SB(0, 1), b2 + hstep, voffB); PG8_STAGE(PG8_SA(0, 0), a2, voffA);
;             PG8_WAIT_V(8); PG8_WAIT_L(0); PG8_BAR; PG8_MMA(1, 0, At, B0); PG8_MMA(1, 1, At, B1); PG8_BAR; PG8_SCHED;
;             PG8_LDB(B0, 1, 0); PG8_LDB(B1, 1, 1); PG8_SCHED; PG8_LDA(At, 1, 0); PG8_STAGE(PG8_SA(0, 1), a2 + hstep, voffA);
;             PG8_WAIT_V(8); PG8_WAIT_L(0); PG8_BAR; PG8_MMA(0, 0, At, B0); PG8_MMA(0, 1, At, B1); PG8_BAR; PG8_SCHED;
	s_setprio 1
	s_waitcnt lgkmcnt(0)
	v_mfma_f32_16x16x32_bf16 v[62:65], v[148:151], v[188:191], 0
	v_mfma_f32_16x16x32_bf16 v[58:61], v[164:167], v[188:191], 0
	v_mfma_f32_16x16x32_bf16 v[54:57], v[148:151], v[210:213], 0
	v_mfma_f32_16x16x32_bf16 v[46:49], v[164:167], v[210:213], 0
	v_mfma_f32_16x16x32_bf16 v[38:41], v[148:151], v[218:221], 0
	v_mfma_f32_16x16x32_bf16 v[30:33], v[164:167], v[218:221], 0
	v_mfma_f32_16x16x32_bf16 v[22:25], v[148:151], v[226:229], 0
	v_mfma_f32_16x16x32_bf16 v[14:17], v[164:167], v[226:229], 0
	v_mfma_f32_16x16x32_bf16 v[62:65], v[160:163], v[192:195], v[62:65]
	v_mfma_f32_16x16x32_bf16 v[58:61], v[168:171], v[192:195], v[58:61]
	v_mfma_f32_16x16x32_bf16 v[54:57], v[160:163], v[214:217], v[54:57]
	v_mfma_f32_16x16x32_bf16 v[46:49], v[168:171], v[214:217], v[46:49]
	v_mfma_f32_16x16x32_bf16 v[38:41], v[160:163], v[222:225], v[38:41]
	v_mfma_f32_16x16x32_bf16 v[30:33], v[168:171], v[222:225], v[30:33]
	v_mfma_f32_16x16x32_bf16 v[22:25], v[160:163], v[230:233], v[22:25]
	v_mfma_f32_16x16x32_bf16 v[14:17], v[168:171], v[230:233], v[14:17]
	s_setprio 0
	s_setprio 1
	v_mfma_f32_16x16x32_bf16 v[50:53], v[172:175], v[188:191], 0
	v_mfma_f32_16x16x32_bf16 v[42:45], v[180:183], v[188:191], 0
	v_mfma_f32_16x16x32_bf16 v[34:37], v[172:175], v[210:213], 0
	v_mfma_f32_16x16x32_bf16 v[26:29], v[180:183], v[210:213], 0
	v_mfma_f32_16x16x32_bf16 v[18:21], v[172:175], v[218:221], 0
	v_mfma_f32_16x16x32_bf16 v[10:13], v[180:183], v[218:221], 0
	v_mfma_f32_16x16x32_bf16 v[6:9], v[172:175], v[226:229], 0
	v_mfma_f32_16x16x32_bf16 v[2:5], v[180:183], v[226:229], 0
	v_mfma_f32_16x16x32_bf16 v[50:53], v[176:179], v[192:195], v[50:53]
	v_mfma_f32_16x16x32_bf16 v[42:45], v[184:187], v[192:195], v[42:45]
	v_mfma_f32_16x16x32_bf16 v[34:37], v[176:179], v[214:217], v[34:37]
	v_mfma_f32_16x16x32_bf16 v[26:29], v[184:187], v[214:217], v[26:29]
	v_mfma_f32_16x16x32_bf16 v[18:21], v[176:179], v[222:225], v[18:21]
	v_mfma_f32_16x16x32_bf16 v[10:13], v[184:187], v[222:225], v[10:13]
	v_mfma_f32_16x16x32_bf16 v[6:9], v[176:179], v[230:233], v[6:9]
	v_mfma_f32_16x16x32_bf16 v[2:5], v[184:187], v[230:233], v[2:5]
	s_setprio 0
	s_barrier
	s_add_i32 s33, 0, 0x18000
	v_add_u32_e32 v147, s33, v144
	s_add_i32 s70, 0, 0x1c000
	ds_read_b128 v[148:151], v147
	ds_read_b128 v[160:163], v147 offset:1024
	ds_read_b128 v[164:167], v147 offset:2048
	ds_read_b128 v[168:171], v147 offset:3072
	v_add_u32_e32 v147, s70, v144
	ds_read_b128 v[172:175], v147
	ds_read_b128 v[176:179], v147 offset:1024
	ds_read_b128 v[180:183], v147 offset:2048
	ds_read_b128 v[184:187], v147 offset:3072
	s_add_u32 s16, vcc_lo, 0x80000
	s_addc_u32 s17, vcc_hi, 0
	s_mov_b32 m0, s9
	v_lshl_add_u64 v[236:237], s[16:17], 0, v[136:137]
	ds_read_b128 v[188:191], v146 offset:32768
	ds_read_b128 v[192:195], v146 offset:33792
	ds_read_b128 v[210:213], v146 offset:34816
	ds_read_b128 v[214:217], v146 offset:35840
	ds_read_b128 v[218:221], v146 offset:36864
	ds_read_b128 v[222:225], v146 offset:37888
	ds_read_b128 v[226:229], v146 offset:38912
	ds_read_b128 v[230:233], v146 offset:39936
	global_load_lds_dwordx4 v[236:237], off
	v_lshl_add_u64 v[236:237], s[16:17], 0, v[132:133]
	s_mov_b32 m0, s10
	s_nop 0
	global_load_lds_dwordx4 v[236:237], off
	s_waitcnt vmcnt(8)
	s_waitcnt lgkmcnt(0)
	s_barrier
	s_setprio 1
	s_waitcnt lgkmcnt(0)
	v_mfma_f32_16x16x32_bf16 v[126:129], v[148:151], v[188:191], v[126:129]
	v_mfma_f32_16x16x32_bf16 v[122:125], v[164:167], v[188:191], v[122:125]
	v_mfma_f32_16x16x32_bf16 v[118:121], v[148:151], v[210:213], v[118:121]
	v_mfma_f32_16x16x32_bf16 v[110:113], v[164:167], v[210:213], v[110:113]
	v_mfma_f32_16x16x32_bf16 v[102:105], v[148:151], v[218:221], v[102:105]
	v_mfma_f32_16x16x32_bf16 v[94:97], v[164:167], v[218:221], v[94:97]
	v_mfma_f32_16x16x32_bf16 v[82:85], v[148:151], v[226:229], v[82:85]
	v_mfma_f32_16x16x32_bf16 v[74:77], v[164:167], v[226:229], v[74:77]
	v_mfma_f32_16x16x32_bf16 v[126:129], v[160:163], v[192:195], v[126:129]
	v_mfma_f32_16x16x32_bf16 v[122:125], v[168:171], v[192:195], v[122:125]
	v_mfma_f32_16x16x32_bf16 v[118:121], v[160:163], v[214:217], v[118:121]
	v_mfma_f32_16x16x32_bf16 v[110:113], v[168:171], v[214:217], v[110:113]
	v_mfma_f32_16x16x32_bf16 v[102:105], v[160:163], v[222:225], v[102:105]
	v_mfma_f32_16x16x32_bf16 v[94:97], v[168:171], v[222:225], v[94:97]
	v_mfma_f32_16x16x32_bf16 v[82:85], v[160:163], v[230:233], v[82:85]
	v_mfma_f32_16x16x32_bf16 v[74:77], v[168:171], v[230:233], v[74:77]
	s_setprio 0
	s_setprio 1
	v_mfma_f32_16x16x32_bf16 v[114:117], v[172:175], v[188:191], v[114:117]
	v_mfma_f32_16x16x32_bf16 v[106:109], v[180:183], v[188:191], v[106:109]
	v_mfma_f32_16x16x32_bf16 v[98:101], v[172:175], v[210:213], v[98:101]
	v_mfma_f32_16x16x32_bf16 v[90:93], v[180:183], v[210:213], v[90:93]
	v_mfma_f32_16x16x32_bf16 v[86:89], v[172:175], v[218:221], v[86:89]
	v_mfma_f32_16x16x32_bf16 v[78:81], v[180:183], v[218:221], v[78:81]
	v_mfma_f32_16x16x32_bf16 v[70:73], v[172:175], v[226:229], v[70:73]
	v_mfma_f32_16x16x32_bf16 v[66:69], v[180:183], v[226:229], v[66:69]
	v_mfma_f32_16x16x32_bf16 v[114:117], v[176:179], v[192:195], v[114:117]
	v_mfma_f32_16x16x32_bf16 v[106:109], v[184:187], v[192:195], v[106:109]
	v_mfma_f32_16x16x32_bf16 v[98:101], v[176:179], v[214:217], v[98:101]
	v_mfma_f32_16x16x32_bf16 v[90:93], v[184:187], v[214:217], v[90:93]
	v_mfma_f32_16x16x32_bf16 v[86:89], v[176:179], v[222:225], v[86:89]
	v_mfma_f32_16x16x32_bf16 v[78:81], v[184:187], v[222:225], v[78:81]
	v_mfma_f32_16x16x32_bf16 v[70:73], v[176:179], v[230:233], v[70:73]
	v_mfma_f32_16x16x32_bf16 v[66:69], v[184:187], v[230:233], v[66:69]
	s_setprio 0
	s_barrier
; #define PG8_STAGE(bufoff, gbase, voff) do { _Pragma("unroll") for (int _i = 0; _i < 2; ++_i) \
;         __builtin_amdgcn_global_load_lds((const unsigned*)((const char*)(gbase) + (voff)[_i]), (LAS unsigned*)(lds + (bufoff) + ldsw + _i * 8192), 16, 0, 0); } while (0)
; #define PG8_LDA(dst, b, h) do { _Pragma("unroll") for (int m = 0; m < 4; ++m) _Pragma("unroll") for (int k = 0; k < 2; ++k) dst[m][k] = *(const LAS bf16x8*)(lds + PG8_SA(b, h) + aoff + m * 2048 + k * 1024); } while (0)
; #define PG8_MMA(ai, bj, At, Bt) do { __builtin_amdgcn_s_setprio(1); _Pragma("unroll") for (int m = 0; m < 4; ++m) _Pragma("unroll") for (int n = 0; n < 2; ++n) _Pragma("unroll") for (int k = 0; k < 2; ++k) \
;         acc[ai][bj][m][n] = __builtin_amdgcn_mfma_f32_16x16x32_bf16(Bt[n][k], At[m][k], acc[ai][bj][m][n], 0, 0, 0); __builtin_amdgcn_s_setprio(0); } while (0)
; #define PG8_WAIT_V(n) asm volatile("s_waitcnt vmcnt(" #n ")" ::: "memory")
; #define PG8_WAIT_L(n) asm volatile("s_waitcnt lgkmcnt(" #n ")" ::: "memory")
; #define PG8_BAR __builtin_amdgcn_s_barrier()
; #define PG8_SCHED __builtin_amdgcn_sched_barrier(0)
; template <class Epi, class Sched = StaticOrder, bool ALIGN_EPI = true>
; __device__ __forceinline__ void gemm_phase(LAS unsigned char* lds, const Gemm g, const Sched& S, const Epi& E) {
;     ...
;             PG8_LDA(At, 1, 1); PG8_STAGE(PG8_SB(1, 0), b3, voffB); PG8_STAGE(PG8_SB(1, 1), b3 + hstep, voffB); PG8_STAGE(PG8_SA(1, 0), a3, voffA);
;             PG8_WAIT_V(8); PG8_WAIT_L(0); PG8_BAR; PG8_MMA(1, 0, At, B0); PG8_MMA(1, 1, At, B1); PG8_BAR; PG8_SCHED;
;         }
	s_add_i32 s16, s33, s5
	v_lshl_add_u64 v[142:143], v[142:143], 0, s[34:35]
	s_mov_b32 m0, s16
	ds_read_b128 v[188:191], v146 offset:49152
	ds_read_b128 v[192:195], v146 offset:50176
	ds_read_b128 v[210:213], v146 offset:51200
	ds_read_b128 v[214:217], v146 offset:52224
	ds_read_b128 v[218:221], v146 offset:53248
	ds_read_b128 v[222:225], v146 offset:54272
	ds_read_b128 v[226:229], v146 offset:55296
	ds_read_b128 v[230:233], v146 offset:56320
	global_load_lds_dwordx4 v[142:143], off
	s_add_i32 m0, s16, 0x2000
	s_add_u32 s16, s46, 0x80080
	v_lshl_add_u64 v[142:143], v[152:153], 0, s[34:35]
	s_addc_u32 s17, s47, 0
	s_add_i32 s33, s70, s5
	global_load_lds_dwordx4 v[142:143], off
	v_lshl_add_u64 v[142:143], s[16:17], 0, v[134:135]
	s_mov_b32 m0, s33
	s_nop 0
	global_load_lds_dwordx4 v[142:143], off
	v_lshl_add_u64 v[142:143], s[16:17], 0, v[130:131]
	s_add_i32 m0, s33, 0x2000
	s_nop 0
	global_load_lds_dwordx4 v[142:143], off
	v_lshl_add_u64 v[142:143], v[196:197], 0, s[34:35]
	s_mov_b32 m0, s11
	s_nop 0
	global_load_lds_dwordx4 v[142:143], off
	v_lshl_add_u64 v[142:143], v[234:235], 0, s[34:35]
	s_mov_b32 m0, s18
	s_nop 0
	global_load_lds_dwordx4 v[142:143], off
	s_waitcnt vmcnt(8)
	s_waitcnt lgkmcnt(0)
	s_barrier
	s_setprio 1
	s_waitcnt lgkmcnt(0)
	v_mfma_f32_16x16x32_bf16 v[62:65], v[148:151], v[188:191], v[62:65]
	v_mfma_f32_16x16x32_bf16 v[58:61], v[164:167], v[188:191], v[58:61]
	v_mfma_f32_16x16x32_bf16 v[54:57], v[148:151], v[210:213], v[54:57]
	v_mfma_f32_16x16x32_bf16 v[46:49], v[164:167], v[210:213], v[46:49]
	v_mfma_f32_16x16x32_bf16 v[38:41], v[148:151], v[218:221], v[38:41]
	v_mfma_f32_16x16x32_bf16 v[30:33], v[164:167], v[218:221], v[30:33]
	v_mfma_f32_16x16x32_bf16 v[22:25], v[148:151], v[226:229], v[22:25]
	v_mfma_f32_16x16x32_bf16 v[14:17], v[164:167], v[226:229], v[14:17]
	v_mfma_f32_16x16x32_bf16 v[62:65], v[160:163], v[192:195], v[62:65]
	v_mfma_f32_16x16x32_bf16 v[58:61], v[168:171], v[192:195], v[58:61]
	v_mfma_f32_16x16x32_bf16 v[54:57], v[160:163], v[214:217], v[54:57]
	v_mfma_f32_16x16x32_bf16 v[46:49], v[168:171], v[214:217], v[46:49]
	v_mfma_f32_16x16x32_bf16 v[38:41], v[160:163], v[222:225], v[38:41]
	v_mfma_f32_16x16x32_bf16 v[30:33], v[168:171], v[222:225], v[30:33]
	v_mfma_f32_16x16x32_bf16 v[22:25], v[160:163], v[230:233], v[22:25]
	v_mfma_f32_16x16x32_bf16 v[14:17], v[168:171], v[230:233], v[14:17]
	s_setprio 0
	s_setprio 1
	v_mfma_f32_16x16x32_bf16 v[50:53], v[172:175], v[188:191], v[50:53]
	v_mfma_f32_16x16x32_bf16 v[42:45], v[180:183], v[188:191], v[42:45]
	v_mfma_f32_16x16x32_bf16 v[34:37], v[172:175], v[210:213], v[34:37]
	v_mfma_f32_16x16x32_bf16 v[26:29], v[180:183], v[210:213], v[26:29]
	v_mfma_f32_16x16x32_bf16 v[18:21], v[172:175], v[218:221], v[18:21]
	v_mfma_f32_16x16x32_bf16 v[10:13], v[180:183], v[218:221], v[10:13]
	v_mfma_f32_16x16x32_bf16 v[6:9], v[172:175], v[226:229], v[6:9]
	v_mfma_f32_16x16x32_bf16 v[2:5], v[180:183], v[226:229], v[2:5]
	v_mfma_f32_16x16x32_bf16 v[50:53], v[176:179], v[192:195], v[50:53]
	v_mfma_f32_16x16x32_bf16 v[42:45], v[184:187], v[192:195], v[42:45]
	v_mfma_f32_16x16x32_bf16 v[34:37], v[176:179], v[214:217], v[34:37]
	v_mfma_f32_16x16x32_bf16 v[26:29], v[184:187], v[214:217], v[26:29]
	v_mfma_f32_16x16x32_bf16 v[18:21], v[176:179], v[222:225], v[18:21]
	v_mfma_f32_16x16x32_bf16 v[10:13], v[184:187], v[222:225], v[10:13]
	v_mfma_f32_16x16x32_bf16 v[6:9], v[176:179], v[230:233], v[6:9]
	v_mfma_f32_16x16x32_bf16 v[2:5], v[184:187], v[230:233], v[2:5]
	s_setprio 0
	s_barrier
	s_add_i32 s49, s49, 2
	s_add_u32 s80, s80, 0x100
	s_addc_u32 s81, s81, 0
	s_add_u32 s37, s37, 0x100
	s_addc_u32 s43, s43, 0
	s_cmp_gt_u32 s49, 29
	s_cbranch_scc0 .LBB0_106

; __device__ __forceinline__ unsigned cvt_pk_bf16(float lo, float hi) { unsigned r; asm volatile("v_cvt_pk_bf16_f32 %0, %1, %2" : "=v"(r) : "v"(lo), "v"(hi)); return r; }
; #define PG8_BAR __builtin_amdgcn_s_barrier()
;     __device__ __forceinline__ void operator()(const f32x4 (&acc)[2][2][4][2], const Unit& u, int wr, int wc, int fr, int fq) const {
;         const int row0 = u.pm * BM + wr * 64 + fr, col0 = u.pn * BM + wc * 32 + 8 * fq;
; #pragma unroll
;         for (int ai = 0; ai < 2; ++ai)
; #pragma unroll
;             for (int m = 0; m < 4; ++m) { bf16_t* rowp = O + (size_t)(row0 + ai * HALF + m * 16) * ldc + col0;
; #pragma unroll
;                 for (int bj = 0; bj < 2; ++bj) { const f32x4 v0 = acc[ai][bj][m][0], v1 = acc[ai][bj][m][1];
;                     u32x4 w; w.x = cvt_pk_bf16(v0[0], v0[1]); w.y = cvt_pk_bf16(v0[2], v0[3]); w.z = cvt_pk_bf16(v1[0], v1[1]); w.w = cvt_pk_bf16(v1[2], v1[3]);
;                     *(u32x4*)(rowp + bj * HALF) = w; } }
; template <class Epi, class Sched = StaticOrder, bool ALIGN_EPI = true>
; __device__ __forceinline__ void gemm_phase(LAS unsigned char* lds, const Gemm g, const Sched& S, const Epi& E) {
;     ...
;         if constexpr (ALIGN_EPI) { if (wr == 0) PG8_BAR; }
;         E(acc, cur, wr, wc, fr, fq);
;         if (!has_next) break;
; #pragma unroll
;         for (int a = 0; a < 2; ++a)
; #pragma unroll
;             for (int b = 0; b < 2; ++b)
; #pragma unroll
;                 for (int m = 0; m < 4; ++m)
; #pragma unroll
;                     for (int n = 0; n < 2; ++n) acc[a][b][m][n] = (f32x4){0.f, 0.f, 0.f, 0.f};
;         cur = nxt; cA = nA; cB = nB; ++ui;
;         if constexpr (ALIGN_EPI) { if (wr == 1) PG8_BAR; }
.LBB0_109:
	v_lshl_add_u32 v148, s48, 8, v1
	v_lshl_or_b32 v142, s23, 8, v145
	v_ashrrev_i32_e32 v149, 31, v148
	v_readlane_b32 s80, v253, 58
	v_ashrrev_i32_e32 v143, 31, v142
	v_lshlrev_b64 v[150:151], 12, v[148:149]
	v_readlane_b32 s84, v253, 62
	v_readlane_b32 s85, v253, 63
	v_lshlrev_b64 v[152:153], 1, v[142:143]
	v_cvt_pk_bf16_f32 v126, v126, v127
	v_cvt_pk_bf16_f32 v127, v128, v129
	v_cvt_pk_bf16_f32 v128, v122, v123
	v_cvt_pk_bf16_f32 v129, v124, v125
	s_nop 0
	v_lshl_add_u64 v[150:151], s[84:85], 0, v[150:151]
	v_lshl_add_u64 v[142:143], v[150:151], 0, v[152:153]
	global_store_dwordx4 v[142:143], v[126:129], off
	v_cvt_pk_bf16_f32 v114, v114, v115
	v_cvt_pk_bf16_f32 v115, v116, v117
	v_cvt_pk_bf16_f32 v116, v106, v107
	v_or_b32_e32 v106, 16, v148
	v_ashrrev_i32_e32 v107, 31, v106
	v_lshlrev_b64 v[106:107], 12, v[106:107]
	v_lshl_add_u64 v[106:107], s[84:85], 0, v[106:107]
	v_cvt_pk_bf16_f32 v117, v108, v109
	global_store_dwordx4 v[142:143], v[114:117], off offset:256
	s_mov_b64 s[16:17], 0x80000
	s_mov_b64 s[30:31], -1
	v_lshl_add_u64 v[114:115], v[106:107], 0, v[152:153]
	v_cvt_pk_bf16_f32 v106, v118, v119
	v_cvt_pk_bf16_f32 v107, v120, v121
	v_cvt_pk_bf16_f32 v108, v110, v111
	v_cvt_pk_bf16_f32 v109, v112, v113
	global_store_dwordx4 v[114:115], v[106:109], off
	v_cvt_pk_bf16_f32 v98, v98, v99
	v_cvt_pk_bf16_f32 v99, v100, v101
	v_cvt_pk_bf16_f32 v100, v90, v91
	v_or_b32_e32 v90, 32, v148
	v_ashrrev_i32_e32 v91, 31, v90
	v_lshlrev_b64 v[90:91], 12, v[90:91]
	v_lshl_add_u64 v[90:91], s[84:85], 0, v[90:91]
	v_cvt_pk_bf16_f32 v101, v92, v93
	global_store_dwordx4 v[114:115], v[98:101], off offset:256
	s_cmp_eq_u64 s[12:13], 0
	s_cbranch_scc1 .Lmy_al_106
	s_barrier
.Lmy_al_106:
	v_readlane_b32 s33, v254, 40
	v_readlane_b32 s77, v254, 46
	v_lshl_add_u64 v[98:99], v[90:91], 0, v[152:153]
	v_cvt_pk_bf16_f32 v90, v102, v103
	v_cvt_pk_bf16_f32 v91, v104, v105
	v_cvt_pk_bf16_f32 v92, v94, v95
	v_cvt_pk_bf16_f32 v93, v96, v97
	global_store_dwordx4 v[98:99], v[90:93], off
	v_cvt_pk_bf16_f32 v86, v86, v87
	v_cvt_pk_bf16_f32 v87, v88, v89
	v_cvt_pk_bf16_f32 v88, v78, v79
	v_or_b32_e32 v78, 48, v148
	v_ashrrev_i32_e32 v79, 31, v78
	v_lshlrev_b64 v[78:79], 12, v[78:79]
	v_lshl_add_u64 v[78:79], s[84:85], 0, v[78:79]
	v_cvt_pk_bf16_f32 v89, v80, v81
	global_store_dwordx4 v[98:99], v[86:89], off offset:256
	s_mov_b32 s70, 0x3a000000
	v_readlane_b32 s81, v253, 59
	v_lshl_add_u64 v[86:87], v[78:79], 0, v[152:153]
	v_cvt_pk_bf16_f32 v78, v82, v83
	v_cvt_pk_bf16_f32 v79, v84, v85
	v_cvt_pk_bf16_f32 v80, v74, v75
	v_cvt_pk_bf16_f32 v81, v76, v77
	global_store_dwordx4 v[86:87], v[78:81], off
	v_cvt_pk_bf16_f32 v70, v70, v71
	v_cvt_pk_bf16_f32 v71, v72, v73
	v_cvt_pk_bf16_f32 v72, v66, v67
	v_lshl_add_u64 v[66:67], v[142:143], 0, s[16:17]
	s_mov_b32 s16, 0x80000
	v_cvt_pk_bf16_f32 v73, v68, v69
	global_store_dwordx4 v[86:87], v[70:73], off offset:256
	v_cvt_pk_bf16_f32 v62, v62, v63
	v_cvt_pk_bf16_f32 v63, v64, v65
	v_cvt_pk_bf16_f32 v64, v58, v59
	v_add_co_u32_e32 v58, vcc, s16, v142
	v_cvt_pk_bf16_f32 v65, v60, v61
	s_mov_b64 s[16:17], 0x90000
	s_nop 0
	v_addc_co_u32_e32 v59, vcc, 0, v143, vcc
	global_store_dwordx4 v[58:59], v[62:65], off
	v_cvt_pk_bf16_f32 v50, v50, v51
	v_cvt_pk_bf16_f32 v51, v52, v53
	v_cvt_pk_bf16_f32 v52, v42, v43
	v_cvt_pk_bf16_f32 v53, v44, v45
	global_store_dwordx4 v[66:67], v[50:53], off offset:256
	v_cvt_pk_bf16_f32 v42, v54, v55
	v_cvt_pk_bf16_f32 v43, v56, v57
	v_cvt_pk_bf16_f32 v44, v46, v47
	v_cvt_pk_bf16_f32 v45, v48, v49
	v_readlane_b32 s82, v253, 60
	s_nop 0
	v_lshl_add_u64 v[50:51], v[142:143], 0, s[16:17]
	s_mov_b32 s16, 0x90000
	v_add_co_u32_e32 v46, vcc, s16, v142
	s_mov_b64 s[16:17], 0xa0000
	s_nop 0
	v_addc_co_u32_e32 v47, vcc, 0, v143, vcc
	global_store_dwordx4 v[46:47], v[42:45], off
	v_cvt_pk_bf16_f32 v34, v34, v35
	v_cvt_pk_bf16_f32 v35, v36, v37
	v_cvt_pk_bf16_f32 v36, v26, v27
	v_cvt_pk_bf16_f32 v37, v28, v29
	global_store_dwordx4 v[50:51], v[34:37], off offset:256
	v_cvt_pk_bf16_f32 v26, v38, v39
	v_cvt_pk_bf16_f32 v27, v40, v41
	v_cvt_pk_bf16_f32 v28, v30, v31
	v_cvt_pk_bf16_f32 v29, v32, v33
	v_readlane_b32 s83, v253, 61
	s_nop 0
	v_lshl_add_u64 v[34:35], v[142:143], 0, s[16:17]
	s_mov_b32 s16, 0xa0000
	v_add_co_u32_e32 v30, vcc, s16, v142
	s_mov_b64 s[16:17], 0xb0000
	s_nop 0
	v_addc_co_u32_e32 v31, vcc, 0, v143, vcc
	global_store_dwordx4 v[30:31], v[26:29], off
	v_cvt_pk_bf16_f32 v18, v18, v19
	v_cvt_pk_bf16_f32 v19, v20, v21
	v_cvt_pk_bf16_f32 v20, v10, v11
	v_cvt_pk_bf16_f32 v21, v12, v13
	global_store_dwordx4 v[34:35], v[18:21], off offset:256
	v_cvt_pk_bf16_f32 v10, v22, v23
	v_cvt_pk_bf16_f32 v11, v24, v25
	v_cvt_pk_bf16_f32 v12, v14, v15
	v_readlane_b32 s86, v254, 0
	v_readlane_b32 s87, v254, 1
	v_lshl_add_u64 v[18:19], v[142:143], 0, s[16:17]
	s_mov_b32 s16, 0xb0000
	v_add_co_u32_e32 v14, vcc, s16, v142
	v_readlane_b32 s16, v254, 43
	s_nop 0
	v_addc_co_u32_e32 v15, vcc, 0, v143, vcc
	s_andn2_b64 vcc, exec, s[40:41]
	v_readlane_b32 s17, v254, 44
	v_cvt_pk_bf16_f32 v13, v16, v17
	global_store_dwordx4 v[14:15], v[10:13], off
	v_cvt_pk_bf16_f32 v6, v6, v7
	v_cvt_pk_bf16_f32 v7, v8, v9
	v_cvt_pk_bf16_f32 v8, v2, v3
	v_cvt_pk_bf16_f32 v9, v4, v5
	global_store_dwordx4 v[18:19], v[6:9], off offset:256
	s_cbranch_vccnz .LBB0_102
	s_branch .LBB0_101

;     __device__ bool next(int i, Unit& u) const { const int idx = i * G + c; if (idx >= 64) return false; u.kp = idx & 3; u.pn = (idx >> 2) & 7; u.pm = 192 + (idx >> 5); return true; }
; #define PG8_STAGE(bufoff, gbase, voff) do { _Pragma("unroll") for (int _i = 0; _i < 2; ++_i) \
;         __builtin_amdgcn_global_load_lds((const unsigned*)((const char*)(gbase) + (voff)[_i]), (LAS unsigned*)(lds + (bufoff) + ldsw + _i * 8192), 16, 0, 0); } while (0)
; #define PG8_LDA(dst, b, h) do { _Pragma("unroll") for (int m = 0; m < 4; ++m) _Pragma("unroll") for (int k = 0; k < 2; ++k) dst[m][k] = *(const LAS bf16x8*)(lds + PG8_SA(b, h) + aoff + m * 2048 + k * 1024); } while (0)
; #define PG8_LDB(dst, b, h) do { _Pragma("unroll") for (int n = 0; n < 2; ++n) _Pragma("unroll") for (int k = 0; k < 2; ++k) dst[n][k] = *(const LAS bf16x8*)(lds + PG8_SB(b, h) + boff + n * 2048 + k * 1024); } while (0)
; #define PG8_BAR __builtin_amdgcn_s_barrier()
; template <class Epi, class Sched = StaticOrder, bool ALIGN_EPI = true>
; __device__ __forceinline__ void gemm_phase(LAS unsigned char* lds, const Gemm g, const Sched& S, const Epi& E) {
;     ...
;         const bool has_next = S.next(ui + 1, nxt);
;         const char* nA = has_next ? (const char*)g.A + (size_t)nxt.pm * tstep + (size_t)nxt.kp * K * 2 : cA; const char* nB = has_next ? (const char*)g.Bt + (size_t)nxt.pn * tstep + (size_t)nxt.kp * K * 2 : cB;
;         for (int t = 0; t < nt; t += 2) {
;             const bool last = (t == nt - 2);
;             const char* a1 = cA + (size_t)(t + 1) * kstep;
;             const char* a2 = last ? nA : cA + (size_t)(t + 2) * kstep; const char* b2 = last ? nB : cB + (size_t)(t + 2) * kstep;
;             const char* a3 = a2 + kstep; const char* b3 = b2 + kstep;
;             PG8_LDB(B0, 0, 0); PG8_LDB(B1, 0, 1); PG8_SCHED; PG8_LDA(At, 0, 0); PG8_STAGE(PG8_SA(1, 1), a1 + hstep, voffA);
;             PG8_WAIT_V(8); PG8_WAIT_L(0); PG8_BAR; PG8_MMA(0, 0, At, B0); PG8_MMA(0, 1, At, B1); PG8_BAR; PG8_SCHED;
;             PG8_LDA(At, 0, 1); PG8_STAGE(PG8_SB(0, 0), b2, voffB); PG8_STAGE(PG8_SB(0, 1), b2 + hstep, voffB); PG8_STAGE(PG8_SA(0, 0), a2, voffA);
;             PG8_WAIT_V(8); PG8_WAIT_L(0); PG8_BAR; PG8_MMA(1, 0, At, B0); PG8_MMA(1, 1, At, B1); PG8_BAR; PG8_SCHED;
;     ...
;         cur = nxt; cA = nA; cB = nB; ++ui;
;         if constexpr (ALIGN_EPI) { if (wr == 1) PG8_BAR; }
.LBB0_335:
	s_ashr_i32 s43, s42, 31
	s_lshl_b64 s[16:17], s[42:43], 20
	v_readlane_b32 s30, v252, 0
	v_readlane_b32 s31, v252, 1
	s_add_u32 s44, s30, s16
	s_addc_u32 s45, s31, s17
	s_and_b64 s[16:17], s[40:41], exec
	s_cselect_b32 s36, s45, s1
	s_cselect_b32 s37, s44, s0
	s_ashr_i32 s21, s20, 31
	s_lshl_b64 s[16:17], s[20:21], 20
	v_readlane_b32 s21, v253, 35
	s_add_u32 s46, s21, s16
	v_readlane_b32 s16, v253, 36
	s_addc_u32 s47, s16, s17
	s_and_b64 s[16:17], s[40:41], exec
	s_cselect_b32 s21, s47, s93
	s_cselect_b32 s43, s46, s92
	s_add_u32 s80, s0, 0x80080
	s_addc_u32 s81, s1, 0
	s_add_u32 s49, s92, 0x100
	s_addc_u32 s70, s93, 0
	s_mov_b32 s79, -2
	s_cmp_eq_u32 s22, 1
	s_cbranch_scc1 .Lmy_nb_336
	s_cmp_eq_u64 s[2:3], 0
	s_cbranch_scc1 .Lmy_nb_336
	s_barrier
.Lmy_nb_336:
	s_add_u32 s0, s80, 0xfff80080
	s_addc_u32 s1, s81, -1
	s_add_i32 s16, 0, 0x10000
	s_cmp_eq_u32 s79, 28
	s_cselect_b32 s31, s36, s1
	s_cselect_b32 s30, s37, s0
	v_add_u32_e32 v142, s16, v144
	s_cselect_b32 s1, s21, s70
	s_cselect_b32 s0, s43, s49
	s_add_i32 s33, 0, 0x14000
	ds_read_b128 v[148:151], v142
	ds_read_b128 v[160:163], v142 offset:1024
	ds_read_b128 v[164:167], v142 offset:2048
	ds_read_b128 v[168:171], v142 offset:3072
	v_add_u32_e32 v142, s33, v144
	ds_read_b128 v[172:175], v142
	ds_read_b128 v[176:179], v142 offset:1024
	ds_read_b128 v[180:183], v142 offset:2048
	ds_read_b128 v[184:187], v142 offset:3072
	v_lshl_add_u64 v[142:143], s[80:81], 0, v[138:139]
	s_add_i32 m0, s7, 0xc000
	ds_read_b128 v[188:191], v146
	ds_read_b128 v[192:195], v146 offset:1024
	ds_read_b128 v[210:213], v146 offset:2048
	ds_read_b128 v[214:217], v146 offset:3072
	ds_read_b128 v[218:221], v146 offset:4096
	ds_read_b128 v[222:225], v146 offset:5120
	ds_read_b128 v[226:229], v146 offset:6144
	ds_read_b128 v[230:233], v146 offset:7168
	global_load_lds_dwordx4 v[142:143], off
	v_lshl_add_u64 v[142:143], s[80:81], 0, v[140:141]
	s_add_i32 m0, s7, 0xe000
	s_nop 0
	global_load_lds_dwordx4 v[142:143], off
	s_waitcnt vmcnt(8)
	s_waitcnt lgkmcnt(0)
	s_barrier
	s_setprio 1
	s_waitcnt lgkmcnt(0)
	v_mfma_f32_16x16x32_bf16 v[126:129], v[148:151], v[188:191], 0
	v_mfma_f32_16x16x32_bf16 v[122:125], v[164:167], v[188:191], 0
	v_mfma_f32_16x16x32_bf16 v[118:121], v[148:151], v[210:213], 0
	v_mfma_f32_16x16x32_bf16 v[110:113], v[164:167], v[210:213], 0
	v_mfma_f32_16x16x32_bf16 v[102:105], v[148:151], v[218:221], 0
	v_mfma_f32_16x16x32_bf16 v[94:97], v[164:167], v[218:221], 0
	v_mfma_f32_16x16x32_bf16 v[86:89], v[148:151], v[226:229], 0
	v_mfma_f32_16x16x32_bf16 v[78:81], v[164:167], v[226:229], 0
	v_mfma_f32_16x16x32_bf16 v[126:129], v[160:163], v[192:195], v[126:129]
	v_mfma_f32_16x16x32_bf16 v[122:125], v[168:171], v[192:195], v[122:125]
	v_mfma_f32_16x16x32_bf16 v[118:121], v[160:163], v[214:217], v[118:121]
	v_mfma_f32_16x16x32_bf16 v[110:113], v[168:171], v[214:217], v[110:113]
	v_mfma_f32_16x16x32_bf16 v[102:105], v[160:163], v[222:225], v[102:105]
	v_mfma_f32_16x16x32_bf16 v[94:97], v[168:171], v[222:225], v[94:97]
	v_mfma_f32_16x16x32_bf16 v[86:89], v[160:163], v[230:233], v[86:89]
	v_mfma_f32_16x16x32_bf16 v[78:81], v[168:171], v[230:233], v[78:81]
	s_setprio 0
	s_setprio 1
	v_mfma_f32_16x16x32_bf16 v[114:117], v[172:175], v[188:191], 0
	v_mfma_f32_16x16x32_bf16 v[106:109], v[180:183], v[188:191], 0
	v_mfma_f32_16x16x32_bf16 v[98:101], v[172:175], v[210:213], 0
	v_mfma_f32_16x16x32_bf16 v[90:93], v[180:183], v[210:213], 0
	v_mfma_f32_16x16x32_bf16 v[82:85], v[172:175], v[218:221], 0
	v_mfma_f32_16x16x32_bf16 v[74:77], v[180:183], v[218:221], 0
	v_mfma_f32_16x16x32_bf16 v[70:73], v[172:175], v[226:229], 0
	v_mfma_f32_16x16x32_bf16 v[66:69], v[180:183], v[226:229], 0
	v_mfma_f32_16x16x32_bf16 v[114:117], v[176:179], v[192:195], v[114:117]
	v_mfma_f32_16x16x32_bf16 v[106:109], v[184:187], v[192:195], v[106:109]
	v_mfma_f32_16x16x32_bf16 v[98:101], v[176:179], v[214:217], v[98:101]
	v_mfma_f32_16x16x32_bf16 v[90:93], v[184:187], v[214:217], v[90:93]
	v_mfma_f32_16x16x32_bf16 v[82:85], v[176:179], v[222:225], v[82:85]
	v_mfma_f32_16x16x32_bf16 v[74:77], v[184:187], v[222:225], v[74:77]
	v_mfma_f32_16x16x32_bf16 v[70:73], v[176:179], v[230:233], v[70:73]
	v_mfma_f32_16x16x32_bf16 v[66:69], v[184:187], v[230:233], v[66:69]
	s_setprio 0
	s_barrier
	s_add_i32 s16, s16, s5
	v_lshl_add_u64 v[142:143], s[0:1], 0, v[134:135]
	s_mov_b32 m0, s16
	ds_read_b128 v[188:191], v146 offset:16384
	ds_read_b128 v[192:195], v146 offset:17408
	ds_read_b128 v[210:213], v146 offset:18432
	ds_read_b128 v[214:217], v146 offset:19456
	ds_read_b128 v[218:221], v146 offset:20480
	ds_read_b128 v[222:225], v146 offset:21504
	ds_read_b128 v[226:229], v146 offset:22528
	ds_read_b128 v[230:233], v146 offset:23552
	global_load_lds_dwordx4 v[142:143], off
	s_add_i32 m0, s16, 0x2000
	s_add_u32 s16, s0, 0x80000
	v_lshl_add_u64 v[152:153], s[0:1], 0, v[130:131]
	s_addc_u32 s17, s1, 0
	s_add_i32 s33, s33, s5
	global_load_lds_dwordx4 v[152:153], off
	v_lshl_add_u64 v[196:197], s[16:17], 0, v[134:135]
	s_mov_b32 m0, s33
	v_lshl_add_u64 v[234:235], s[30:31], 0, v[132:133]
	global_load_lds_dwordx4 v[196:197], off
	v_lshl_add_u64 v[196:197], s[16:17], 0, v[130:131]
	s_add_i32 m0, s33, 0x2000
	s_nop 0
	global_load_lds_dwordx4 v[196:197], off
	v_lshl_add_u64 v[196:197], s[30:31], 0, v[136:137]
	s_mov_b32 m0, s7
	s_nop 0
	global_load_lds_dwordx4 v[196:197], off
	s_mov_b32 m0, s8
	s_nop 0
	global_load_lds_dwordx4 v[234:235], off
	s_waitcnt vmcnt(8)
	s_waitcnt lgkmcnt(0)
	s_barrier
; #define PG8_STAGE(bufoff, gbase, voff) do { _Pragma("unroll") for (int _i = 0; _i < 2; ++_i) \
;         __builtin_amdgcn_global_load_lds((const unsigned*)((const char*)(gbase) + (voff)[_i]), (LAS unsigned*)(lds + (bufoff) + ldsw + _i * 8192), 16, 0, 0); } while (0)
; #define PG8_LDA(dst, b, h) do { _Pragma("unroll") for (int m = 0; m < 4; ++m) _Pragma("unroll") for (int k = 0; k < 2; ++k) dst[m][k] = *(const LAS bf16x8*)(lds + PG8_SA(b, h) + aoff + m * 2048 + k * 1024); } while (0)
; #define PG8_LDB(dst, b, h) do { _Pragma("unroll") for (int n = 0; n < 2; ++n) _Pragma("unroll") for (int k = 0; k < 2; ++k) dst[n][k] = *(const LAS bf16x8*)(lds + PG8_SB(b, h) + boff + n * 2048 + k * 1024); } while (0)
; #define PG8_MMA(ai, bj, At, Bt) do { __builtin_amdgcn_s_setprio(1); _Pragma("unroll") for (int m = 0; m < 4; ++m) _Pragma("unroll") for (int n = 0; n < 2; ++n) _Pragma("unroll") for (int k = 0; k < 2; ++k) \
;         acc[ai][bj][m][n] = __builtin_amdgcn_mfma_f32_16x16x32_bf16(Bt[n][k], At[m][k], acc[ai][bj][m][n], 0, 0, 0); __builtin_amdgcn_s_setprio(0); } while (0)
; #define PG8_WAIT_V(n) asm volatile("s_waitcnt vmcnt(" #n ")" ::: "memory")
; #define PG8_WAIT_L(n) asm volatile("s_waitcnt lgkmcnt(" #n ")" ::: "memory")
; #define PG8_BAR __builtin_amdgcn_s_barrier()
; #define PG8_SCHED __builtin_amdgcn_sched_barrier(0)
; template <class Epi, class Sched = StaticOrder, bool ALIGN_EPI = true>
; __device__ __forceinline__ void gemm_phase(LAS unsigned char* lds, const Gemm g, const Sched& S, const Epi& E) {
;     ...
;             PG8_LDA(At, 0, 1); PG8_STAGE(PG8_SB(0, 0), b2, voffB); PG8_STAGE(PG8_SB(0, 1), b2 + hstep, voffB); PG8_STAGE(PG8_SA(0, 0), a2, voffA);
;             PG8_WAIT_V(8); PG8_WAIT_L(0); PG8_BAR; PG8_MMA(1, 0, At, B0); PG8_MMA(1, 1, At, B1); PG8_BAR; PG8_SCHED;
;             PG8_LDB(B0, 1, 0); PG8_LDB(B1, 1, 1); PG8_SCHED; PG8_LDA(At, 1, 0); PG8_STAGE(PG8_SA(0, 1), a2 + hstep, voffA);
;             PG8_WAIT_V(8); PG8_WAIT_L(0); PG8_BAR; PG8_MMA(0, 0, At, B0); PG8_MMA(0, 1, At, B1); PG8_BAR; PG8_SCHED;
	s_setprio 1
	s_waitcnt lgkmcnt(0)
	v_mfma_f32_16x16x32_bf16 v[62:65], v[148:151], v[188:191], 0
	v_mfma_f32_16x16x32_bf16 v[58:61], v[164:167], v[188:191], 0
	v_mfma_f32_16x16x32_bf16 v[54:57], v[148:151], v[210:213], 0
	v_mfma_f32_16x16x32_bf16 v[46:49], v[164:167], v[210:213], 0
	v_mfma_f32_16x16x32_bf16 v[38:41], v[148:151], v[218:221], 0
	v_mfma_f32_16x16x32_bf16 v[30:33], v[164:167], v[218:221], 0
	v_mfma_f32_16x16x32_bf16 v[22:25], v[148:151], v[226:229], 0
	v_mfma_f32_16x16x32_bf16 v[14:17], v[164:167], v[226:229], 0
	v_mfma_f32_16x16x32_bf16 v[62:65], v[160:163], v[192:195], v[62:65]
	v_mfma_f32_16x16x32_bf16 v[58:61], v[168:171], v[192:195], v[58:61]
	v_mfma_f32_16x16x32_bf16 v[54:57], v[160:163], v[214:217], v[54:57]
	v_mfma_f32_16x16x32_bf16 v[46:49], v[168:171], v[214:217], v[46:49]
	v_mfma_f32_16x16x32_bf16 v[38:41], v[160:163], v[222:225], v[38:41]
	v_mfma_f32_16x16x32_bf16 v[30:33], v[168:171], v[222:225], v[30:33]
	v_mfma_f32_16x16x32_bf16 v[22:25], v[160:163], v[230:233], v[22:25]
	v_mfma_f32_16x16x32_bf16 v[14:17], v[168:171], v[230:233], v[14:17]
	s_setprio 0
	s_setprio 1
	v_mfma_f32_16x16x32_bf16 v[50:53], v[172:175], v[188:191], 0
	v_mfma_f32_16x16x32_bf16 v[42:45], v[180:183], v[188:191], 0
	v_mfma_f32_16x16x32_bf16 v[34:37], v[172:175], v[210:213], 0
	v_mfma_f32_16x16x32_bf16 v[26:29], v[180:183], v[210:213], 0
	v_mfma_f32_16x16x32_bf16 v[18:21], v[172:175], v[218:221], 0
	v_mfma_f32_16x16x32_bf16 v[10:13], v[180:183], v[218:221], 0
	v_mfma_f32_16x16x32_bf16 v[6:9], v[172:175], v[226:229], 0
	v_mfma_f32_16x16x32_bf16 v[2:5], v[180:183], v[226:229], 0
	v_mfma_f32_16x16x32_bf16 v[50:53], v[176:179], v[192:195], v[50:53]
	v_mfma_f32_16x16x32_bf16 v[42:45], v[184:187], v[192:195], v[42:45]
	v_mfma_f32_16x16x32_bf16 v[34:37], v[176:179], v[214:217], v[34:37]
	v_mfma_f32_16x16x32_bf16 v[26:29], v[184:187], v[214:217], v[26:29]
	v_mfma_f32_16x16x32_bf16 v[18:21], v[176:179], v[222:225], v[18:21]
	v_mfma_f32_16x16x32_bf16 v[10:13], v[184:187], v[222:225], v[10:13]
	v_mfma_f32_16x16x32_bf16 v[6:9], v[176:179], v[230:233], v[6:9]
	v_mfma_f32_16x16x32_bf16 v[2:5], v[184:187], v[230:233], v[2:5]
	s_setprio 0
	s_barrier
	s_add_i32 s33, 0, 0x18000
	v_add_u32_e32 v147, s33, v144
	s_add_i32 s82, 0, 0x1c000
	ds_read_b128 v[148:151], v147
	ds_read_b128 v[160:163], v147 offset:1024
	ds_read_b128 v[164:167], v147 offset:2048
	ds_read_b128 v[168:171], v147 offset:3072
	v_add_u32_e32 v147, s82, v144
	ds_read_b128 v[172:175], v147
	ds_read_b128 v[176:179], v147 offset:1024
	ds_read_b128 v[180:183], v147 offset:2048
	ds_read_b128 v[184:187], v147 offset:3072
	s_add_u32 s16, s30, 0x80000
	s_addc_u32 s17, s31, 0
	s_mov_b32 m0, s9
	v_lshl_add_u64 v[236:237], s[16:17], 0, v[136:137]
	ds_read_b128 v[188:191], v146 offset:32768
	ds_read_b128 v[192:195], v146 offset:33792
	ds_read_b128 v[210:213], v146 offset:34816
	ds_read_b128 v[214:217], v146 offset:35840
	ds_read_b128 v[218:221], v146 offset:36864
	ds_read_b128 v[222:225], v146 offset:37888
	ds_read_b128 v[226:229], v146 offset:38912
	ds_read_b128 v[230:233], v146 offset:39936
	global_load_lds_dwordx4 v[236:237], off
	v_lshl_add_u64 v[236:237], s[16:17], 0, v[132:133]
	s_mov_b32 m0, s10
	s_nop 0
	global_load_lds_dwordx4 v[236:237], off
	s_waitcnt vmcnt(8)
	s_waitcnt lgkmcnt(0)
	s_barrier
	s_setprio 1
	s_waitcnt lgkmcnt(0)
	v_mfma_f32_16x16x32_bf16 v[126:129], v[148:151], v[188:191], v[126:129]
	v_mfma_f32_16x16x32_bf16 v[122:125], v[164:167], v[188:191], v[122:125]
	v_mfma_f32_16x16x32_bf16 v[118:121], v[148:151], v[210:213], v[118:121]
	v_mfma_f32_16x16x32_bf16 v[110:113], v[164:167], v[210:213], v[110:113]
	v_mfma_f32_16x16x32_bf16 v[102:105], v[148:151], v[218:221], v[102:105]
	v_mfma_f32_16x16x32_bf16 v[94:97], v[164:167], v[218:221], v[94:97]
	v_mfma_f32_16x16x32_bf16 v[86:89], v[148:151], v[226:229], v[86:89]
	v_mfma_f32_16x16x32_bf16 v[78:81], v[164:167], v[226:229], v[78:81]
	v_mfma_f32_16x16x32_bf16 v[126:129], v[160:163], v[192:195], v[126:129]
	v_mfma_f32_16x16x32_bf16 v[122:125], v[168:171], v[192:195], v[122:125]
	v_mfma_f32_16x16x32_bf16 v[118:121], v[160:163], v[214:217], v[118:121]
	v_mfma_f32_16x16x32_bf16 v[110:113], v[168:171], v[214:217], v[110:113]
	v_mfma_f32_16x16x32_bf16 v[102:105], v[160:163], v[222:225], v[102:105]
	v_mfma_f32_16x16x32_bf16 v[94:97], v[168:171], v[222:225], v[94:97]
	v_mfma_f32_16x16x32_bf16 v[86:89], v[160:163], v[230:233], v[86:89]
	v_mfma_f32_16x16x32_bf16 v[78:81], v[168:171], v[230:233], v[78:81]
	s_setprio 0
	s_setprio 1
	v_mfma_f32_16x16x32_bf16 v[114:117], v[172:175], v[188:191], v[114:117]
	v_mfma_f32_16x16x32_bf16 v[106:109], v[180:183], v[188:191], v[106:109]
	v_mfma_f32_16x16x32_bf16 v[98:101], v[172:175], v[210:213], v[98:101]
	v_mfma_f32_16x16x32_bf16 v[90:93], v[180:183], v[210:213], v[90:93]
	v_mfma_f32_16x16x32_bf16 v[82:85], v[172:175], v[218:221], v[82:85]
	v_mfma_f32_16x16x32_bf16 v[74:77], v[180:183], v[218:221], v[74:77]
	v_mfma_f32_16x16x32_bf16 v[70:73], v[172:175], v[226:229], v[70:73]
	v_mfma_f32_16x16x32_bf16 v[66:69], v[180:183], v[226:229], v[66:69]
	v_mfma_f32_16x16x32_bf16 v[114:117], v[176:179], v[192:195], v[114:117]
	v_mfma_f32_16x16x32_bf16 v[106:109], v[184:187], v[192:195], v[106:109]
	v_mfma_f32_16x16x32_bf16 v[98:101], v[176:179], v[214:217], v[98:101]
	v_mfma_f32_16x16x32_bf16 v[90:93], v[184:187], v[214:217], v[90:93]
	v_mfma_f32_16x16x32_bf16 v[82:85], v[176:179], v[222:225], v[82:85]
	v_mfma_f32_16x16x32_bf16 v[74:77], v[184:187], v[222:225], v[74:77]
	v_mfma_f32_16x16x32_bf16 v[70:73], v[176:179], v[230:233], v[70:73]
	v_mfma_f32_16x16x32_bf16 v[66:69], v[184:187], v[230:233], v[66:69]
	s_setprio 0
	s_barrier
; #define PG8_STAGE(bufoff, gbase, voff) do { _Pragma("unroll") for (int _i = 0; _i < 2; ++_i) \
;         __builtin_amdgcn_global_load_lds((const unsigned*)((const char*)(gbase) + (voff)[_i]), (LAS unsigned*)(lds + (bufoff) + ldsw + _i * 8192), 16, 0, 0); } while (0)
; #define PG8_LDA(dst, b, h) do { _Pragma("unroll") for (int m = 0; m < 4; ++m) _Pragma("unroll") for (int k = 0; k < 2; ++k) dst[m][k] = *(const LAS bf16x8*)(lds + PG8_SA(b, h) + aoff + m * 2048 + k * 1024); } while (0)
; #define PG8_MMA(ai, bj, At, Bt) do { __builtin_amdgcn_s_setprio(1); _Pragma("unroll") for (int m = 0; m < 4; ++m) _Pragma("unroll") for (int n = 0; n < 2; ++n) _Pragma("unroll") for (int k = 0; k < 2; ++k) \
;         acc[ai][bj][m][n] = __builtin_amdgcn_mfma_f32_16x16x32_bf16(Bt[n][k], At[m][k], acc[ai][bj][m][n], 0, 0, 0); __builtin_amdgcn_s_setprio(0); } while (0)
; #define PG8_WAIT_V(n) asm volatile("s_waitcnt vmcnt(" #n ")" ::: "memory")
; #define PG8_WAIT_L(n) asm volatile("s_waitcnt lgkmcnt(" #n ")" ::: "memory")
; #define PG8_BAR __builtin_amdgcn_s_barrier()
; #define PG8_SCHED __builtin_amdgcn_sched_barrier(0)
; template <class Epi, class Sched = StaticOrder, bool ALIGN_EPI = true>
; __device__ __forceinline__ void gemm_phase(LAS unsigned char* lds, const Gemm g, const Sched& S, const Epi& E) {
;     ...
;             PG8_LDA(At, 1, 1); PG8_STAGE(PG8_SB(1, 0), b3, voffB); PG8_STAGE(PG8_SB(1, 1), b3 + hstep, voffB); PG8_STAGE(PG8_SA(1, 0), a3, voffA);
;             PG8_WAIT_V(8); PG8_WAIT_L(0); PG8_BAR; PG8_MMA(1, 0, At, B0); PG8_MMA(1, 1, At, B1); PG8_BAR; PG8_SCHED;
;         }
	s_add_i32 s16, s33, s5
	v_lshl_add_u64 v[142:143], v[142:143], 0, s[34:35]
	s_mov_b32 m0, s16
	ds_read_b128 v[188:191], v146 offset:49152
	ds_read_b128 v[192:195], v146 offset:50176
	ds_read_b128 v[210:213], v146 offset:51200
	ds_read_b128 v[214:217], v146 offset:52224
	ds_read_b128 v[218:221], v146 offset:53248
	ds_read_b128 v[222:225], v146 offset:54272
	ds_read_b128 v[226:229], v146 offset:55296
	ds_read_b128 v[230:233], v146 offset:56320
	global_load_lds_dwordx4 v[142:143], off
	s_add_i32 m0, s16, 0x2000
	s_add_u32 s0, s0, 0x80080
	v_lshl_add_u64 v[142:143], v[152:153], 0, s[34:35]
	s_addc_u32 s1, s1, 0
	s_add_i32 s16, s82, s5
	global_load_lds_dwordx4 v[142:143], off
	v_lshl_add_u64 v[142:143], s[0:1], 0, v[134:135]
	s_mov_b32 m0, s16
	s_nop 0
	global_load_lds_dwordx4 v[142:143], off
	v_lshl_add_u64 v[142:143], s[0:1], 0, v[130:131]
	s_add_i32 m0, s16, 0x2000
	s_nop 0
	global_load_lds_dwordx4 v[142:143], off
	v_lshl_add_u64 v[142:143], v[196:197], 0, s[34:35]
	s_mov_b32 m0, s11
	s_nop 0
	global_load_lds_dwordx4 v[142:143], off
	v_lshl_add_u64 v[142:143], v[234:235], 0, s[34:35]
	s_mov_b32 m0, s18
	s_nop 0
	global_load_lds_dwordx4 v[142:143], off
	s_waitcnt vmcnt(8)
	s_waitcnt lgkmcnt(0)
	s_barrier
	s_setprio 1
	s_waitcnt lgkmcnt(0)
	v_mfma_f32_16x16x32_bf16 v[62:65], v[148:151], v[188:191], v[62:65]
	v_mfma_f32_16x16x32_bf16 v[58:61], v[164:167], v[188:191], v[58:61]
	v_mfma_f32_16x16x32_bf16 v[54:57], v[148:151], v[210:213], v[54:57]
	v_mfma_f32_16x16x32_bf16 v[46:49], v[164:167], v[210:213], v[46:49]
	v_mfma_f32_16x16x32_bf16 v[38:41], v[148:151], v[218:221], v[38:41]
	v_mfma_f32_16x16x32_bf16 v[30:33], v[164:167], v[218:221], v[30:33]
	v_mfma_f32_16x16x32_bf16 v[22:25], v[148:151], v[226:229], v[22:25]
	v_mfma_f32_16x16x32_bf16 v[14:17], v[164:167], v[226:229], v[14:17]
	v_mfma_f32_16x16x32_bf16 v[62:65], v[160:163], v[192:195], v[62:65]
	v_mfma_f32_16x16x32_bf16 v[58:61], v[168:171], v[192:195], v[58:61]
	v_mfma_f32_16x16x32_bf16 v[54:57], v[160:163], v[214:217], v[54:57]
	v_mfma_f32_16x16x32_bf16 v[46:49], v[168:171], v[214:217], v[46:49]
	v_mfma_f32_16x16x32_bf16 v[38:41], v[160:163], v[222:225], v[38:41]
	v_mfma_f32_16x16x32_bf16 v[30:33], v[168:171], v[222:225], v[30:33]
	v_mfma_f32_16x16x32_bf16 v[22:25], v[160:163], v[230:233], v[22:25]
	v_mfma_f32_16x16x32_bf16 v[14:17], v[168:171], v[230:233], v[14:17]
	s_setprio 0
	s_setprio 1
	v_mfma_f32_16x16x32_bf16 v[50:53], v[172:175], v[188:191], v[50:53]
	v_mfma_f32_16x16x32_bf16 v[42:45], v[180:183], v[188:191], v[42:45]
	v_mfma_f32_16x16x32_bf16 v[34:37], v[172:175], v[210:213], v[34:37]
	v_mfma_f32_16x16x32_bf16 v[26:29], v[180:183], v[210:213], v[26:29]
	v_mfma_f32_16x16x32_bf16 v[18:21], v[172:175], v[218:221], v[18:21]
	v_mfma_f32_16x16x32_bf16 v[10:13], v[180:183], v[218:221], v[10:13]
	v_mfma_f32_16x16x32_bf16 v[6:9], v[172:175], v[226:229], v[6:9]
	v_mfma_f32_16x16x32_bf16 v[2:5], v[180:183], v[226:229], v[2:5]
	v_mfma_f32_16x16x32_bf16 v[50:53], v[176:179], v[192:195], v[50:53]
	v_mfma_f32_16x16x32_bf16 v[42:45], v[184:187], v[192:195], v[42:45]
	v_mfma_f32_16x16x32_bf16 v[34:37], v[176:179], v[214:217], v[34:37]
	v_mfma_f32_16x16x32_bf16 v[26:29], v[184:187], v[214:217], v[26:29]
	v_mfma_f32_16x16x32_bf16 v[18:21], v[176:179], v[222:225], v[18:21]
	v_mfma_f32_16x16x32_bf16 v[10:13], v[184:187], v[222:225], v[10:13]
	v_mfma_f32_16x16x32_bf16 v[6:9], v[176:179], v[230:233], v[6:9]
	v_mfma_f32_16x16x32_bf16 v[2:5], v[184:187], v[230:233], v[2:5]
	s_setprio 0
	s_barrier
	s_add_i32 s79, s79, 2
	s_add_u32 s80, s80, 0x100
	s_addc_u32 s81, s81, 0
	s_add_u32 s49, s49, 0x100
	s_addc_u32 s70, s70, 0
	s_cmp_gt_u32 s79, 29
	s_cbranch_scc0 .LBB0_336

; __device__ __forceinline__ unsigned cvt_pk_bf16(float lo, float hi) { unsigned r; asm volatile("v_cvt_pk_bf16_f32 %0, %1, %2" : "=v"(r) : "v"(lo), "v"(hi)); return r; }
; #define PG8_BAR __builtin_amdgcn_s_barrier()
;     __device__ __forceinline__ void operator()(const f32x4 (&acc)[2][2][4][2], const Unit& u, int wr, int wc, int fr, int fq) const {
;         const int row0 = u.pm * BM + wr * 64 + fr, col0 = u.pn * BM + wc * 32 + 8 * fq;
; #pragma unroll
;         for (int ai = 0; ai < 2; ++ai)
; #pragma unroll
;             for (int m = 0; m < 4; ++m) { bf16_t* rowp = O + (size_t)(row0 + ai * HALF + m * 16) * ldc + col0;
; #pragma unroll
;                 for (int bj = 0; bj < 2; ++bj) { const f32x4 v0 = acc[ai][bj][m][0], v1 = acc[ai][bj][m][1];
;                     u32x4 w; w.x = cvt_pk_bf16(v0[0], v0[1]); w.y = cvt_pk_bf16(v0[2], v0[3]); w.z = cvt_pk_bf16(v1[0], v1[1]); w.w = cvt_pk_bf16(v1[2], v1[3]);
;                     *(u32x4*)(rowp + bj * HALF) = w; } }
; template <class Epi, class Sched = StaticOrder, bool ALIGN_EPI = true>
; __device__ __forceinline__ void gemm_phase(LAS unsigned char* lds, const Gemm g, const Sched& S, const Epi& E) {
;     ...
;         if constexpr (ALIGN_EPI) { if (wr == 0) PG8_BAR; }
;         E(acc, cur, wr, wc, fr, fq);
;         if (!has_next) break;
; #pragma unroll
;         for (int a = 0; a < 2; ++a)
; #pragma unroll
;             for (int b = 0; b < 2; ++b)
; #pragma unroll
;                 for (int m = 0; m < 4; ++m)
; #pragma unroll
;                     for (int n = 0; n < 2; ++n) acc[a][b][m][n] = (f32x4){0.f, 0.f, 0.f, 0.f};
;         cur = nxt; cA = nA; cB = nB; ++ui;
;         if constexpr (ALIGN_EPI) { if (wr == 1) PG8_BAR; }
.LBB0_339:
	v_lshl_add_u32 v148, s48, 8, v1
	v_lshl_or_b32 v142, s23, 8, v145
	v_ashrrev_i32_e32 v149, 31, v148
	v_ashrrev_i32_e32 v143, 31, v142
	v_lshlrev_b64 v[150:151], 13, v[148:149]
	v_lshl_add_u64 v[150:151], s[94:95], 0, v[150:151]
	v_lshlrev_b64 v[152:153], 1, v[142:143]
	v_lshl_add_u64 v[142:143], v[150:151], 0, v[152:153]
	v_cvt_pk_bf16_f32 v126, v126, v127
	v_cvt_pk_bf16_f32 v127, v128, v129
	v_cvt_pk_bf16_f32 v128, v122, v123
	v_cvt_pk_bf16_f32 v129, v124, v125
	global_store_dwordx4 v[142:143], v[126:129], off
	v_cvt_pk_bf16_f32 v114, v114, v115
	v_cvt_pk_bf16_f32 v115, v116, v117
	v_cvt_pk_bf16_f32 v116, v106, v107
	v_or_b32_e32 v106, 16, v148
	v_ashrrev_i32_e32 v107, 31, v106
	v_lshlrev_b64 v[106:107], 13, v[106:107]
	v_lshl_add_u64 v[106:107], s[94:95], 0, v[106:107]
	v_cvt_pk_bf16_f32 v117, v108, v109
	global_store_dwordx4 v[142:143], v[114:117], off offset:256
	s_mov_b64 s[0:1], 0x100000
	v_readlane_b32 s82, v254, 41
	v_lshl_add_u64 v[114:115], v[106:107], 0, v[152:153]
	v_cvt_pk_bf16_f32 v106, v118, v119
	v_cvt_pk_bf16_f32 v107, v120, v121
	v_cvt_pk_bf16_f32 v108, v110, v111
	v_cvt_pk_bf16_f32 v109, v112, v113
	global_store_dwordx4 v[114:115], v[106:109], off
	v_cvt_pk_bf16_f32 v98, v98, v99
	v_cvt_pk_bf16_f32 v99, v100, v101
	v_cvt_pk_bf16_f32 v100, v90, v91
	v_or_b32_e32 v90, 32, v148
	v_ashrrev_i32_e32 v91, 31, v90
	v_lshlrev_b64 v[90:91], 13, v[90:91]
	v_lshl_add_u64 v[90:91], s[94:95], 0, v[90:91]
	v_cvt_pk_bf16_f32 v101, v92, v93
	global_store_dwordx4 v[114:115], v[98:101], off offset:256
	s_cmp_eq_u64 s[12:13], 0
	s_cbranch_scc1 .Lmy_al_336
	s_barrier
.Lmy_al_336:
	v_readlane_b32 s33, v254, 40
	s_mov_b32 s96, s82
	v_lshl_add_u64 v[98:99], v[90:91], 0, v[152:153]
	v_cvt_pk_bf16_f32 v90, v102, v103
	v_cvt_pk_bf16_f32 v91, v104, v105
	v_cvt_pk_bf16_f32 v92, v94, v95
	v_cvt_pk_bf16_f32 v93, v96, v97
	global_store_dwordx4 v[98:99], v[90:93], off
	v_cvt_pk_bf16_f32 v82, v82, v83
	v_cvt_pk_bf16_f32 v83, v84, v85
	v_cvt_pk_bf16_f32 v84, v74, v75
	v_or_b32_e32 v74, 48, v148
	v_ashrrev_i32_e32 v75, 31, v74
	v_lshlrev_b64 v[74:75], 13, v[74:75]
	v_lshl_add_u64 v[74:75], s[94:95], 0, v[74:75]
	v_cvt_pk_bf16_f32 v85, v76, v77
	global_store_dwordx4 v[98:99], v[82:85], off offset:256
	v_readlane_b32 s77, v254, 46
	s_movk_i32 s79, 0x4000
	v_lshl_add_u64 v[82:83], v[74:75], 0, v[152:153]
	v_cvt_pk_bf16_f32 v74, v86, v87
	v_cvt_pk_bf16_f32 v75, v88, v89
	v_cvt_pk_bf16_f32 v76, v78, v79
	v_cvt_pk_bf16_f32 v77, v80, v81
	global_store_dwordx4 v[82:83], v[74:77], off
	v_cvt_pk_bf16_f32 v70, v70, v71
	v_cvt_pk_bf16_f32 v71, v72, v73
	v_cvt_pk_bf16_f32 v72, v66, v67
	v_lshl_add_u64 v[66:67], v[142:143], 0, s[0:1]
	s_mov_b32 s0, 0x100000
	v_cvt_pk_bf16_f32 v73, v68, v69
	global_store_dwordx4 v[82:83], v[70:73], off offset:256
	v_cvt_pk_bf16_f32 v62, v62, v63
	v_cvt_pk_bf16_f32 v63, v64, v65
	v_cvt_pk_bf16_f32 v64, v58, v59
	v_add_co_u32_e32 v58, vcc, s0, v142
	v_cvt_pk_bf16_f32 v65, v60, v61
	s_mov_b64 s[0:1], 0x120000
	s_nop 0
	v_addc_co_u32_e32 v59, vcc, 0, v143, vcc
	global_store_dwordx4 v[58:59], v[62:65], off
	v_cvt_pk_bf16_f32 v50, v50, v51
	v_cvt_pk_bf16_f32 v51, v52, v53
	v_cvt_pk_bf16_f32 v52, v42, v43
	v_cvt_pk_bf16_f32 v53, v44, v45
	global_store_dwordx4 v[66:67], v[50:53], off offset:256
	v_cvt_pk_bf16_f32 v42, v54, v55
	v_cvt_pk_bf16_f32 v43, v56, v57
	v_cvt_pk_bf16_f32 v44, v46, v47
	v_cvt_pk_bf16_f32 v45, v48, v49
	s_mov_b32 s70, 0x3a000000
	s_nop 0
	v_lshl_add_u64 v[50:51], v[142:143], 0, s[0:1]
	s_mov_b32 s0, 0x120000
	v_add_co_u32_e32 v46, vcc, s0, v142
	s_mov_b64 s[0:1], 0x140000
	s_nop 0
	v_addc_co_u32_e32 v47, vcc, 0, v143, vcc
	global_store_dwordx4 v[46:47], v[42:45], off
	v_cvt_pk_bf16_f32 v34, v34, v35
	v_cvt_pk_bf16_f32 v35, v36, v37
	v_cvt_pk_bf16_f32 v36, v26, v27
	v_cvt_pk_bf16_f32 v37, v28, v29
	global_store_dwordx4 v[50:51], v[34:37], off offset:256
	v_cvt_pk_bf16_f32 v26, v38, v39
	v_cvt_pk_bf16_f32 v27, v40, v41
	v_cvt_pk_bf16_f32 v28, v30, v31
	v_cvt_pk_bf16_f32 v29, v32, v33
	v_readlane_b32 s83, v254, 42
	s_nop 0
	v_lshl_add_u64 v[34:35], v[142:143], 0, s[0:1]
	s_mov_b32 s0, 0x140000
	v_add_co_u32_e32 v30, vcc, s0, v142
	s_mov_b64 s[0:1], 0x160000
	s_nop 0
	v_addc_co_u32_e32 v31, vcc, 0, v143, vcc
	global_store_dwordx4 v[30:31], v[26:29], off
	v_cvt_pk_bf16_f32 v18, v18, v19
	v_cvt_pk_bf16_f32 v19, v20, v21
	v_cvt_pk_bf16_f32 v20, v10, v11
	v_cvt_pk_bf16_f32 v21, v12, v13
	global_store_dwordx4 v[34:35], v[18:21], off offset:256
	v_cvt_pk_bf16_f32 v10, v22, v23
	v_cvt_pk_bf16_f32 v11, v24, v25
	v_cvt_pk_bf16_f32 v12, v14, v15
	v_cvt_pk_bf16_f32 v13, v16, v17
	s_nop 1
	v_lshl_add_u64 v[18:19], v[142:143], 0, s[0:1]
	s_mov_b32 s0, 0x160000
	v_add_co_u32_e32 v14, vcc, s0, v142
	s_mov_b64 s[0:1], -1
	s_nop 0
	v_addc_co_u32_e32 v15, vcc, 0, v143, vcc
	s_andn2_b64 vcc, exec, s[40:41]
	global_store_dwordx4 v[14:15], v[10:13], off
	v_cvt_pk_bf16_f32 v6, v6, v7
	v_cvt_pk_bf16_f32 v7, v8, v9
	v_cvt_pk_bf16_f32 v8, v2, v3
	v_cvt_pk_bf16_f32 v9, v4, v5
	global_store_dwordx4 v[18:19], v[6:9], off offset:256
	s_cbranch_vccnz .LBB0_332
	s_branch .LBB0_331

; #define LAS __attribute__((address_space(3)))
; __device__ __forceinline__ int ltid() { int t = threadIdx.x; asm volatile("" : "+v"(t)); return t; }
; template <int NR>
; __device__ __forceinline__ void ln_comb(bf16_t* h, const bf16_t* sb, float scale, const float* g, const float* b, int lane) {
;     u32x4 hv[NR][4], sv[NR][4]; f32x4 v[NR][4][2]; float sm[NR];
; #pragma unroll
;     for (int i = 0; i < NR; ++i)
; #pragma unroll
;         for (int j = 0; j < 4; ++j) { hv[i][j] = *(const u32x4*)(h + (size_t)i * D + 8 * lane + 512 * j); sv[i][j] = *(const u32x4*)(sb + (size_t)i * D + 8 * lane + 512 * j); }
; template <int MODE>
; __device__ __forceinline__ void ln_phase(const Args& a, const float* g, const float* b, int nrows, float scale) {
;     ...
;         const bf16_t* sbuf = (const bf16_t*)a.out;
;         for (int r = 3 * gw; r < NTOK; r += 3 * NGW) ln_comb<3>(hb + (size_t)r * D, sbuf + (size_t)r * D, scale, g, b, lane);
; __device__ __forceinline__ void fill_gb(LAS unsigned char* lds, const float* g, const float* b) {
;     const int tid = ltid(); LAS float* gb = (LAS float*)(lds + LDS_GB);
;     *(LAS f32x4*)(gb + 4 * tid) = *(const f32x4*)(g + 4 * tid); *(LAS f32x4*)(gb + D + 4 * tid) = *(const f32x4*)(b + 4 * tid) * ALPHA;
;     __syncthreads();
; }
.LBB0_344:
	s_andn2_b64 vcc, exec, s[0:1]
	s_cbranch_vccnz .LBB0_352
	v_readlane_b32 s0, v251, 6
	v_readlane_b32 s1, v251, 7
	s_lshl_b64 s[0:1], s[0:1], 2
	v_readlane_b32 s52, v254, 23
	v_readlane_b32 s53, v254, 24
	s_add_u32 s42, s52, s0
	v_readlane_b32 s54, v254, 25
	s_addc_u32 s43, s53, s1
	v_readlane_b32 s55, v254, 26
	s_add_u32 s44, s54, s0
	v_mov_b32_e32 v1, v155
	s_mov_b32 s0, s22
	s_addc_u32 s45, s55, s1
	s_lshl_b32 s46, s0, 3
	v_ashrrev_i32_e32 v42, 6, v1
	v_and_b32_e32 v109, 63, v1
	v_add_u32_e32 v43, s46, v42
	v_cmp_gt_i32_e32 vcc, s79, v43
	v_lshlrev_b32_e32 v44, 4, v109
	v_readlane_b32 s56, v254, 27
	v_readlane_b32 s57, v254, 28
	v_readlane_b32 s58, v254, 29
	v_readlane_b32 s59, v254, 30
	v_readlane_b32 s60, v254, 31
	v_readlane_b32 s61, v254, 32
	v_readlane_b32 s62, v254, 33
	v_readlane_b32 s63, v254, 34
	v_readlane_b32 s64, v254, 35
	v_readlane_b32 s65, v254, 36
	v_readlane_b32 s66, v254, 37
	v_readlane_b32 s67, v254, 38
	v_lshlrev_b32_e32 v2, 4, v155
	global_load_dwordx4 v[6:9], v2, s[42:43]
	global_load_dwordx4 v[14:17], v2, s[44:45]
	v_add_u32_e32 v2, 0x20000, v2
	s_waitcnt vmcnt(0)
	ds_write_b128 v2, v[6:9]
	ds_write_b128 v2, v[14:17] offset:8192
	s_waitcnt lgkmcnt(0)
	s_barrier
	s_and_saveexec_b64 s[92:93], vcc
	s_cbranch_execz .LBB0_348
	v_xor_b32_e32 v1, 1, v201
	v_cmp_lt_i32_e32 vcc, v1, v202
	v_lshl_add_u32 v46, v43, 1, v43
	v_lshlrev_b32_e32 v2, 5, v109
	v_cndmask_b32_e32 v1, v201, v1, vcc
	v_lshlrev_b32_e32 v111, 2, v1
	v_xor_b32_e32 v1, 2, v201
	v_cmp_lt_i32_e32 vcc, v1, v202
	v_mov_b32_e32 v3, v0
	v_add_u32_e32 v48, 0x20000, v2
	v_cndmask_b32_e32 v1, v201, v1, vcc
	v_lshlrev_b32_e32 v113, 2, v1
	v_xor_b32_e32 v1, 4, v201
	v_cmp_lt_i32_e32 vcc, v1, v202
	v_or_b32_e32 v4, 0x1000, v2
	v_cndmask_b32_e32 v1, v201, v1, vcc
	v_lshlrev_b32_e32 v148, 2, v1
	v_xor_b32_e32 v1, 8, v201
	v_cmp_lt_i32_e32 vcc, v1, v202
	v_or_b32_e32 v2, 0x1800, v2
	v_ashrrev_i32_e32 v47, 31, v46
	v_cndmask_b32_e32 v1, v201, v1, vcc
	v_lshlrev_b32_e32 v149, 2, v1
	v_xor_b32_e32 v1, 16, v201
	v_cmp_lt_i32_e32 vcc, v1, v202
	v_readlane_b32 s0, v253, 58
	v_mov_b32_e32 v5, v0
	v_cndmask_b32_e32 v1, v201, v1, vcc
	v_lshlrev_b32_e32 v150, 2, v1
	v_xor_b32_e32 v1, 32, v201
	v_cmp_lt_i32_e32 vcc, v1, v202
	s_waitcnt vmcnt(0)
	v_cndmask_b32_e32 v1, v201, v1, vcc
	v_lshlrev_b64 v[2:3], 12, v[46:47]
	v_readlane_b32 s4, v253, 62
	v_readlane_b32 s5, v253, 63
	v_readlane_b32 s6, v254, 0
	v_readlane_b32 s7, v254, 1
	v_lshlrev_b32_e32 v151, 2, v1
	v_mov_b32_e32 v45, v0
	v_lshl_add_u64 v[60:61], s[6:7], 0, v[2:3]
	v_lshl_add_u64 v[62:63], s[4:5], 0, v[2:3]
	s_mov_b64 s[20:21], 0
	v_readlane_b32 s1, v253, 59
	v_readlane_b32 s2, v253, 60
	v_readlane_b32 s3, v253, 61
.LBB0_347:
	v_lshl_add_u64 v[68:69], v[60:61], 0, v[44:45]
	v_lshl_add_u64 v[2:3], v[62:63], 0, v[44:45]
	global_load_dwordx4 v[70:73], v[68:69], off
	global_load_dwordx4 v[74:77], v[2:3], off
	global_load_dwordx4 v[78:81], v[68:69], off offset:1024
	global_load_dwordx4 v[82:85], v[2:3], off offset:1024
	global_load_dwordx4 v[86:89], v[68:69], off offset:2048
	global_load_dwordx4 v[90:93], v[2:3], off offset:2048
	global_load_dwordx4 v[100:103], v[68:69], off offset:3072
	global_load_dwordx4 v[104:107], v[2:3], off offset:3072
	v_add_co_u32_e32 v64, vcc, 0x1000, v68
	v_add_u32_e32 v46, s96, v46
	s_nop 0
	v_addc_co_u32_e32 v65, vcc, 0, v69, vcc
	global_load_dwordx4 v[114:117], v[64:65], off
	v_add_co_u32_e32 v4, vcc, 0x1000, v2
	v_lshl_add_u64 v[60:61], v[60:61], 0, s[16:17]
	s_nop 0
	v_addc_co_u32_e32 v5, vcc, 0, v3, vcc
	global_load_dwordx4 v[118:121], v[4:5], off
	global_load_dwordx4 v[140:143], v[64:65], off offset:1024
	global_load_dwordx4 v[144:147], v[4:5], off offset:1024
	global_load_dwordx4 v[160:163], v[64:65], off offset:2048
	global_load_dwordx4 v[164:167], v[4:5], off offset:2048
	global_load_dwordx4 v[38:41], v[64:65], off offset:3072
	global_load_dwordx4 v[34:37], v[4:5], off offset:3072
	v_add_co_u32_e32 v66, vcc, 0x2000, v68
	v_lshl_add_u64 v[62:63], v[62:63], 0, s[16:17]
	s_nop 0
	v_addc_co_u32_e32 v67, vcc, 0, v69, vcc
	global_load_dwordx4 v[30:33], v[66:67], off
	v_add_co_u32_e32 v2, vcc, 0x2000, v2
	v_addc_co_u32_e32 v3, vcc, 0, v3, vcc
	global_load_dwordx4 v[26:29], v[2:3], off
	global_load_dwordx4 v[22:25], v[66:67], off offset:1024
	global_load_dwordx4 v[18:21], v[2:3], off offset:1024
	global_load_dwordx4 v[14:17], v[66:67], off offset:2048
	global_load_dwordx4 v[10:13], v[2:3], off offset:2048
	global_load_dwordx4 v[6:9], v[66:67], off offset:3072
	s_nop 0
	global_load_dwordx4 v[2:5], v[2:3], off offset:3072
	s_waitcnt vmcnt(23)
	v_lshlrev_b32_e32 v94, 16, v70
	s_waitcnt vmcnt(22)
	v_lshlrev_b32_e32 v98, 16, v74
	v_and_b32_e32 v99, 0xffff0000, v74
	v_lshlrev_b32_e32 v74, 16, v75
	v_and_b32_e32 v75, 0xffff0000, v75
	v_and_b32_e32 v95, 0xffff0000, v70
	v_lshlrev_b32_e32 v70, 16, v71
	v_and_b32_e32 v71, 0xffff0000, v71
	v_lshlrev_b32_e32 v122, 16, v76
	v_and_b32_e32 v123, 0xffff0000, v76
	v_pk_mul_f32 v[74:75], v[74:75], 0.5 op_sel_hi:[1,0]
	v_lshlrev_b32_e32 v96, 16, v72
	v_and_b32_e32 v97, 0xffff0000, v72
	v_lshlrev_b32_e32 v76, 16, v77
	v_and_b32_e32 v77, 0xffff0000, v77
	v_pk_mul_f32 v[98:99], v[98:99], 0.5 op_sel_hi:[1,0]
	v_pk_fma_f32 v[128:129], v[70:71], s[24:25], v[74:75] op_sel_hi:[1,0,1]
	v_pk_mul_f32 v[70:71], v[122:123], 0.5 op_sel_hi:[1,0]
	v_lshlrev_b32_e32 v72, 16, v73
	v_and_b32_e32 v73, 0xffff0000, v73
	v_pk_fma_f32 v[130:131], v[94:95], s[24:25], v[98:99] op_sel_hi:[1,0,1]
	v_pk_mul_f32 v[74:75], v[76:77], 0.5 op_sel_hi:[1,0]
	v_pk_fma_f32 v[126:127], v[96:97], s[24:25], v[70:71] op_sel_hi:[1,0,1]
	v_pk_fma_f32 v[124:125], v[72:73], s[24:25], v[74:75] op_sel_hi:[1,0,1]
	v_mov_b32_e32 v70, v130
	v_mov_b32_e32 v71, v126
	v_mov_b32_e32 v72, v131
	v_mov_b32_e32 v73, v127
	v_pk_add_f32 v[70:71], v[70:71], v[72:73]
	v_mov_b32_e32 v72, v128
	v_mov_b32_e32 v73, v124
	v_mov_b32_e32 v74, v129
	v_mov_b32_e32 v75, v125
	v_pk_add_f32 v[72:73], v[72:73], v[74:75]
	s_waitcnt vmcnt(21)
; __device__ __forceinline__ void unpack8v(const u32x4 w, f32x4& lo, f32x4& hi) { lo = (f32x4){bf_lo(w.x), bf_hi(w.x), bf_lo(w.y), bf_hi(w.y)}; hi = (f32x4){bf_lo(w.z), bf_hi(w.z), bf_lo(w.w), bf_hi(w.w)}; }
; template <int NR>
; __device__ __forceinline__ void ln_comb(bf16_t* h, const bf16_t* sb, float scale, const float* g, const float* b, int lane) {
;     ...
; #pragma unroll
;     for (int i = 0; i < NR; ++i) { float s = 0.f;
; #pragma unroll
;         for (int j = 0; j < 4; ++j) { f32x4 h0, h1, s0, s1; unpack8v(hv[i][j], h0, h1); unpack8v(sv[i][j], s0, s1);
;             v[i][j][0] = h0 * ALPHA + s0 * scale; v[i][j][1] = h1 * ALPHA + s1 * scale;
;             s += ((v[i][j][0].x + v[i][j][0].y) + (v[i][j][0].z + v[i][j][0].w)) + ((v[i][j][1].x + v[i][j][1].y) + (v[i][j][1].z + v[i][j][1].w)); }
;         sm[i] = s; }
	v_lshlrev_b32_e32 v74, 16, v80
	v_pk_add_f32 v[70:71], v[70:71], v[72:73]
	v_lshlrev_b32_e32 v72, 16, v79
	v_pk_add_f32 v[132:133], v[70:71], v[70:71] op_sel:[0,1] op_sel_hi:[1,0]
	v_lshlrev_b32_e32 v70, 16, v78
	v_and_b32_e32 v71, 0xffff0000, v78
	v_and_b32_e32 v73, 0xffff0000, v79
	v_and_b32_e32 v75, 0xffff0000, v80
	v_lshlrev_b32_e32 v76, 16, v81
	v_and_b32_e32 v77, 0xffff0000, v81
	s_waitcnt vmcnt(20)
	v_lshlrev_b32_e32 v78, 16, v82
	v_and_b32_e32 v79, 0xffff0000, v82
	v_lshlrev_b32_e32 v80, 16, v83
	v_and_b32_e32 v81, 0xffff0000, v83
	v_lshlrev_b32_e32 v82, 16, v84
	v_and_b32_e32 v83, 0xffff0000, v84
	v_lshlrev_b32_e32 v84, 16, v85
	v_and_b32_e32 v85, 0xffff0000, v85
	v_pk_mul_f32 v[78:79], v[78:79], 0.5 op_sel_hi:[1,0]
	v_pk_mul_f32 v[80:81], v[80:81], 0.5 op_sel_hi:[1,0]
	v_pk_fma_f32 v[122:123], v[70:71], s[24:25], v[78:79] op_sel_hi:[1,0,1]
	v_pk_fma_f32 v[98:99], v[72:73], s[24:25], v[80:81] op_sel_hi:[1,0,1]
	v_pk_mul_f32 v[70:71], v[82:83], 0.5 op_sel_hi:[1,0]
	v_pk_mul_f32 v[72:73], v[84:85], 0.5 op_sel_hi:[1,0]
	v_pk_fma_f32 v[96:97], v[74:75], s[24:25], v[70:71] op_sel_hi:[1,0,1]
	v_pk_fma_f32 v[94:95], v[76:77], s[24:25], v[72:73] op_sel_hi:[1,0,1]
	v_pk_mov_b32 v[70:71], v[122:123], v[98:99] op_sel:[1,0]
	v_mov_b32_e32 v72, v122
	v_mov_b32_e32 v73, v99
	v_pk_add_f32 v[70:71], v[70:71], v[72:73]
	v_mov_b32_e32 v72, v96
	v_pk_add_f32 v[134:135], v[70:71], v[70:71] op_sel:[0,1] op_sel_hi:[1,0]
	v_pk_mov_b32 v[70:71], v[96:97], v[94:95] op_sel:[1,0]
	v_mov_b32_e32 v73, v95
	v_pk_add_f32 v[70:71], v[70:71], v[72:73]
	s_waitcnt vmcnt(18)
	v_lshlrev_b32_e32 v78, 16, v90
	v_and_b32_e32 v79, 0xffff0000, v90
	v_lshlrev_b32_e32 v80, 16, v91
	v_and_b32_e32 v81, 0xffff0000, v91
	v_pk_add_f32 v[136:137], v[70:71], v[70:71] op_sel:[0,1] op_sel_hi:[1,0]
	v_lshlrev_b32_e32 v70, 16, v86
	v_and_b32_e32 v71, 0xffff0000, v86
	v_lshlrev_b32_e32 v72, 16, v87
	v_and_b32_e32 v73, 0xffff0000, v87
	v_lshlrev_b32_e32 v74, 16, v88
	v_and_b32_e32 v75, 0xffff0000, v88
	v_lshlrev_b32_e32 v76, 16, v89
	v_and_b32_e32 v77, 0xffff0000, v89
	v_lshlrev_b32_e32 v86, 16, v92
	v_and_b32_e32 v87, 0xffff0000, v92
	v_lshlrev_b32_e32 v88, 16, v93
	v_and_b32_e32 v89, 0xffff0000, v93
	v_pk_mul_f32 v[78:79], v[78:79], 0.5 op_sel_hi:[1,0]
	v_pk_mul_f32 v[80:81], v[80:81], 0.5 op_sel_hi:[1,0]
	v_pk_fma_f32 v[84:85], v[70:71], s[24:25], v[78:79] op_sel_hi:[1,0,1]
	v_pk_fma_f32 v[82:83], v[72:73], s[24:25], v[80:81] op_sel_hi:[1,0,1]
	v_pk_mul_f32 v[70:71], v[86:87], 0.5 op_sel_hi:[1,0]
	v_pk_mul_f32 v[72:73], v[88:89], 0.5 op_sel_hi:[1,0]
	v_pk_fma_f32 v[80:81], v[74:75], s[24:25], v[70:71] op_sel_hi:[1,0,1]
	v_pk_fma_f32 v[78:79], v[76:77], s[24:25], v[72:73] op_sel_hi:[1,0,1]
	s_waitcnt vmcnt(17)
	v_lshlrev_b32_e32 v70, 16, v100
	v_and_b32_e32 v71, 0xffff0000, v100
	v_lshlrev_b32_e32 v72, 16, v101
	v_and_b32_e32 v73, 0xffff0000, v101
	v_lshlrev_b32_e32 v74, 16, v102
	v_and_b32_e32 v75, 0xffff0000, v102
	v_lshlrev_b32_e32 v100, 16, v103
	v_and_b32_e32 v101, 0xffff0000, v103
	s_waitcnt vmcnt(16)
	v_lshlrev_b32_e32 v76, 16, v104
	v_and_b32_e32 v77, 0xffff0000, v104
	v_lshlrev_b32_e32 v102, 16, v105
	v_and_b32_e32 v103, 0xffff0000, v105
	v_lshlrev_b32_e32 v104, 16, v106
	v_and_b32_e32 v105, 0xffff0000, v106
	v_lshlrev_b32_e32 v106, 16, v107
	v_and_b32_e32 v107, 0xffff0000, v107
	v_pk_mul_f32 v[76:77], v[76:77], 0.5 op_sel_hi:[1,0]
	v_pk_mul_f32 v[102:103], v[102:103], 0.5 op_sel_hi:[1,0]
	v_pk_fma_f32 v[76:77], v[70:71], s[24:25], v[76:77] op_sel_hi:[1,0,1]
	v_pk_fma_f32 v[72:73], v[72:73], s[24:25], v[102:103] op_sel_hi:[1,0,1]
	v_pk_mul_f32 v[102:103], v[104:105], 0.5 op_sel_hi:[1,0]
	v_pk_mul_f32 v[70:71], v[106:107], 0.5 op_sel_hi:[1,0]
	v_pk_fma_f32 v[74:75], v[74:75], s[24:25], v[102:103] op_sel_hi:[1,0,1]
	v_pk_fma_f32 v[70:71], v[100:101], s[24:25], v[70:71] op_sel_hi:[1,0,1]
	v_add_f32_e32 v86, v84, v85
	v_add_f32_e32 v88, v82, v83
	v_add_f32_e32 v90, v80, v81
	v_add_f32_e32 v92, v78, v79
	v_mov_b32_e32 v133, v76
	v_mov_b32_e32 v1, v77
	v_mov_b32_e32 v135, v72
	v_mov_b32_e32 v137, v73
	v_mov_b32_e32 v87, v74
	v_mov_b32_e32 v89, v75
	v_mov_b32_e32 v91, v70
	v_mov_b32_e32 v93, v71
	v_pk_add_f32 v[100:101], v[132:133], v[0:1]
	v_pk_add_f32 v[102:103], v[134:135], v[136:137]
	v_pk_add_f32 v[86:87], v[86:87], v[88:89]
	v_pk_add_f32 v[88:89], v[90:91], v[92:93]
	v_pk_add_f32 v[100:101], v[100:101], v[102:103]
	v_pk_add_f32 v[86:87], v[86:87], v[88:89]
	s_waitcnt vmcnt(14)
	v_lshlrev_b32_e32 v102, 16, v119
	v_pk_add_f32 v[86:87], v[100:101], v[86:87]
	v_lshlrev_b32_e32 v100, 16, v118
	v_and_b32_e32 v101, 0xffff0000, v118
	v_add_f32_e32 v47, v86, v87
	v_lshlrev_b32_e32 v86, 16, v114
	v_and_b32_e32 v87, 0xffff0000, v114
	v_and_b32_e32 v103, 0xffff0000, v119
	v_lshlrev_b32_e32 v104, 16, v120
	v_and_b32_e32 v105, 0xffff0000, v120
	v_pk_mul_f32 v[100:101], v[100:101], 0.5 op_sel_hi:[1,0]
	v_lshlrev_b32_e32 v88, 16, v115
	v_and_b32_e32 v89, 0xffff0000, v115
	v_lshlrev_b32_e32 v90, 16, v116
	v_and_b32_e32 v91, 0xffff0000, v116
	v_lshlrev_b32_e32 v106, 16, v121
	v_and_b32_e32 v107, 0xffff0000, v121
	v_pk_mul_f32 v[102:103], v[102:103], 0.5 op_sel_hi:[1,0]
	v_pk_fma_f32 v[136:137], v[86:87], s[24:25], v[100:101] op_sel_hi:[1,0,1]
	v_pk_mul_f32 v[86:87], v[104:105], 0.5 op_sel_hi:[1,0]
	v_lshlrev_b32_e32 v92, 16, v117
	v_and_b32_e32 v93, 0xffff0000, v117
	v_pk_fma_f32 v[132:133], v[88:89], s[24:25], v[102:103] op_sel_hi:[1,0,1]
	v_pk_mul_f32 v[88:89], v[106:107], 0.5 op_sel_hi:[1,0]
	v_pk_fma_f32 v[138:139], v[90:91], s[24:25], v[86:87] op_sel_hi:[1,0,1]
	v_pk_fma_f32 v[134:135], v[92:93], s[24:25], v[88:89] op_sel_hi:[1,0,1]
	v_mov_b32_e32 v86, v136
	v_mov_b32_e32 v87, v138
	v_mov_b32_e32 v88, v137
	v_mov_b32_e32 v89, v139
	v_pk_add_f32 v[86:87], v[86:87], v[88:89]
	v_mov_b32_e32 v88, v132
	v_mov_b32_e32 v89, v134
	v_mov_b32_e32 v90, v133
	v_mov_b32_e32 v91, v135
	v_pk_add_f32 v[88:89], v[88:89], v[90:91]
	s_waitcnt vmcnt(12)
; __device__ __forceinline__ void unpack8v(const u32x4 w, f32x4& lo, f32x4& hi) { lo = (f32x4){bf_lo(w.x), bf_hi(w.x), bf_lo(w.y), bf_hi(w.y)}; hi = (f32x4){bf_lo(w.z), bf_hi(w.z), bf_lo(w.w), bf_hi(w.w)}; }
; template <int NR>
; __device__ __forceinline__ void ln_comb(bf16_t* h, const bf16_t* sb, float scale, const float* g, const float* b, int lane) {
;     ...
; #pragma unroll
;     for (int i = 0; i < NR; ++i) { float s = 0.f;
; #pragma unroll
;         for (int j = 0; j < 4; ++j) { f32x4 h0, h1, s0, s1; unpack8v(hv[i][j], h0, h1); unpack8v(sv[i][j], s0, s1);
;             v[i][j][0] = h0 * ALPHA + s0 * scale; v[i][j][1] = h1 * ALPHA + s1 * scale;
;             s += ((v[i][j][0].x + v[i][j][0].y) + (v[i][j][0].z + v[i][j][0].w)) + ((v[i][j][1].x + v[i][j][1].y) + (v[i][j][1].z + v[i][j][1].w)); }
;         sm[i] = s; }
	v_lshlrev_b32_e32 v100, 16, v144
	v_pk_add_f32 v[86:87], v[86:87], v[88:89]
	v_and_b32_e32 v101, 0xffff0000, v144
	v_lshlrev_b32_e32 v102, 16, v145
	v_and_b32_e32 v103, 0xffff0000, v145
	v_pk_add_f32 v[114:115], v[86:87], v[86:87] op_sel:[0,1] op_sel_hi:[1,0]
	v_lshlrev_b32_e32 v86, 16, v140
	v_and_b32_e32 v87, 0xffff0000, v140
	v_lshlrev_b32_e32 v88, 16, v141
	v_and_b32_e32 v89, 0xffff0000, v141
	v_lshlrev_b32_e32 v116, 16, v146
	v_and_b32_e32 v117, 0xffff0000, v146
	v_lshlrev_b32_e32 v118, 16, v147
	v_and_b32_e32 v119, 0xffff0000, v147
	v_pk_mul_f32 v[100:101], v[100:101], 0.5 op_sel_hi:[1,0]
	v_pk_mul_f32 v[102:103], v[102:103], 0.5 op_sel_hi:[1,0]
	v_lshlrev_b32_e32 v90, 16, v142
	v_and_b32_e32 v91, 0xffff0000, v142
	v_lshlrev_b32_e32 v92, 16, v143
	v_and_b32_e32 v93, 0xffff0000, v143
	v_pk_fma_f32 v[104:105], v[88:89], s[24:25], v[102:103] op_sel_hi:[1,0,1]
	v_pk_fma_f32 v[106:107], v[86:87], s[24:25], v[100:101] op_sel_hi:[1,0,1]
	v_pk_mul_f32 v[86:87], v[116:117], 0.5 op_sel_hi:[1,0]
	v_pk_mul_f32 v[88:89], v[118:119], 0.5 op_sel_hi:[1,0]
	v_pk_fma_f32 v[102:103], v[90:91], s[24:25], v[86:87] op_sel_hi:[1,0,1]
	v_pk_fma_f32 v[100:101], v[92:93], s[24:25], v[88:89] op_sel_hi:[1,0,1]
	v_pk_mov_b32 v[86:87], v[106:107], v[104:105] op_sel:[1,0]
	v_mov_b32_e32 v88, v106
	v_mov_b32_e32 v89, v105
	v_pk_add_f32 v[86:87], v[86:87], v[88:89]
	v_mov_b32_e32 v88, v102
	v_pk_add_f32 v[116:117], v[86:87], v[86:87] op_sel:[0,1] op_sel_hi:[1,0]
	v_pk_mov_b32 v[86:87], v[102:103], v[100:101] op_sel:[1,0]
	v_mov_b32_e32 v89, v101
	v_pk_add_f32 v[86:87], v[86:87], v[88:89]
	s_waitcnt vmcnt(10)
	v_lshlrev_b32_e32 v90, 16, v164
	v_and_b32_e32 v91, 0xffff0000, v164
	v_pk_add_f32 v[118:119], v[86:87], v[86:87] op_sel:[0,1] op_sel_hi:[1,0]
	v_lshlrev_b32_e32 v86, 16, v160
	v_and_b32_e32 v87, 0xffff0000, v160
	v_lshlrev_b32_e32 v88, 16, v161
	v_and_b32_e32 v89, 0xffff0000, v161
	v_lshlrev_b32_e32 v92, 16, v165
	v_and_b32_e32 v93, 0xffff0000, v165
	v_pk_mul_f32 v[146:147], v[90:91], 0.5 op_sel_hi:[1,0]
	s_waitcnt vmcnt(9)
	v_lshlrev_b32_e32 v152, 16, v40
	v_and_b32_e32 v153, 0xffff0000, v40
	v_lshlrev_b32_e32 v160, 16, v41
	v_and_b32_e32 v161, 0xffff0000, v41
	s_waitcnt vmcnt(8)
	v_lshlrev_b32_e32 v40, 16, v34
	v_and_b32_e32 v41, 0xffff0000, v34
	v_lshlrev_b32_e32 v34, 16, v35
	v_and_b32_e32 v35, 0xffff0000, v35
	v_lshlrev_b32_e32 v120, 16, v162
	v_and_b32_e32 v121, 0xffff0000, v162
	v_lshlrev_b32_e32 v140, 16, v163
	v_and_b32_e32 v141, 0xffff0000, v163
	v_lshlrev_b32_e32 v142, 16, v166
	v_and_b32_e32 v143, 0xffff0000, v166
	v_lshlrev_b32_e32 v144, 16, v167
	v_and_b32_e32 v145, 0xffff0000, v167
	v_pk_mul_f32 v[90:91], v[92:93], 0.5 op_sel_hi:[1,0]
	v_pk_fma_f32 v[92:93], v[86:87], s[24:25], v[146:147] op_sel_hi:[1,0,1]
	v_lshlrev_b32_e32 v146, 16, v38
	v_and_b32_e32 v147, 0xffff0000, v38
	v_lshlrev_b32_e32 v38, 16, v39
	v_and_b32_e32 v39, 0xffff0000, v39
	v_lshlrev_b32_e32 v162, 16, v36
	v_and_b32_e32 v163, 0xffff0000, v36
	v_lshlrev_b32_e32 v164, 16, v37
	v_and_b32_e32 v165, 0xffff0000, v37
	v_pk_mul_f32 v[40:41], v[40:41], 0.5 op_sel_hi:[1,0]
	v_pk_mul_f32 v[34:35], v[34:35], 0.5 op_sel_hi:[1,0]
	v_pk_fma_f32 v[90:91], v[88:89], s[24:25], v[90:91] op_sel_hi:[1,0,1]
	v_pk_mul_f32 v[88:89], v[142:143], 0.5 op_sel_hi:[1,0]
	v_pk_mul_f32 v[86:87], v[144:145], 0.5 op_sel_hi:[1,0]
	v_pk_fma_f32 v[36:37], v[38:39], s[24:25], v[34:35] op_sel_hi:[1,0,1]
	v_pk_fma_f32 v[40:41], v[146:147], s[24:25], v[40:41] op_sel_hi:[1,0,1]
	v_pk_mul_f32 v[38:39], v[162:163], 0.5 op_sel_hi:[1,0]
	v_pk_mul_f32 v[34:35], v[164:165], 0.5 op_sel_hi:[1,0]
	v_pk_fma_f32 v[86:87], v[140:141], s[24:25], v[86:87] op_sel_hi:[1,0,1]
	v_pk_fma_f32 v[88:89], v[120:121], s[24:25], v[88:89] op_sel_hi:[1,0,1]
	v_pk_fma_f32 v[34:35], v[160:161], s[24:25], v[34:35] op_sel_hi:[1,0,1]
	v_pk_fma_f32 v[38:39], v[152:153], s[24:25], v[38:39] op_sel_hi:[1,0,1]
	v_mov_b32_e32 v115, v40
	v_mov_b32_e32 v1, v41
	v_mov_b32_e32 v117, v36
	v_mov_b32_e32 v119, v37
	v_add_f32_e32 v120, v92, v93
	v_add_f32_e32 v140, v90, v91
	v_add_f32_e32 v142, v88, v89
	v_add_f32_e32 v144, v86, v87
	v_pk_add_f32 v[114:115], v[114:115], v[0:1]
	v_pk_add_f32 v[116:117], v[116:117], v[118:119]
	v_mov_b32_e32 v121, v38
	v_mov_b32_e32 v141, v39
	v_mov_b32_e32 v143, v34
	v_mov_b32_e32 v145, v35
	v_pk_add_f32 v[114:115], v[114:115], v[116:117]
	v_pk_add_f32 v[116:117], v[120:121], v[140:141]
	v_pk_add_f32 v[118:119], v[142:143], v[144:145]
	s_waitcnt vmcnt(6)
	v_lshlrev_b32_e32 v120, 16, v28
	v_pk_add_f32 v[116:117], v[116:117], v[118:119]
	v_lshlrev_b32_e32 v118, 16, v26
	v_pk_add_f32 v[114:115], v[114:115], v[116:117]
	v_and_b32_e32 v119, 0xffff0000, v26
	v_lshlrev_b32_e32 v26, 16, v27
	v_and_b32_e32 v27, 0xffff0000, v27
	v_add_f32_e32 v108, v114, v115
	v_lshlrev_b32_e32 v114, 16, v30
	v_and_b32_e32 v115, 0xffff0000, v30
	v_lshlrev_b32_e32 v30, 16, v31
	v_and_b32_e32 v31, 0xffff0000, v31
	v_and_b32_e32 v121, 0xffff0000, v28
	v_pk_mul_f32 v[26:27], v[26:27], 0.5 op_sel_hi:[1,0]
	v_lshlrev_b32_e32 v116, 16, v32
	v_and_b32_e32 v117, 0xffff0000, v32
	v_lshlrev_b32_e32 v28, 16, v29
	v_and_b32_e32 v29, 0xffff0000, v29
	v_pk_mul_f32 v[118:119], v[118:119], 0.5 op_sel_hi:[1,0]
	v_pk_fma_f32 v[140:141], v[30:31], s[24:25], v[26:27] op_sel_hi:[1,0,1]
	v_pk_mul_f32 v[26:27], v[120:121], 0.5 op_sel_hi:[1,0]
	v_lshlrev_b32_e32 v32, 16, v33
	v_and_b32_e32 v33, 0xffff0000, v33
	v_pk_fma_f32 v[144:145], v[114:115], s[24:25], v[118:119] op_sel_hi:[1,0,1]
	v_pk_mul_f32 v[28:29], v[28:29], 0.5 op_sel_hi:[1,0]
	v_pk_fma_f32 v[146:147], v[116:117], s[24:25], v[26:27] op_sel_hi:[1,0,1]
	v_pk_fma_f32 v[142:143], v[32:33], s[24:25], v[28:29] op_sel_hi:[1,0,1]
	v_mov_b32_e32 v26, v144
	v_mov_b32_e32 v27, v146
	v_mov_b32_e32 v28, v145
	v_mov_b32_e32 v29, v147
	v_pk_add_f32 v[26:27], v[26:27], v[28:29]
	v_mov_b32_e32 v28, v140
	v_mov_b32_e32 v29, v142
	v_mov_b32_e32 v30, v141
	v_mov_b32_e32 v31, v143
	v_pk_add_f32 v[28:29], v[28:29], v[30:31]
	s_waitcnt vmcnt(4)
; template <int NR>
; __device__ __forceinline__ void ln_comb(bf16_t* h, const bf16_t* sb, float scale, const float* g, const float* b, int lane) {
;     ...
;             s += ((v[i][j][0].x + v[i][j][0].y) + (v[i][j][0].z + v[i][j][0].w)) + ((v[i][j][1].x + v[i][j][1].y) + (v[i][j][1].z + v[i][j][1].w)); }
;         sm[i] = s; }
; #pragma unroll
;     for (int o = 1; o < 64; o <<= 1) {
; #pragma unroll
;         for (int i = 0; i < NR; ++i) sm[i] += __shfl_xor(sm[i], o); }
	v_lshlrev_b32_e32 v30, 16, v18
	v_pk_add_f32 v[26:27], v[26:27], v[28:29]
	v_and_b32_e32 v31, 0xffff0000, v18
	v_lshlrev_b32_e32 v18, 16, v19
	v_and_b32_e32 v19, 0xffff0000, v19
	v_pk_add_f32 v[152:153], v[26:27], v[26:27] op_sel:[0,1] op_sel_hi:[1,0]
	v_lshlrev_b32_e32 v26, 16, v22
	v_and_b32_e32 v27, 0xffff0000, v22
	v_lshlrev_b32_e32 v22, 16, v23
	v_and_b32_e32 v23, 0xffff0000, v23
	v_lshlrev_b32_e32 v32, 16, v20
	v_and_b32_e32 v33, 0xffff0000, v20
	v_lshlrev_b32_e32 v20, 16, v21
	v_and_b32_e32 v21, 0xffff0000, v21
	v_pk_mul_f32 v[30:31], v[30:31], 0.5 op_sel_hi:[1,0]
	v_pk_mul_f32 v[18:19], v[18:19], 0.5 op_sel_hi:[1,0]
	v_lshlrev_b32_e32 v28, 16, v24
	v_and_b32_e32 v29, 0xffff0000, v24
	v_lshlrev_b32_e32 v24, 16, v25
	v_and_b32_e32 v25, 0xffff0000, v25
	v_pk_fma_f32 v[118:119], v[22:23], s[24:25], v[18:19] op_sel_hi:[1,0,1]
	v_pk_fma_f32 v[120:121], v[26:27], s[24:25], v[30:31] op_sel_hi:[1,0,1]
	v_pk_mul_f32 v[18:19], v[32:33], 0.5 op_sel_hi:[1,0]
	v_pk_mul_f32 v[20:21], v[20:21], 0.5 op_sel_hi:[1,0]
	v_pk_fma_f32 v[116:117], v[28:29], s[24:25], v[18:19] op_sel_hi:[1,0,1]
	v_pk_fma_f32 v[114:115], v[24:25], s[24:25], v[20:21] op_sel_hi:[1,0,1]
	v_pk_mov_b32 v[18:19], v[120:121], v[118:119] op_sel:[1,0]
	v_mov_b32_e32 v20, v120
	v_mov_b32_e32 v21, v119
	v_pk_add_f32 v[18:19], v[18:19], v[20:21]
	v_mov_b32_e32 v20, v116
	v_pk_add_f32 v[160:161], v[18:19], v[18:19] op_sel:[0,1] op_sel_hi:[1,0]
	v_pk_mov_b32 v[18:19], v[116:117], v[114:115] op_sel:[1,0]
	v_mov_b32_e32 v21, v115
	v_pk_add_f32 v[18:19], v[18:19], v[20:21]
	s_waitcnt vmcnt(2)
	v_lshlrev_b32_e32 v22, 16, v10
	v_and_b32_e32 v23, 0xffff0000, v10
	v_lshlrev_b32_e32 v10, 16, v11
	v_and_b32_e32 v11, 0xffff0000, v11
	v_pk_add_f32 v[162:163], v[18:19], v[18:19] op_sel:[0,1] op_sel_hi:[1,0]
	v_lshlrev_b32_e32 v18, 16, v14
	v_and_b32_e32 v19, 0xffff0000, v14
	v_lshlrev_b32_e32 v14, 16, v15
	v_and_b32_e32 v15, 0xffff0000, v15
	v_lshlrev_b32_e32 v24, 16, v12
	v_and_b32_e32 v25, 0xffff0000, v12
	v_pk_mul_f32 v[10:11], v[10:11], 0.5 op_sel_hi:[1,0]
	v_lshlrev_b32_e32 v20, 16, v16
	v_and_b32_e32 v21, 0xffff0000, v16
	v_pk_fma_f32 v[30:31], v[14:15], s[24:25], v[10:11] op_sel_hi:[1,0,1]
	v_pk_mul_f32 v[10:11], v[24:25], 0.5 op_sel_hi:[1,0]
	v_pk_mul_f32 v[22:23], v[22:23], 0.5 op_sel_hi:[1,0]
	v_pk_fma_f32 v[28:29], v[20:21], s[24:25], v[10:11] op_sel_hi:[1,0,1]
	s_waitcnt vmcnt(0)
	v_lshlrev_b32_e32 v20, 16, v2
	v_and_b32_e32 v21, 0xffff0000, v2
	v_lshlrev_b32_e32 v2, 16, v3
	v_and_b32_e32 v3, 0xffff0000, v3
	v_lshlrev_b32_e32 v12, 16, v13
	v_and_b32_e32 v13, 0xffff0000, v13
	v_pk_fma_f32 v[32:33], v[18:19], s[24:25], v[22:23] op_sel_hi:[1,0,1]
	v_lshlrev_b32_e32 v18, 16, v6
	v_and_b32_e32 v19, 0xffff0000, v6
	v_lshlrev_b32_e32 v6, 16, v7
	v_and_b32_e32 v7, 0xffff0000, v7
	v_lshlrev_b32_e32 v164, 16, v4
	v_and_b32_e32 v165, 0xffff0000, v4
	v_lshlrev_b32_e32 v4, 16, v5
	v_and_b32_e32 v5, 0xffff0000, v5
	v_pk_mul_f32 v[24:25], v[20:21], 0.5 op_sel_hi:[1,0]
	v_pk_mul_f32 v[2:3], v[2:3], 0.5 op_sel_hi:[1,0]
	v_lshlrev_b32_e32 v16, 16, v17
	v_and_b32_e32 v17, 0xffff0000, v17
	v_pk_mul_f32 v[12:13], v[12:13], 0.5 op_sel_hi:[1,0]
	v_lshlrev_b32_e32 v22, 16, v8
	v_and_b32_e32 v23, 0xffff0000, v8
	v_lshlrev_b32_e32 v8, 16, v9
	v_and_b32_e32 v9, 0xffff0000, v9
	v_pk_fma_f32 v[20:21], v[6:7], s[24:25], v[2:3] op_sel_hi:[1,0,1]
	v_pk_fma_f32 v[24:25], v[18:19], s[24:25], v[24:25] op_sel_hi:[1,0,1]
	v_pk_mul_f32 v[2:3], v[164:165], 0.5 op_sel_hi:[1,0]
	v_pk_mul_f32 v[4:5], v[4:5], 0.5 op_sel_hi:[1,0]
	v_pk_fma_f32 v[26:27], v[16:17], s[24:25], v[12:13] op_sel_hi:[1,0,1]
	v_pk_fma_f32 v[18:19], v[8:9], s[24:25], v[4:5] op_sel_hi:[1,0,1]
	v_pk_fma_f32 v[22:23], v[22:23], s[24:25], v[2:3] op_sel_hi:[1,0,1]
	v_mov_b32_e32 v153, v24
	v_mov_b32_e32 v1, v25
	v_mov_b32_e32 v161, v20
	v_mov_b32_e32 v163, v21
	v_add_f32_e32 v10, v32, v33
	v_add_f32_e32 v12, v30, v31
	v_add_f32_e32 v14, v28, v29
	v_add_f32_e32 v16, v26, v27
	v_pk_add_f32 v[2:3], v[152:153], v[0:1]
	v_pk_add_f32 v[4:5], v[160:161], v[162:163]
	v_mov_b32_e32 v11, v22
	v_mov_b32_e32 v13, v23
	v_mov_b32_e32 v15, v18
	v_mov_b32_e32 v17, v19
	v_pk_add_f32 v[2:3], v[2:3], v[4:5]
	v_pk_add_f32 v[4:5], v[10:11], v[12:13]
	v_pk_add_f32 v[6:7], v[14:15], v[16:17]
	s_nop 0
	v_pk_add_f32 v[4:5], v[4:5], v[6:7]
	s_nop 0
	v_pk_add_f32 v[2:3], v[2:3], v[4:5]
	s_nop 0
	v_add_f32_e32 v1, v2, v3
	ds_bpermute_b32 v2, v111, v47
	ds_bpermute_b32 v4, v111, v1
	ds_bpermute_b32 v3, v111, v108
	s_waitcnt lgkmcnt(2)
	v_add_f32_e32 v2, v47, v2
	s_waitcnt lgkmcnt(1)
	v_add_f32_e32 v1, v1, v4
	ds_bpermute_b32 v4, v113, v2
	s_waitcnt lgkmcnt(1)
	v_add_f32_e32 v3, v108, v3
	s_waitcnt lgkmcnt(0)
	v_add_f32_e32 v2, v2, v4
	ds_bpermute_b32 v4, v113, v3
	s_waitcnt lgkmcnt(0)
	v_add_f32_e32 v3, v3, v4
	ds_bpermute_b32 v4, v113, v1
	s_waitcnt lgkmcnt(0)
	v_add_f32_e32 v1, v1, v4
	ds_bpermute_b32 v4, v148, v2
	s_waitcnt lgkmcnt(0)
	v_add_f32_e32 v2, v2, v4
	ds_bpermute_b32 v4, v148, v3
	s_waitcnt lgkmcnt(0)
	v_add_f32_e32 v3, v3, v4
	ds_bpermute_b32 v4, v148, v1
	s_waitcnt lgkmcnt(0)
	v_add_f32_e32 v1, v1, v4
	ds_bpermute_b32 v4, v149, v2
	s_waitcnt lgkmcnt(0)
	v_add_f32_e32 v2, v2, v4
	ds_bpermute_b32 v4, v149, v3
	s_waitcnt lgkmcnt(0)
	v_add_f32_e32 v3, v3, v4
	ds_bpermute_b32 v4, v149, v1
	s_waitcnt lgkmcnt(0)
	v_add_f32_e32 v1, v1, v4
	ds_bpermute_b32 v4, v150, v2
	s_waitcnt lgkmcnt(0)
	v_add_f32_e32 v2, v2, v4
	ds_bpermute_b32 v4, v150, v3
	s_waitcnt lgkmcnt(0)
	v_add_f32_e32 v3, v3, v4
	ds_bpermute_b32 v4, v150, v1
	s_waitcnt lgkmcnt(0)
	v_add_f32_e32 v1, v1, v4
	ds_bpermute_b32 v4, v151, v2
	s_waitcnt lgkmcnt(0)
; template <int NR>
; __device__ __forceinline__ void ln_comb(bf16_t* h, const bf16_t* sb, float scale, const float* g, const float* b, int lane) {
;     ...
;     for (int i = 0; i < NR; ++i) { const float mean = sm[i] * (1.f / D); float s2 = 0.f;
; #pragma unroll
;         for (int j = 0; j < 4; ++j)
; #pragma unroll
;             for (int e = 0; e < 2; ++e) { v[i][j][e] = v[i][j][e] - mean; s2 += (v[i][j][e].x * v[i][j][e].x + v[i][j][e].y * v[i][j][e].y) + (v[i][j][e].z * v[i][j][e].z + v[i][j][e].w * v[i][j][e].w); }
;         q[i] = s2; }
	v_add_f32_e32 v10, v2, v4
	ds_bpermute_b32 v2, v151, v3
	v_fmamk_f32 v131, v10, 0xba000000, v131
	v_fmamk_f32 v127, v10, 0xba000000, v127
	v_fmamk_f32 v129, v10, 0xba000000, v129
	v_fmac_f32_e32 v130, 0xba000000, v10
	s_waitcnt lgkmcnt(0)
	v_add_f32_e32 v11, v3, v2
	ds_bpermute_b32 v2, v151, v1
	v_fmamk_f32 v125, v10, 0xba000000, v125
	v_fmac_f32_e32 v126, 0xba000000, v10
	v_mov_b32_e32 v4, v131
	v_mov_b32_e32 v5, v127
	s_waitcnt lgkmcnt(0)
	v_add_f32_e32 v1, v1, v2
	v_fmac_f32_e32 v128, 0xba000000, v10
	v_fmac_f32_e32 v124, 0xba000000, v10
	v_mov_b32_e32 v2, v130
	v_mov_b32_e32 v3, v126
	v_pk_mul_f32 v[4:5], v[4:5], v[4:5]
	v_mov_b32_e32 v6, v129
	v_mov_b32_e32 v7, v125
	v_pk_fma_f32 v[2:3], v[2:3], v[2:3], v[4:5]
	v_mov_b32_e32 v4, v128
	v_mov_b32_e32 v5, v124
	v_pk_mul_f32 v[6:7], v[6:7], v[6:7]
	v_fmamk_f32 v123, v10, 0xba000000, v123
	v_pk_fma_f32 v[4:5], v[4:5], v[4:5], v[6:7]
	v_fmac_f32_e32 v122, 0xba000000, v10
	v_pk_add_f32 v[2:3], v[2:3], v[4:5]
	v_fmamk_f32 v99, v10, 0xba000000, v99
	v_fmac_f32_e32 v98, 0xba000000, v10
	v_pk_add_f32 v[2:3], v[2:3], v[2:3] op_sel_hi:[0,1]
	v_pk_mul_f32 v[4:5], v[98:99], v[98:99]
	v_pk_mul_f32 v[6:7], v[122:123], v[122:123]
	v_fmac_f32_e32 v96, 0xba000000, v10
	v_pk_mov_b32 v[8:9], v[6:7], v[4:5] op_sel:[1,0]
	v_mov_b32_e32 v7, v5
	v_fmamk_f32 v97, v10, 0xba000000, v97
	v_fmac_f32_e32 v94, 0xba000000, v10
	v_mul_f32_e32 v2, v96, v96
	v_pk_add_f32 v[4:5], v[8:9], v[6:7]
	v_fmamk_f32 v95, v10, 0xba000000, v95
	v_pk_fma_f32 v[6:7], v[96:97], v[96:97], v[2:3] op_sel_hi:[1,1,0]
	v_mul_f32_e32 v2, v94, v94
	v_pk_add_f32 v[4:5], v[4:5], v[4:5] op_sel_hi:[0,1]
	v_pk_fma_f32 v[8:9], v[94:95], v[94:95], v[2:3] op_sel_hi:[1,1,0]
	v_fmamk_f32 v83, v10, 0xba000000, v83
	v_fmac_f32_e32 v82, 0xba000000, v10
	v_fmamk_f32 v85, v10, 0xba000000, v85
	v_fmac_f32_e32 v84, 0xba000000, v10
	v_mul_f32_e32 v6, v84, v84
	v_mul_f32_e32 v8, v85, v85
	v_mul_f32_e32 v4, v82, v82
	v_mul_f32_e32 v2, v83, v83
	v_pk_add_f32 v[6:7], v[6:7], v[8:9]
	v_pk_add_f32 v[2:3], v[4:5], v[2:3]
	v_fmamk_f32 v81, v10, 0xba000000, v81
	v_pk_add_f32 v[2:3], v[6:7], v[2:3]
	v_fmac_f32_e32 v80, 0xba000000, v10
	v_fmamk_f32 v79, v10, 0xba000000, v79
	v_fmac_f32_e32 v78, 0xba000000, v10
	v_pk_add_f32 v[2:3], v[2:3], v[2:3] op_sel_hi:[0,1]
	v_pk_mul_f32 v[4:5], v[78:79], v[78:79]
	v_pk_mul_f32 v[6:7], v[80:81], v[80:81]
	v_fmac_f32_e32 v76, 0xba000000, v10
	v_pk_mov_b32 v[8:9], v[6:7], v[4:5] op_sel:[1,0]
	v_mov_b32_e32 v7, v5
	v_fmamk_f32 v77, v10, 0xba000000, v77
	v_fmac_f32_e32 v72, 0xba000000, v10
	v_mul_f32_e32 v2, v76, v76
	v_pk_add_f32 v[4:5], v[8:9], v[6:7]
	v_fmamk_f32 v73, v10, 0xba000000, v73
	v_pk_fma_f32 v[6:7], v[76:77], v[76:77], v[2:3] op_sel_hi:[1,1,0]
	v_mul_f32_e32 v2, v72, v72
	v_pk_add_f32 v[4:5], v[4:5], v[4:5] op_sel_hi:[0,1]
	v_pk_fma_f32 v[8:9], v[72:73], v[72:73], v[2:3] op_sel_hi:[1,1,0]
	v_fmamk_f32 v71, v10, 0xba000000, v71
	v_fmac_f32_e32 v70, 0xba000000, v10
	v_fmamk_f32 v75, v10, 0xba000000, v75
	v_fmac_f32_e32 v74, 0xba000000, v10
	v_mul_f32_e32 v6, v74, v74
	v_mul_f32_e32 v8, v75, v75
	v_mul_f32_e32 v4, v70, v70
	v_mul_f32_e32 v2, v71, v71
	v_pk_add_f32 v[6:7], v[6:7], v[8:9]
	v_pk_add_f32 v[2:3], v[4:5], v[2:3]
	v_fmamk_f32 v137, v11, 0xba000000, v137
	v_fmamk_f32 v139, v11, 0xba000000, v139
	v_pk_add_f32 v[2:3], v[6:7], v[2:3]
	v_fmamk_f32 v133, v11, 0xba000000, v133
	v_fmac_f32_e32 v136, 0xba000000, v11
	v_fmamk_f32 v135, v11, 0xba000000, v135
	v_fmac_f32_e32 v138, 0xba000000, v11
	v_mov_b32_e32 v4, v137
	v_mov_b32_e32 v5, v139
	v_add_f32_e32 v12, v2, v3
	v_fmac_f32_e32 v132, 0xba000000, v11
	v_fmac_f32_e32 v134, 0xba000000, v11
	v_mov_b32_e32 v2, v136
	v_mov_b32_e32 v3, v138
	v_pk_mul_f32 v[4:5], v[4:5], v[4:5]
	v_mov_b32_e32 v6, v133
	v_mov_b32_e32 v7, v135
	v_pk_fma_f32 v[2:3], v[2:3], v[2:3], v[4:5]
	v_mov_b32_e32 v4, v132
	v_mov_b32_e32 v5, v134
	v_pk_mul_f32 v[6:7], v[6:7], v[6:7]
	v_fmamk_f32 v107, v11, 0xba000000, v107
	v_pk_fma_f32 v[4:5], v[4:5], v[4:5], v[6:7]
	v_fmac_f32_e32 v106, 0xba000000, v11
	v_pk_add_f32 v[2:3], v[2:3], v[4:5]
	v_fmamk_f32 v105, v11, 0xba000000, v105
	v_fmac_f32_e32 v104, 0xba000000, v11
	v_pk_add_f32 v[2:3], v[2:3], v[2:3] op_sel_hi:[0,1]
	v_pk_mul_f32 v[4:5], v[104:105], v[104:105]
	v_pk_mul_f32 v[6:7], v[106:107], v[106:107]
	v_fmac_f32_e32 v102, 0xba000000, v11
	v_pk_mov_b32 v[8:9], v[6:7], v[4:5] op_sel:[1,0]
	v_mov_b32_e32 v7, v5
	v_fmamk_f32 v103, v11, 0xba000000, v103
	v_fmac_f32_e32 v100, 0xba000000, v11
	v_mul_f32_e32 v2, v102, v102
	v_pk_add_f32 v[4:5], v[8:9], v[6:7]
	v_fmamk_f32 v101, v11, 0xba000000, v101
	v_pk_fma_f32 v[6:7], v[102:103], v[102:103], v[2:3] op_sel_hi:[1,1,0]
	v_mul_f32_e32 v2, v100, v100
	v_pk_add_f32 v[4:5], v[4:5], v[4:5] op_sel_hi:[0,1]
	v_pk_fma_f32 v[8:9], v[100:101], v[100:101], v[2:3] op_sel_hi:[1,1,0]
	v_fmamk_f32 v91, v11, 0xba000000, v91
	v_fmac_f32_e32 v90, 0xba000000, v11
	v_fmamk_f32 v93, v11, 0xba000000, v93
	v_fmac_f32_e32 v92, 0xba000000, v11
	v_mul_f32_e32 v6, v92, v92
	v_mul_f32_e32 v8, v93, v93
	v_mul_f32_e32 v4, v90, v90
	v_mul_f32_e32 v2, v91, v91
	v_pk_add_f32 v[6:7], v[6:7], v[8:9]
	v_pk_add_f32 v[2:3], v[4:5], v[2:3]
	v_fmamk_f32 v89, v11, 0xba000000, v89
	v_pk_add_f32 v[2:3], v[6:7], v[2:3]
	v_fmac_f32_e32 v88, 0xba000000, v11
	v_fmamk_f32 v87, v11, 0xba000000, v87
	v_fmac_f32_e32 v86, 0xba000000, v11
	v_pk_add_f32 v[2:3], v[2:3], v[2:3] op_sel_hi:[0,1]
	v_pk_mul_f32 v[4:5], v[86:87], v[86:87]
	v_pk_mul_f32 v[6:7], v[88:89], v[88:89]
	v_fmac_f32_e32 v40, 0xba000000, v11
	v_pk_mov_b32 v[8:9], v[6:7], v[4:5] op_sel:[1,0]
	v_mov_b32_e32 v7, v5
	v_fmamk_f32 v41, v11, 0xba000000, v41
	v_fmac_f32_e32 v36, 0xba000000, v11
; template <int NR>
; __device__ __forceinline__ void ln_comb(bf16_t* h, const bf16_t* sb, float scale, const float* g, const float* b, int lane) {
;     ...
;         q[i] = s2; }
; #pragma unroll
;     for (int o = 1; o < 64; o <<= 1) {
; #pragma unroll
;         for (int i = 0; i < NR; ++i) q[i] += __shfl_xor(q[i], o); }
; #pragma unroll
;     for (int i = 0; i < NR; ++i) rstd[i] = rsqrtf(q[i] * (1.f / D) + LN_EPS);
	v_mul_f32_e32 v2, v40, v40
	v_pk_add_f32 v[4:5], v[8:9], v[6:7]
	v_fmamk_f32 v37, v11, 0xba000000, v37
	v_pk_fma_f32 v[6:7], v[40:41], v[40:41], v[2:3] op_sel_hi:[1,1,0]
	v_mul_f32_e32 v2, v36, v36
	v_pk_add_f32 v[4:5], v[4:5], v[4:5] op_sel_hi:[0,1]
	v_pk_fma_f32 v[8:9], v[36:37], v[36:37], v[2:3] op_sel_hi:[1,1,0]
	v_fmamk_f32 v35, v11, 0xba000000, v35
	v_fmac_f32_e32 v34, 0xba000000, v11
	v_fmamk_f32 v39, v11, 0xba000000, v39
	v_fmac_f32_e32 v38, 0xba000000, v11
	v_mul_f32_e32 v6, v38, v38
	v_mul_f32_e32 v8, v39, v39
	v_mul_f32_e32 v4, v34, v34
	v_mul_f32_e32 v2, v35, v35
	v_pk_add_f32 v[6:7], v[6:7], v[8:9]
	v_pk_add_f32 v[2:3], v[4:5], v[2:3]
	v_fmamk_f32 v145, v1, 0xba000000, v145
	v_fmamk_f32 v147, v1, 0xba000000, v147
	v_pk_add_f32 v[2:3], v[6:7], v[2:3]
	v_fmamk_f32 v141, v1, 0xba000000, v141
	v_fmac_f32_e32 v144, 0xba000000, v1
	v_fmamk_f32 v143, v1, 0xba000000, v143
	v_fmac_f32_e32 v146, 0xba000000, v1
	v_mov_b32_e32 v6, v145
	v_mov_b32_e32 v7, v147
	v_fmac_f32_e32 v140, 0xba000000, v1
	v_fmac_f32_e32 v142, 0xba000000, v1
	v_mov_b32_e32 v4, v144
	v_mov_b32_e32 v5, v146
	v_pk_mul_f32 v[6:7], v[6:7], v[6:7]
	v_mov_b32_e32 v8, v141
	v_mov_b32_e32 v9, v143
	v_pk_fma_f32 v[4:5], v[4:5], v[4:5], v[6:7]
	v_mov_b32_e32 v6, v140
	v_mov_b32_e32 v7, v142
	v_pk_mul_f32 v[8:9], v[8:9], v[8:9]
	v_fmamk_f32 v121, v1, 0xba000000, v121
	v_pk_fma_f32 v[6:7], v[6:7], v[6:7], v[8:9]
	v_fmac_f32_e32 v120, 0xba000000, v1
	v_pk_add_f32 v[4:5], v[4:5], v[6:7]
	v_fmamk_f32 v119, v1, 0xba000000, v119
	v_fmac_f32_e32 v118, 0xba000000, v1
	v_pk_add_f32 v[4:5], v[4:5], v[4:5] op_sel_hi:[0,1]
	v_pk_mul_f32 v[6:7], v[118:119], v[118:119]
	v_pk_mul_f32 v[8:9], v[120:121], v[120:121]
	v_fmac_f32_e32 v116, 0xba000000, v1
	v_pk_mov_b32 v[10:11], v[8:9], v[6:7] op_sel:[1,0]
	v_mov_b32_e32 v9, v7
	v_fmamk_f32 v117, v1, 0xba000000, v117
	v_fmac_f32_e32 v114, 0xba000000, v1
	v_mul_f32_e32 v4, v116, v116
	v_pk_add_f32 v[6:7], v[10:11], v[8:9]
	v_fmamk_f32 v115, v1, 0xba000000, v115
	v_pk_fma_f32 v[8:9], v[116:117], v[116:117], v[4:5] op_sel_hi:[1,1,0]
	v_mul_f32_e32 v4, v114, v114
	v_pk_add_f32 v[6:7], v[6:7], v[6:7] op_sel_hi:[0,1]
	v_pk_fma_f32 v[10:11], v[114:115], v[114:115], v[4:5] op_sel_hi:[1,1,0]
	v_fmamk_f32 v31, v1, 0xba000000, v31
	v_fmac_f32_e32 v30, 0xba000000, v1
	v_fmamk_f32 v33, v1, 0xba000000, v33
	v_fmac_f32_e32 v32, 0xba000000, v1
	v_mul_f32_e32 v8, v32, v32
	v_mul_f32_e32 v10, v33, v33
	v_mul_f32_e32 v6, v30, v30
	v_mul_f32_e32 v4, v31, v31
	v_pk_add_f32 v[8:9], v[8:9], v[10:11]
	v_pk_add_f32 v[4:5], v[6:7], v[4:5]
	v_fmamk_f32 v29, v1, 0xba000000, v29
	v_fmac_f32_e32 v28, 0xba000000, v1
	v_fmamk_f32 v27, v1, 0xba000000, v27
	v_fmac_f32_e32 v26, 0xba000000, v1
	v_fmamk_f32 v25, v1, 0xba000000, v25
	v_fmac_f32_e32 v24, 0xba000000, v1
	v_fmamk_f32 v21, v1, 0xba000000, v21
	v_fmac_f32_e32 v20, 0xba000000, v1
	v_fmamk_f32 v19, v1, 0xba000000, v19
	v_fmac_f32_e32 v18, 0xba000000, v1
	v_fmamk_f32 v23, v1, 0xba000000, v23
	v_fmac_f32_e32 v22, 0xba000000, v1
	ds_bpermute_b32 v1, v111, v12
	v_pk_add_f32 v[4:5], v[8:9], v[4:5]
	v_pk_mul_f32 v[6:7], v[26:27], v[26:27]
	v_pk_mul_f32 v[8:9], v[28:29], v[28:29]
	v_pk_add_f32 v[4:5], v[4:5], v[4:5] op_sel_hi:[0,1]
	v_pk_mov_b32 v[10:11], v[8:9], v[6:7] op_sel:[1,0]
	v_mov_b32_e32 v9, v7
	v_pk_add_f32 v[6:7], v[10:11], v[8:9]
	v_mul_f32_e32 v4, v24, v24
	v_pk_add_f32 v[6:7], v[6:7], v[6:7] op_sel_hi:[0,1]
	v_pk_fma_f32 v[8:9], v[24:25], v[24:25], v[4:5] op_sel_hi:[1,1,0]
	v_mul_f32_e32 v4, v20, v20
	v_pk_fma_f32 v[10:11], v[20:21], v[20:21], v[4:5] op_sel_hi:[1,1,0]
	v_mul_f32_e32 v6, v18, v18
	v_mul_f32_e32 v4, v19, v19
	s_waitcnt lgkmcnt(0)
	v_add_f32_e32 v1, v12, v1
	v_pk_add_f32 v[4:5], v[6:7], v[4:5]
	ds_bpermute_b32 v6, v113, v1
	v_mul_f32_e32 v8, v22, v22
	v_mul_f32_e32 v10, v23, v23
	v_pk_add_f32 v[8:9], v[8:9], v[10:11]
	v_mov_b32_e32 v7, v2
	s_waitcnt lgkmcnt(0)
	v_add_f32_e32 v1, v1, v6
	ds_bpermute_b32 v6, v148, v1
	v_pk_add_f32 v[4:5], v[8:9], v[4:5]
	s_waitcnt lgkmcnt(0)
	v_add_f32_e32 v1, v1, v6
	ds_bpermute_b32 v6, v149, v1
	v_mov_b32_e32 v2, v5
	s_waitcnt lgkmcnt(0)
	v_add_f32_e32 v1, v1, v6
	ds_bpermute_b32 v6, v150, v1
	s_waitcnt lgkmcnt(0)
	v_add_f32_e32 v1, v1, v6
	ds_bpermute_b32 v6, v151, v1
	s_waitcnt lgkmcnt(0)
	v_add_f32_e32 v1, v1, v6
	v_fmamk_f32 v1, v1, 0x3a000000, v154
	v_cmp_gt_f32_e32 vcc, s73, v1
	v_mul_f32_e32 v6, 0x4b800000, v1
	s_nop 0
	v_cndmask_b32_e32 v1, v1, v6, vcc
	v_rsq_f32_e32 v1, v1
	s_nop 0
	v_mul_f32_e32 v6, 0x45800000, v1
	v_cndmask_b32_e32 v108, v1, v6, vcc
	v_mov_b32_e32 v6, v4
	v_pk_add_f32 v[2:3], v[6:7], v[2:3]
	ds_bpermute_b32 v5, v111, v3
	ds_bpermute_b32 v4, v111, v2
	v_pk_mul_f32 v[126:127], v[126:127], v[108:109] op_sel_hi:[1,0]
	v_pk_mul_f32 v[130:131], v[130:131], v[108:109] op_sel_hi:[1,0]
	v_pk_mul_f32 v[128:129], v[128:129], v[108:109] op_sel_hi:[1,0]
	v_pk_mul_f32 v[124:125], v[124:125], v[108:109] op_sel_hi:[1,0]
	s_waitcnt lgkmcnt(0)
	v_pk_add_f32 v[2:3], v[2:3], v[4:5]
	ds_bpermute_b32 v5, v113, v3
	ds_bpermute_b32 v4, v113, v2
	v_pk_mul_f32 v[96:97], v[96:97], v[108:109] op_sel_hi:[1,0]
	v_pk_mul_f32 v[122:123], v[122:123], v[108:109] op_sel_hi:[1,0]
	v_pk_mul_f32 v[98:99], v[98:99], v[108:109] op_sel_hi:[1,0]
	v_pk_mul_f32 v[94:95], v[94:95], v[108:109] op_sel_hi:[1,0]
	s_waitcnt lgkmcnt(0)
	v_pk_add_f32 v[2:3], v[2:3], v[4:5]
	ds_bpermute_b32 v5, v148, v3
	ds_bpermute_b32 v4, v148, v2
	v_pk_mul_f32 v[80:81], v[80:81], v[108:109] op_sel_hi:[1,0]
	v_pk_mul_f32 v[84:85], v[84:85], v[108:109] op_sel_hi:[1,0]
	v_pk_mul_f32 v[82:83], v[82:83], v[108:109] op_sel_hi:[1,0]
	v_pk_mul_f32 v[78:79], v[78:79], v[108:109] op_sel_hi:[1,0]
	s_waitcnt lgkmcnt(0)
; __device__ __forceinline__ unsigned cvt_pk_bf16(float lo, float hi) { unsigned r; asm volatile("v_cvt_pk_bf16_f32 %0, %1, %2" : "=v"(r) : "v"(lo), "v"(hi)); return r; }
; template <int NR>
; __device__ __forceinline__ void ln_comb(bf16_t* h, const bf16_t* sb, float scale, const float* g, const float* b, int lane) {
;     ...
;     for (int o = 1; o < 64; o <<= 1) {
; #pragma unroll
;         for (int i = 0; i < NR; ++i) q[i] += __shfl_xor(q[i], o); }
; #pragma unroll
;     for (int i = 0; i < NR; ++i) rstd[i] = rsqrtf(q[i] * (1.f / D) + LN_EPS);
; #pragma unroll
;     for (int j = 0; j < 4; ++j) {
;         const int c = 8 * lane + 512 * j;
;         const f32x4 g0 = *(const f32x4*)(g + c), g1 = *(const f32x4*)(g + c + 4), b0 = *(const f32x4*)(b + c), b1 = *(const f32x4*)(b + c + 4);
; #pragma unroll
;         for (int i = 0; i < NR; ++i) { const f32x4 y0 = v[i][j][0] * rstd[i] * g0 + b0, y1 = v[i][j][1] * rstd[i] * g1 + b1;
;             u32x4 w; w.x = cvt_pk_bf16(y0.x, y0.y); w.y = cvt_pk_bf16(y0.z, y0.w); w.z = cvt_pk_bf16(y1.x, y1.y); w.w = cvt_pk_bf16(y1.z, y1.w);
;             *(u32x4*)(h + (size_t)i * D + c) = w; }
;     }
	v_pk_add_f32 v[2:3], v[2:3], v[4:5]
	ds_bpermute_b32 v5, v149, v3
	ds_bpermute_b32 v4, v149, v2
	s_waitcnt lgkmcnt(0)
	v_pk_add_f32 v[2:3], v[2:3], v[4:5]
	ds_bpermute_b32 v5, v150, v3
	ds_bpermute_b32 v4, v150, v2
	s_waitcnt lgkmcnt(0)
	v_pk_add_f32 v[2:3], v[2:3], v[4:5]
	ds_bpermute_b32 v5, v151, v3
	ds_bpermute_b32 v4, v151, v2
	s_waitcnt lgkmcnt(0)
	v_pk_add_f32 v[2:3], v[2:3], v[4:5]
	s_nop 0
	v_pk_fma_f32 v[2:3], v[2:3], s[70:71], v[154:155] op_sel_hi:[1,0,0]
	s_nop 0
	v_mul_f32_e32 v1, 0x4b800000, v3
	v_cmp_gt_f32_e64 s[40:41], s73, v3
	v_cmp_gt_f32_e32 vcc, s73, v2
	s_nop 0
	v_cndmask_b32_e64 v1, v3, v1, s[40:41]
	v_rsq_f32_e32 v1, v1
	s_nop 0
	v_mul_f32_e32 v3, 0x45800000, v1
	v_cndmask_b32_e64 v112, v1, v3, s[40:41]
	v_mul_f32_e32 v1, 0x4b800000, v2
	v_cndmask_b32_e32 v1, v2, v1, vcc
	v_rsq_f32_e32 v1, v1
	v_pk_mul_f32 v[100:101], v[100:101], v[112:113] op_sel_hi:[1,0]
	v_mul_f32_e32 v2, 0x45800000, v1
	v_cndmask_b32_e32 v110, v1, v2, vcc
	ds_read_b128 v[2:5], v48 offset:16
	ds_read_b128 v[10:13], v48
	ds_read_b128 v[6:9], v48 offset:8208
	ds_read_b128 v[14:17], v48 offset:8192
	v_pk_mul_f32 v[32:33], v[32:33], v[110:111] op_sel_hi:[1,0]
	v_pk_mul_f32 v[30:31], v[30:31], v[110:111] op_sel_hi:[1,0]
	v_pk_mul_f32 v[24:25], v[24:25], v[110:111] op_sel_hi:[1,0]
	v_pk_mul_f32 v[20:21], v[20:21], v[110:111] op_sel_hi:[1,0]
	v_cmp_lt_i32_e32 vcc, s69, v46
	s_or_b64 s[20:21], vcc, s[20:21]
	s_waitcnt lgkmcnt(1)
	v_pk_fma_f32 v[126:127], v[2:3], v[126:127], v[6:7]
	s_waitcnt lgkmcnt(0)
	v_pk_fma_f32 v[128:129], v[12:13], v[128:129], v[16:17]
	v_pk_fma_f32 v[130:131], v[10:11], v[130:131], v[14:15]
	v_pk_fma_f32 v[152:153], v[4:5], v[124:125], v[8:9]
	v_cvt_pk_bf16_f32 v124, v130, v131
	v_cvt_pk_bf16_f32 v125, v128, v129
	v_cvt_pk_bf16_f32 v126, v126, v127
	v_pk_mul_f32 v[128:129], v[138:139], v[112:113] op_sel_hi:[1,0]
	v_cvt_pk_bf16_f32 v127, v152, v153
	global_store_dwordx4 v[68:69], v[124:127], off
	v_pk_mul_f32 v[130:131], v[134:135], v[112:113] op_sel_hi:[1,0]
	v_pk_fma_f32 v[128:129], v[2:3], v[128:129], v[6:7]
	v_pk_mul_f32 v[124:125], v[136:137], v[112:113] op_sel_hi:[1,0]
	v_pk_mul_f32 v[126:127], v[132:133], v[112:113] op_sel_hi:[1,0]
	v_pk_fma_f32 v[124:125], v[10:11], v[124:125], v[14:15]
	v_pk_fma_f32 v[126:127], v[12:13], v[126:127], v[16:17]
	v_pk_fma_f32 v[130:131], v[4:5], v[130:131], v[8:9]
	v_cvt_pk_bf16_f32 v124, v124, v125
	v_cvt_pk_bf16_f32 v125, v126, v127
	v_cvt_pk_bf16_f32 v126, v128, v129
	s_nop 0
	v_cvt_pk_bf16_f32 v127, v130, v131
	global_store_dwordx4 v[64:65], v[124:127], off
	s_nop 1
	v_pk_mul_f32 v[124:125], v[144:145], v[110:111] op_sel_hi:[1,0]
	v_pk_mul_f32 v[126:127], v[140:141], v[110:111] op_sel_hi:[1,0]
	v_pk_fma_f32 v[10:11], v[10:11], v[124:125], v[14:15]
	v_pk_fma_f32 v[12:13], v[12:13], v[126:127], v[16:17]
	v_pk_mul_f32 v[14:15], v[146:147], v[110:111] op_sel_hi:[1,0]
	v_pk_mul_f32 v[16:17], v[142:143], v[110:111] op_sel_hi:[1,0]
	s_nop 0
	v_pk_fma_f32 v[8:9], v[4:5], v[16:17], v[8:9]
	v_pk_fma_f32 v[4:5], v[2:3], v[14:15], v[6:7]
	v_cvt_pk_bf16_f32 v2, v10, v11
	v_cvt_pk_bf16_f32 v3, v12, v13
	s_nop 0
	v_cvt_pk_bf16_f32 v4, v4, v5
	v_cvt_pk_bf16_f32 v5, v8, v9
	global_store_dwordx4 v[66:67], v[2:5], off
	s_nop 1
	ds_read_b128 v[2:5], v48 offset:2064
	s_nop 0
	ds_read_b128 v[10:13], v48 offset:2048
	ds_read_b128 v[6:9], v48 offset:10256
	ds_read_b128 v[14:17], v48 offset:10240
	s_waitcnt lgkmcnt(1)
	v_pk_fma_f32 v[96:97], v[96:97], v[2:3], v[6:7]
	s_waitcnt lgkmcnt(0)
	v_pk_fma_f32 v[98:99], v[98:99], v[12:13], v[16:17]
	v_pk_fma_f32 v[122:123], v[122:123], v[10:11], v[14:15]
	v_pk_fma_f32 v[124:125], v[94:95], v[4:5], v[8:9]
	v_cvt_pk_bf16_f32 v94, v122, v123
	v_cvt_pk_bf16_f32 v95, v98, v99
	v_cvt_pk_bf16_f32 v96, v96, v97
	v_pk_mul_f32 v[98:99], v[102:103], v[112:113] op_sel_hi:[1,0]
	v_cvt_pk_bf16_f32 v97, v124, v125
	global_store_dwordx4 v[68:69], v[94:97], off offset:1024
	v_pk_fma_f32 v[100:101], v[100:101], v[4:5], v[8:9]
	v_pk_fma_f32 v[98:99], v[98:99], v[2:3], v[6:7]
	v_pk_mul_f32 v[94:95], v[106:107], v[112:113] op_sel_hi:[1,0]
	v_pk_mul_f32 v[96:97], v[104:105], v[112:113] op_sel_hi:[1,0]
	v_pk_fma_f32 v[94:95], v[94:95], v[10:11], v[14:15]
	v_pk_fma_f32 v[96:97], v[96:97], v[12:13], v[16:17]
	v_cvt_pk_bf16_f32 v94, v94, v95
	s_nop 0
	v_cvt_pk_bf16_f32 v95, v96, v97
	v_cvt_pk_bf16_f32 v96, v98, v99
	v_cvt_pk_bf16_f32 v97, v100, v101
	global_store_dwordx4 v[64:65], v[94:97], off offset:1024
	s_nop 1
	v_pk_mul_f32 v[94:95], v[120:121], v[110:111] op_sel_hi:[1,0]
	v_pk_mul_f32 v[96:97], v[118:119], v[110:111] op_sel_hi:[1,0]
	v_pk_fma_f32 v[10:11], v[94:95], v[10:11], v[14:15]
	v_pk_fma_f32 v[12:13], v[96:97], v[12:13], v[16:17]
	v_pk_mul_f32 v[14:15], v[116:117], v[110:111] op_sel_hi:[1,0]
	v_pk_mul_f32 v[16:17], v[114:115], v[110:111] op_sel_hi:[1,0]
	s_nop 0
	v_pk_fma_f32 v[8:9], v[16:17], v[4:5], v[8:9]
	v_pk_fma_f32 v[4:5], v[14:15], v[2:3], v[6:7]
	v_cvt_pk_bf16_f32 v2, v10, v11
	v_cvt_pk_bf16_f32 v3, v12, v13
	s_nop 0
	v_cvt_pk_bf16_f32 v4, v4, v5
	v_cvt_pk_bf16_f32 v5, v8, v9
	global_store_dwordx4 v[66:67], v[2:5], off offset:1024
	s_nop 1
	ds_read_b128 v[2:5], v48 offset:4112
	s_nop 0
	ds_read_b128 v[6:9], v48 offset:4096
	ds_read_b128 v[10:13], v48 offset:12304
	ds_read_b128 v[14:17], v48 offset:12288
	s_waitcnt lgkmcnt(1)
; __device__ __forceinline__ unsigned cvt_pk_bf16(float lo, float hi) { unsigned r; asm volatile("v_cvt_pk_bf16_f32 %0, %1, %2" : "=v"(r) : "v"(lo), "v"(hi)); return r; }
; template <int NR>
; __device__ __forceinline__ void ln_comb(bf16_t* h, const bf16_t* sb, float scale, const float* g, const float* b, int lane) {
;     ...
; #pragma unroll
;     for (int j = 0; j < 4; ++j) {
;         const int c = 8 * lane + 512 * j;
;         const f32x4 g0 = *(const f32x4*)(g + c), g1 = *(const f32x4*)(g + c + 4), b0 = *(const f32x4*)(b + c), b1 = *(const f32x4*)(b + c + 4);
; #pragma unroll
;         for (int i = 0; i < NR; ++i) { const f32x4 y0 = v[i][j][0] * rstd[i] * g0 + b0, y1 = v[i][j][1] * rstd[i] * g1 + b1;
;             u32x4 w; w.x = cvt_pk_bf16(y0.x, y0.y); w.y = cvt_pk_bf16(y0.z, y0.w); w.z = cvt_pk_bf16(y1.x, y1.y); w.w = cvt_pk_bf16(y1.z, y1.w);
;             *(u32x4*)(h + (size_t)i * D + c) = w; }
;     }
	v_pk_fma_f32 v[80:81], v[80:81], v[2:3], v[10:11]
	s_waitcnt lgkmcnt(0)
	v_pk_fma_f32 v[82:83], v[82:83], v[8:9], v[16:17]
	v_pk_fma_f32 v[84:85], v[84:85], v[6:7], v[14:15]
	v_pk_fma_f32 v[94:95], v[78:79], v[4:5], v[12:13]
	v_cvt_pk_bf16_f32 v78, v84, v85
	v_cvt_pk_bf16_f32 v79, v82, v83
	v_cvt_pk_bf16_f32 v80, v80, v81
	v_pk_mul_f32 v[84:85], v[86:87], v[112:113] op_sel_hi:[1,0]
	v_cvt_pk_bf16_f32 v81, v94, v95
	global_store_dwordx4 v[68:69], v[78:81], off offset:2048
	v_pk_mul_f32 v[82:83], v[88:89], v[112:113] op_sel_hi:[1,0]
	v_pk_fma_f32 v[84:85], v[84:85], v[4:5], v[12:13]
	v_pk_mul_f32 v[78:79], v[92:93], v[112:113] op_sel_hi:[1,0]
	v_pk_mul_f32 v[80:81], v[90:91], v[112:113] op_sel_hi:[1,0]
	v_pk_fma_f32 v[78:79], v[78:79], v[6:7], v[14:15]
	v_pk_fma_f32 v[80:81], v[80:81], v[8:9], v[16:17]
	v_pk_fma_f32 v[8:9], v[30:31], v[8:9], v[16:17]
	v_pk_fma_f32 v[6:7], v[32:33], v[6:7], v[14:15]
	v_pk_mul_f32 v[14:15], v[28:29], v[110:111] op_sel_hi:[1,0]
	v_pk_mul_f32 v[16:17], v[26:27], v[110:111] op_sel_hi:[1,0]
	v_pk_fma_f32 v[82:83], v[82:83], v[2:3], v[10:11]
	v_pk_fma_f32 v[12:13], v[16:17], v[4:5], v[12:13]
	v_pk_fma_f32 v[4:5], v[14:15], v[2:3], v[10:11]
	v_cvt_pk_bf16_f32 v78, v78, v79
	v_cvt_pk_bf16_f32 v79, v80, v81
	v_cvt_pk_bf16_f32 v80, v82, v83
	v_cvt_pk_bf16_f32 v81, v84, v85
	global_store_dwordx4 v[64:65], v[78:81], off offset:2048
	v_cvt_pk_bf16_f32 v2, v6, v7
	v_cvt_pk_bf16_f32 v3, v8, v9
	v_cvt_pk_bf16_f32 v4, v4, v5
	v_cvt_pk_bf16_f32 v5, v12, v13
	global_store_dwordx4 v[66:67], v[2:5], off offset:2048
	s_nop 1
	ds_read_b128 v[2:5], v48 offset:6160
	s_nop 0
	ds_read_b128 v[6:9], v48 offset:6144
	ds_read_b128 v[10:13], v48 offset:14352
	ds_read_b128 v[14:17], v48 offset:14336
	v_pk_mul_f32 v[26:27], v[76:77], v[108:109] op_sel_hi:[1,0]
	v_pk_mul_f32 v[28:29], v[72:73], v[108:109] op_sel_hi:[1,0]
	v_pk_mul_f32 v[30:31], v[74:75], v[108:109] op_sel_hi:[1,0]
	v_pk_mul_f32 v[32:33], v[70:71], v[108:109] op_sel_hi:[1,0]
	s_waitcnt lgkmcnt(1)
	v_pk_fma_f32 v[30:31], v[30:31], v[2:3], v[10:11]
	s_waitcnt lgkmcnt(0)
	v_pk_fma_f32 v[28:29], v[28:29], v[8:9], v[16:17]
	v_pk_fma_f32 v[26:27], v[26:27], v[6:7], v[14:15]
	v_pk_fma_f32 v[32:33], v[32:33], v[4:5], v[12:13]
	v_cvt_pk_bf16_f32 v26, v26, v27
	v_cvt_pk_bf16_f32 v27, v28, v29
	v_cvt_pk_bf16_f32 v28, v30, v31
	v_pk_mul_f32 v[30:31], v[38:39], v[112:113] op_sel_hi:[1,0]
	v_cvt_pk_bf16_f32 v29, v32, v33
	global_store_dwordx4 v[68:69], v[26:29], off offset:3072
	v_pk_mul_f32 v[32:33], v[34:35], v[112:113] op_sel_hi:[1,0]
	v_pk_fma_f32 v[30:31], v[30:31], v[2:3], v[10:11]
	v_pk_mul_f32 v[26:27], v[40:41], v[112:113] op_sel_hi:[1,0]
	v_pk_mul_f32 v[28:29], v[36:37], v[112:113] op_sel_hi:[1,0]
	v_pk_fma_f32 v[26:27], v[26:27], v[6:7], v[14:15]
	v_pk_fma_f32 v[28:29], v[28:29], v[8:9], v[16:17]
	v_pk_fma_f32 v[8:9], v[20:21], v[8:9], v[16:17]
	v_pk_fma_f32 v[6:7], v[24:25], v[6:7], v[14:15]
	v_pk_mul_f32 v[14:15], v[22:23], v[110:111] op_sel_hi:[1,0]
	v_pk_mul_f32 v[16:17], v[18:19], v[110:111] op_sel_hi:[1,0]
	v_pk_fma_f32 v[32:33], v[32:33], v[4:5], v[12:13]
	v_pk_fma_f32 v[12:13], v[16:17], v[4:5], v[12:13]
	v_pk_fma_f32 v[4:5], v[14:15], v[2:3], v[10:11]
	v_cvt_pk_bf16_f32 v26, v26, v27
	v_cvt_pk_bf16_f32 v27, v28, v29
	v_cvt_pk_bf16_f32 v28, v30, v31
	v_cvt_pk_bf16_f32 v29, v32, v33
	global_store_dwordx4 v[64:65], v[26:29], off offset:3072
	v_cvt_pk_bf16_f32 v2, v6, v7
	v_cvt_pk_bf16_f32 v3, v8, v9
	v_cvt_pk_bf16_f32 v4, v4, v5
	v_cvt_pk_bf16_f32 v5, v12, v13
	global_store_dwordx4 v[66:67], v[2:5], off offset:3072
	s_andn2_b64 exec, exec, s[20:21]
	s_cbranch_execnz .LBB0_347

; #define PG8_STAGE(bufoff, gbase, voff) do { _Pragma("unroll") for (int _i = 0; _i < 2; ++_i) \
;         __builtin_amdgcn_global_load_lds((const unsigned*)((const char*)(gbase) + (voff)[_i]), (LAS unsigned*)(lds + (bufoff) + ldsw + _i * 8192), 16, 0, 0); } while (0)
; #define PG8_LDA(dst, b, h) do { _Pragma("unroll") for (int m = 0; m < 4; ++m) _Pragma("unroll") for (int k = 0; k < 2; ++k) dst[m][k] = *(const LAS bf16x8*)(lds + PG8_SA(b, h) + aoff + m * 2048 + k * 1024); } while (0)
; #define PG8_LDB(dst, b, h) do { _Pragma("unroll") for (int n = 0; n < 2; ++n) _Pragma("unroll") for (int k = 0; k < 2; ++k) dst[n][k] = *(const LAS bf16x8*)(lds + PG8_SB(b, h) + boff + n * 2048 + k * 1024); } while (0)
; #define PG8_WAIT_V(n) asm volatile("s_waitcnt vmcnt(" #n ")" ::: "memory")
; #define PG8_WAIT_L(n) asm volatile("s_waitcnt lgkmcnt(" #n ")" ::: "memory")
; #define PG8_BAR __builtin_amdgcn_s_barrier()
; template <class Epi, class Sched = StaticOrder, bool ALIGN_EPI = true>
; __device__ __forceinline__ void gemm_phase(LAS unsigned char* lds, const Gemm g, const Sched& S, const Epi& E) {
;     ...
;         for (int t = 0; t < nt; t += 2) {
;             const bool last = (t == nt - 2);
;             const char* a1 = cA + (size_t)(t + 1) * kstep;
;             const char* a2 = last ? nA : cA + (size_t)(t + 2) * kstep; const char* b2 = last ? nB : cB + (size_t)(t + 2) * kstep;
;             const char* a3 = a2 + kstep; const char* b3 = b2 + kstep;
;             PG8_LDB(B0, 0, 0); PG8_LDB(B1, 0, 1); PG8_SCHED; PG8_LDA(At, 0, 0); PG8_STAGE(PG8_SA(1, 1), a1 + hstep, voffA);
;             PG8_WAIT_V(8); PG8_WAIT_L(0); PG8_BAR; PG8_MMA(0, 0, At, B0); PG8_MMA(0, 1, At, B1); PG8_BAR; PG8_SCHED;
;             PG8_LDA(At, 0, 1); PG8_STAGE(PG8_SB(0, 0), b2, voffB); PG8_STAGE(PG8_SB(0, 1), b2 + hstep, voffB); PG8_STAGE(PG8_SA(0, 0), a2, voffA);
;             PG8_WAIT_V(8); PG8_WAIT_L(0); PG8_BAR; PG8_MMA(1, 0, At, B0); PG8_MMA(1, 1, At, B1); PG8_BAR; PG8_SCHED;
;     ...
; #pragma unroll
;         for (int a = 0; a < 2; ++a)
; #pragma unroll
;             for (int b = 0; b < 2; ++b)
; #pragma unroll
;                 for (int m = 0; m < 4; ++m)
; #pragma unroll
;                     for (int n = 0; n < 2; ++n) acc[a][b][m][n] = (f32x4){0.f, 0.f, 0.f, 0.f};
;         cur = nxt; cA = nA; cB = nB; ++ui;
;         if constexpr (ALIGN_EPI) { if (wr == 1) PG8_BAR; }
.LBB0_369:
	s_add_u32 s79, s46, 0x100
	s_addc_u32 s92, s47, 0
	s_mov_b32 s82, -2
	s_cmp_eq_u32 s22, 1
	s_cbranch_scc1 .Lmy_nb_370
	s_cmp_eq_u64 s[12:13], 0
	s_cbranch_scc1 .Lmy_nb_370
	s_barrier
.Lmy_nb_370:
	s_add_u32 s46, s44, 0x100
	s_addc_u32 s47, s45, 0
	s_add_i32 s16, 0, 0x10000
	s_cmpk_eq_i32 s82, 0x54
	s_cselect_b32 s31, s37, s47
	s_cselect_b32 s30, s36, s46
	v_add_u32_e32 v142, s16, v144
	s_cselect_b32 s1, s43, s92
	s_cselect_b32 s0, s42, s79
	s_add_i32 s33, 0, 0x14000
	ds_read_b128 v[148:151], v142
	ds_read_b128 v[160:163], v142 offset:1024
	ds_read_b128 v[164:167], v142 offset:2048
	ds_read_b128 v[168:171], v142 offset:3072
	v_add_u32_e32 v142, s33, v144
	ds_read_b128 v[172:175], v142
	ds_read_b128 v[176:179], v142 offset:1024
	ds_read_b128 v[180:183], v142 offset:2048
	ds_read_b128 v[184:187], v142 offset:3072
	v_lshl_add_u64 v[142:143], s[44:45], 0, v[138:139]
	s_add_i32 m0, s6, 0xc000
	ds_read_b128 v[188:191], v146
	ds_read_b128 v[192:195], v146 offset:1024
	ds_read_b128 v[210:213], v146 offset:2048
	ds_read_b128 v[214:217], v146 offset:3072
	ds_read_b128 v[218:221], v146 offset:4096
	ds_read_b128 v[222:225], v146 offset:5120
	ds_read_b128 v[226:229], v146 offset:6144
	ds_read_b128 v[230:233], v146 offset:7168
	global_load_lds_dwordx4 v[142:143], off
	v_lshl_add_u64 v[142:143], s[44:45], 0, v[140:141]
	s_add_i32 m0, s6, 0xe000
	s_nop 0
	global_load_lds_dwordx4 v[142:143], off
	s_waitcnt vmcnt(8)
	s_waitcnt lgkmcnt(0)
	s_barrier
	s_setprio 1
	s_waitcnt lgkmcnt(0)
	v_mfma_f32_16x16x32_bf16 v[126:129], v[148:151], v[188:191], 0
	v_mfma_f32_16x16x32_bf16 v[122:125], v[164:167], v[188:191], 0
	v_mfma_f32_16x16x32_bf16 v[118:121], v[148:151], v[210:213], 0
	v_mfma_f32_16x16x32_bf16 v[110:113], v[164:167], v[210:213], 0
	v_mfma_f32_16x16x32_bf16 v[102:105], v[148:151], v[218:221], 0
	v_mfma_f32_16x16x32_bf16 v[94:97], v[164:167], v[218:221], 0
	v_mfma_f32_16x16x32_bf16 v[82:85], v[148:151], v[226:229], 0
	v_mfma_f32_16x16x32_bf16 v[74:77], v[164:167], v[226:229], 0
	v_mfma_f32_16x16x32_bf16 v[126:129], v[160:163], v[192:195], v[126:129]
	v_mfma_f32_16x16x32_bf16 v[122:125], v[168:171], v[192:195], v[122:125]
	v_mfma_f32_16x16x32_bf16 v[118:121], v[160:163], v[214:217], v[118:121]
	v_mfma_f32_16x16x32_bf16 v[110:113], v[168:171], v[214:217], v[110:113]
	v_mfma_f32_16x16x32_bf16 v[102:105], v[160:163], v[222:225], v[102:105]
	v_mfma_f32_16x16x32_bf16 v[94:97], v[168:171], v[222:225], v[94:97]
	v_mfma_f32_16x16x32_bf16 v[82:85], v[160:163], v[230:233], v[82:85]
	v_mfma_f32_16x16x32_bf16 v[74:77], v[168:171], v[230:233], v[74:77]
	s_setprio 0
	s_setprio 1
	v_mfma_f32_16x16x32_bf16 v[114:117], v[172:175], v[188:191], 0
	v_mfma_f32_16x16x32_bf16 v[106:109], v[180:183], v[188:191], 0
	v_mfma_f32_16x16x32_bf16 v[98:101], v[172:175], v[210:213], 0
	v_mfma_f32_16x16x32_bf16 v[90:93], v[180:183], v[210:213], 0
	v_mfma_f32_16x16x32_bf16 v[86:89], v[172:175], v[218:221], 0
	v_mfma_f32_16x16x32_bf16 v[78:81], v[180:183], v[218:221], 0
	v_mfma_f32_16x16x32_bf16 v[70:73], v[172:175], v[226:229], 0
	v_mfma_f32_16x16x32_bf16 v[66:69], v[180:183], v[226:229], 0
	v_mfma_f32_16x16x32_bf16 v[114:117], v[176:179], v[192:195], v[114:117]
	v_mfma_f32_16x16x32_bf16 v[106:109], v[184:187], v[192:195], v[106:109]
	v_mfma_f32_16x16x32_bf16 v[98:101], v[176:179], v[214:217], v[98:101]
	v_mfma_f32_16x16x32_bf16 v[90:93], v[184:187], v[214:217], v[90:93]
	v_mfma_f32_16x16x32_bf16 v[86:89], v[176:179], v[222:225], v[86:89]
	v_mfma_f32_16x16x32_bf16 v[78:81], v[184:187], v[222:225], v[78:81]
	v_mfma_f32_16x16x32_bf16 v[70:73], v[176:179], v[230:233], v[70:73]
	v_mfma_f32_16x16x32_bf16 v[66:69], v[184:187], v[230:233], v[66:69]
	s_setprio 0
	s_barrier
	s_add_i32 s16, s16, s4
	v_lshl_add_u64 v[142:143], s[0:1], 0, v[134:135]
	s_mov_b32 m0, s16
	ds_read_b128 v[188:191], v146 offset:16384
	ds_read_b128 v[192:195], v146 offset:17408
	ds_read_b128 v[210:213], v146 offset:18432
	ds_read_b128 v[214:217], v146 offset:19456
	ds_read_b128 v[218:221], v146 offset:20480
	ds_read_b128 v[222:225], v146 offset:21504
	ds_read_b128 v[226:229], v146 offset:22528
	ds_read_b128 v[230:233], v146 offset:23552
	global_load_lds_dwordx4 v[142:143], off
	s_add_i32 m0, s16, 0x2000
	s_add_u32 s16, s0, 0x160000
	v_lshl_add_u64 v[152:153], s[0:1], 0, v[130:131]
	s_addc_u32 s17, s1, 0
	s_add_i32 s33, s33, s4
	global_load_lds_dwordx4 v[152:153], off
	v_lshl_add_u64 v[196:197], s[16:17], 0, v[134:135]
	s_mov_b32 m0, s33
	v_lshl_add_u64 v[234:235], s[30:31], 0, v[132:133]
	global_load_lds_dwordx4 v[196:197], off
	v_lshl_add_u64 v[196:197], s[16:17], 0, v[130:131]
	s_add_i32 m0, s33, 0x2000
	s_nop 0
	global_load_lds_dwordx4 v[196:197], off
	v_lshl_add_u64 v[196:197], s[30:31], 0, v[136:137]
	s_mov_b32 m0, s6
	s_nop 0
	global_load_lds_dwordx4 v[196:197], off
	s_mov_b32 m0, s7
	s_nop 0
	global_load_lds_dwordx4 v[234:235], off
	s_waitcnt vmcnt(8)
	s_waitcnt lgkmcnt(0)
	s_barrier
; #define PG8_STAGE(bufoff, gbase, voff) do { _Pragma("unroll") for (int _i = 0; _i < 2; ++_i) \
;         __builtin_amdgcn_global_load_lds((const unsigned*)((const char*)(gbase) + (voff)[_i]), (LAS unsigned*)(lds + (bufoff) + ldsw + _i * 8192), 16, 0, 0); } while (0)
; #define PG8_LDA(dst, b, h) do { _Pragma("unroll") for (int m = 0; m < 4; ++m) _Pragma("unroll") for (int k = 0; k < 2; ++k) dst[m][k] = *(const LAS bf16x8*)(lds + PG8_SA(b, h) + aoff + m * 2048 + k * 1024); } while (0)
; #define PG8_LDB(dst, b, h) do { _Pragma("unroll") for (int n = 0; n < 2; ++n) _Pragma("unroll") for (int k = 0; k < 2; ++k) dst[n][k] = *(const LAS bf16x8*)(lds + PG8_SB(b, h) + boff + n * 2048 + k * 1024); } while (0)
; #define PG8_MMA(ai, bj, At, Bt) do { __builtin_amdgcn_s_setprio(1); _Pragma("unroll") for (int m = 0; m < 4; ++m) _Pragma("unroll") for (int n = 0; n < 2; ++n) _Pragma("unroll") for (int k = 0; k < 2; ++k) \
;         acc[ai][bj][m][n] = __builtin_amdgcn_mfma_f32_16x16x32_bf16(Bt[n][k], At[m][k], acc[ai][bj][m][n], 0, 0, 0); __builtin_amdgcn_s_setprio(0); } while (0)
; #define PG8_WAIT_V(n) asm volatile("s_waitcnt vmcnt(" #n ")" ::: "memory")
; #define PG8_WAIT_L(n) asm volatile("s_waitcnt lgkmcnt(" #n ")" ::: "memory")
; #define PG8_BAR __builtin_amdgcn_s_barrier()
; #define PG8_SCHED __builtin_amdgcn_sched_barrier(0)
; template <class Epi, class Sched = StaticOrder, bool ALIGN_EPI = true>
; __device__ __forceinline__ void gemm_phase(LAS unsigned char* lds, const Gemm g, const Sched& S, const Epi& E) {
;     ...
;             PG8_WAIT_V(8); PG8_WAIT_L(0); PG8_BAR; PG8_MMA(1, 0, At, B0); PG8_MMA(1, 1, At, B1); PG8_BAR; PG8_SCHED;
;             PG8_LDB(B0, 1, 0); PG8_LDB(B1, 1, 1); PG8_SCHED; PG8_LDA(At, 1, 0); PG8_STAGE(PG8_SA(0, 1), a2 + hstep, voffA);
;             PG8_WAIT_V(8); PG8_WAIT_L(0); PG8_BAR; PG8_MMA(0, 0, At, B0); PG8_MMA(0, 1, At, B1); PG8_BAR; PG8_SCHED;
	s_setprio 1
	s_waitcnt lgkmcnt(0)
	v_mfma_f32_16x16x32_bf16 v[62:65], v[148:151], v[188:191], 0
	v_mfma_f32_16x16x32_bf16 v[58:61], v[164:167], v[188:191], 0
	v_mfma_f32_16x16x32_bf16 v[54:57], v[148:151], v[210:213], 0
	v_mfma_f32_16x16x32_bf16 v[46:49], v[164:167], v[210:213], 0
	v_mfma_f32_16x16x32_bf16 v[38:41], v[148:151], v[218:221], 0
	v_mfma_f32_16x16x32_bf16 v[30:33], v[164:167], v[218:221], 0
	v_mfma_f32_16x16x32_bf16 v[22:25], v[148:151], v[226:229], 0
	v_mfma_f32_16x16x32_bf16 v[14:17], v[164:167], v[226:229], 0
	v_mfma_f32_16x16x32_bf16 v[62:65], v[160:163], v[192:195], v[62:65]
	v_mfma_f32_16x16x32_bf16 v[58:61], v[168:171], v[192:195], v[58:61]
	v_mfma_f32_16x16x32_bf16 v[54:57], v[160:163], v[214:217], v[54:57]
	v_mfma_f32_16x16x32_bf16 v[46:49], v[168:171], v[214:217], v[46:49]
	v_mfma_f32_16x16x32_bf16 v[38:41], v[160:163], v[222:225], v[38:41]
	v_mfma_f32_16x16x32_bf16 v[30:33], v[168:171], v[222:225], v[30:33]
	v_mfma_f32_16x16x32_bf16 v[22:25], v[160:163], v[230:233], v[22:25]
	v_mfma_f32_16x16x32_bf16 v[14:17], v[168:171], v[230:233], v[14:17]
	s_setprio 0
	s_setprio 1
	v_mfma_f32_16x16x32_bf16 v[50:53], v[172:175], v[188:191], 0
	v_mfma_f32_16x16x32_bf16 v[42:45], v[180:183], v[188:191], 0
	v_mfma_f32_16x16x32_bf16 v[34:37], v[172:175], v[210:213], 0
	v_mfma_f32_16x16x32_bf16 v[26:29], v[180:183], v[210:213], 0
	v_mfma_f32_16x16x32_bf16 v[18:21], v[172:175], v[218:221], 0
	v_mfma_f32_16x16x32_bf16 v[10:13], v[180:183], v[218:221], 0
	v_mfma_f32_16x16x32_bf16 v[6:9], v[172:175], v[226:229], 0
	v_mfma_f32_16x16x32_bf16 v[2:5], v[180:183], v[226:229], 0
	v_mfma_f32_16x16x32_bf16 v[50:53], v[176:179], v[192:195], v[50:53]
	v_mfma_f32_16x16x32_bf16 v[42:45], v[184:187], v[192:195], v[42:45]
	v_mfma_f32_16x16x32_bf16 v[34:37], v[176:179], v[214:217], v[34:37]
	v_mfma_f32_16x16x32_bf16 v[26:29], v[184:187], v[214:217], v[26:29]
	v_mfma_f32_16x16x32_bf16 v[18:21], v[176:179], v[222:225], v[18:21]
	v_mfma_f32_16x16x32_bf16 v[10:13], v[184:187], v[222:225], v[10:13]
	v_mfma_f32_16x16x32_bf16 v[6:9], v[176:179], v[230:233], v[6:9]
	v_mfma_f32_16x16x32_bf16 v[2:5], v[184:187], v[230:233], v[2:5]
	s_setprio 0
	s_barrier
	s_add_i32 s33, 0, 0x18000
	v_add_u32_e32 v147, s33, v144
	s_add_i32 s44, 0, 0x1c000
	ds_read_b128 v[148:151], v147
	ds_read_b128 v[160:163], v147 offset:1024
	ds_read_b128 v[164:167], v147 offset:2048
	ds_read_b128 v[168:171], v147 offset:3072
	v_add_u32_e32 v147, s44, v144
	ds_read_b128 v[172:175], v147
	ds_read_b128 v[176:179], v147 offset:1024
	ds_read_b128 v[180:183], v147 offset:2048
	ds_read_b128 v[184:187], v147 offset:3072
	s_add_u32 s16, s30, 0x160000
	s_addc_u32 s17, s31, 0
	s_mov_b32 m0, s8
	v_lshl_add_u64 v[236:237], s[16:17], 0, v[136:137]
	ds_read_b128 v[188:191], v146 offset:32768
	ds_read_b128 v[192:195], v146 offset:33792
	ds_read_b128 v[210:213], v146 offset:34816
	ds_read_b128 v[214:217], v146 offset:35840
	ds_read_b128 v[218:221], v146 offset:36864
	ds_read_b128 v[222:225], v146 offset:37888
	ds_read_b128 v[226:229], v146 offset:38912
	ds_read_b128 v[230:233], v146 offset:39936
	global_load_lds_dwordx4 v[236:237], off
	v_lshl_add_u64 v[236:237], s[16:17], 0, v[132:133]
	s_mov_b32 m0, s9
	s_nop 0
	global_load_lds_dwordx4 v[236:237], off
	s_waitcnt vmcnt(8)
	s_waitcnt lgkmcnt(0)
	s_barrier
	s_setprio 1
	s_waitcnt lgkmcnt(0)
	v_mfma_f32_16x16x32_bf16 v[126:129], v[148:151], v[188:191], v[126:129]
	v_mfma_f32_16x16x32_bf16 v[122:125], v[164:167], v[188:191], v[122:125]
	v_mfma_f32_16x16x32_bf16 v[118:121], v[148:151], v[210:213], v[118:121]
	v_mfma_f32_16x16x32_bf16 v[110:113], v[164:167], v[210:213], v[110:113]
	v_mfma_f32_16x16x32_bf16 v[102:105], v[148:151], v[218:221], v[102:105]
	v_mfma_f32_16x16x32_bf16 v[94:97], v[164:167], v[218:221], v[94:97]
	v_mfma_f32_16x16x32_bf16 v[82:85], v[148:151], v[226:229], v[82:85]
	v_mfma_f32_16x16x32_bf16 v[74:77], v[164:167], v[226:229], v[74:77]
	v_mfma_f32_16x16x32_bf16 v[126:129], v[160:163], v[192:195], v[126:129]
	v_mfma_f32_16x16x32_bf16 v[122:125], v[168:171], v[192:195], v[122:125]
	v_mfma_f32_16x16x32_bf16 v[118:121], v[160:163], v[214:217], v[118:121]
	v_mfma_f32_16x16x32_bf16 v[110:113], v[168:171], v[214:217], v[110:113]
	v_mfma_f32_16x16x32_bf16 v[102:105], v[160:163], v[222:225], v[102:105]
	v_mfma_f32_16x16x32_bf16 v[94:97], v[168:171], v[222:225], v[94:97]
	v_mfma_f32_16x16x32_bf16 v[82:85], v[160:163], v[230:233], v[82:85]
	v_mfma_f32_16x16x32_bf16 v[74:77], v[168:171], v[230:233], v[74:77]
	s_setprio 0
	s_setprio 1
	v_mfma_f32_16x16x32_bf16 v[114:117], v[172:175], v[188:191], v[114:117]
	v_mfma_f32_16x16x32_bf16 v[106:109], v[180:183], v[188:191], v[106:109]
	v_mfma_f32_16x16x32_bf16 v[98:101], v[172:175], v[210:213], v[98:101]
	v_mfma_f32_16x16x32_bf16 v[90:93], v[180:183], v[210:213], v[90:93]
	v_mfma_f32_16x16x32_bf16 v[86:89], v[172:175], v[218:221], v[86:89]
	v_mfma_f32_16x16x32_bf16 v[78:81], v[180:183], v[218:221], v[78:81]
	v_mfma_f32_16x16x32_bf16 v[70:73], v[172:175], v[226:229], v[70:73]
	v_mfma_f32_16x16x32_bf16 v[66:69], v[180:183], v[226:229], v[66:69]
	v_mfma_f32_16x16x32_bf16 v[114:117], v[176:179], v[192:195], v[114:117]
	v_mfma_f32_16x16x32_bf16 v[106:109], v[184:187], v[192:195], v[106:109]
	v_mfma_f32_16x16x32_bf16 v[98:101], v[176:179], v[214:217], v[98:101]
	v_mfma_f32_16x16x32_bf16 v[90:93], v[184:187], v[214:217], v[90:93]
	v_mfma_f32_16x16x32_bf16 v[86:89], v[176:179], v[222:225], v[86:89]
	v_mfma_f32_16x16x32_bf16 v[78:81], v[184:187], v[222:225], v[78:81]
	v_mfma_f32_16x16x32_bf16 v[70:73], v[176:179], v[230:233], v[70:73]
	v_mfma_f32_16x16x32_bf16 v[66:69], v[184:187], v[230:233], v[66:69]
	s_setprio 0
	s_barrier
; #define PG8_STAGE(bufoff, gbase, voff) do { _Pragma("unroll") for (int _i = 0; _i < 2; ++_i) \
;         __builtin_amdgcn_global_load_lds((const unsigned*)((const char*)(gbase) + (voff)[_i]), (LAS unsigned*)(lds + (bufoff) + ldsw + _i * 8192), 16, 0, 0); } while (0)
; #define PG8_LDA(dst, b, h) do { _Pragma("unroll") for (int m = 0; m < 4; ++m) _Pragma("unroll") for (int k = 0; k < 2; ++k) dst[m][k] = *(const LAS bf16x8*)(lds + PG8_SA(b, h) + aoff + m * 2048 + k * 1024); } while (0)
; #define PG8_MMA(ai, bj, At, Bt) do { __builtin_amdgcn_s_setprio(1); _Pragma("unroll") for (int m = 0; m < 4; ++m) _Pragma("unroll") for (int n = 0; n < 2; ++n) _Pragma("unroll") for (int k = 0; k < 2; ++k) \
;         acc[ai][bj][m][n] = __builtin_amdgcn_mfma_f32_16x16x32_bf16(Bt[n][k], At[m][k], acc[ai][bj][m][n], 0, 0, 0); __builtin_amdgcn_s_setprio(0); } while (0)
; #define PG8_WAIT_V(n) asm volatile("s_waitcnt vmcnt(" #n ")" ::: "memory")
; #define PG8_WAIT_L(n) asm volatile("s_waitcnt lgkmcnt(" #n ")" ::: "memory")
; #define PG8_BAR __builtin_amdgcn_s_barrier()
; #define PG8_SCHED __builtin_amdgcn_sched_barrier(0)
; template <class Epi, class Sched = StaticOrder, bool ALIGN_EPI = true>
; __device__ __forceinline__ void gemm_phase(LAS unsigned char* lds, const Gemm g, const Sched& S, const Epi& E) {
;     ...
;             PG8_LDA(At, 1, 1); PG8_STAGE(PG8_SB(1, 0), b3, voffB); PG8_STAGE(PG8_SB(1, 1), b3 + hstep, voffB); PG8_STAGE(PG8_SA(1, 0), a3, voffA);
;             PG8_WAIT_V(8); PG8_WAIT_L(0); PG8_BAR; PG8_MMA(1, 0, At, B0); PG8_MMA(1, 1, At, B1); PG8_BAR; PG8_SCHED;
;         }
	s_add_i32 s16, s33, s4
	v_lshl_add_u64 v[142:143], v[142:143], 0, s[34:35]
	s_mov_b32 m0, s16
	ds_read_b128 v[188:191], v146 offset:49152
	ds_read_b128 v[192:195], v146 offset:50176
	ds_read_b128 v[210:213], v146 offset:51200
	ds_read_b128 v[214:217], v146 offset:52224
	ds_read_b128 v[218:221], v146 offset:53248
	ds_read_b128 v[222:225], v146 offset:54272
	ds_read_b128 v[226:229], v146 offset:55296
	ds_read_b128 v[230:233], v146 offset:56320
	global_load_lds_dwordx4 v[142:143], off
	s_add_i32 m0, s16, 0x2000
	s_add_u32 s0, s0, 0x160080
	v_lshl_add_u64 v[142:143], v[152:153], 0, s[34:35]
	s_addc_u32 s1, s1, 0
	s_add_i32 s16, s44, s4
	global_load_lds_dwordx4 v[142:143], off
	v_lshl_add_u64 v[142:143], s[0:1], 0, v[134:135]
	s_mov_b32 m0, s16
	s_nop 0
	global_load_lds_dwordx4 v[142:143], off
	v_lshl_add_u64 v[142:143], s[0:1], 0, v[130:131]
	s_add_i32 m0, s16, 0x2000
	s_nop 0
	global_load_lds_dwordx4 v[142:143], off
	v_lshl_add_u64 v[142:143], v[196:197], 0, s[34:35]
	s_mov_b32 m0, s10
	s_nop 0
	global_load_lds_dwordx4 v[142:143], off
	v_lshl_add_u64 v[142:143], v[234:235], 0, s[34:35]
	s_mov_b32 m0, s11
	s_nop 0
	global_load_lds_dwordx4 v[142:143], off
	s_waitcnt vmcnt(8)
	s_waitcnt lgkmcnt(0)
	s_barrier
	s_setprio 1
	s_waitcnt lgkmcnt(0)
	v_mfma_f32_16x16x32_bf16 v[62:65], v[148:151], v[188:191], v[62:65]
	v_mfma_f32_16x16x32_bf16 v[58:61], v[164:167], v[188:191], v[58:61]
	v_mfma_f32_16x16x32_bf16 v[54:57], v[148:151], v[210:213], v[54:57]
	v_mfma_f32_16x16x32_bf16 v[46:49], v[164:167], v[210:213], v[46:49]
	v_mfma_f32_16x16x32_bf16 v[38:41], v[148:151], v[218:221], v[38:41]
	v_mfma_f32_16x16x32_bf16 v[30:33], v[164:167], v[218:221], v[30:33]
	v_mfma_f32_16x16x32_bf16 v[22:25], v[148:151], v[226:229], v[22:25]
	v_mfma_f32_16x16x32_bf16 v[14:17], v[164:167], v[226:229], v[14:17]
	v_mfma_f32_16x16x32_bf16 v[62:65], v[160:163], v[192:195], v[62:65]
	v_mfma_f32_16x16x32_bf16 v[58:61], v[168:171], v[192:195], v[58:61]
	v_mfma_f32_16x16x32_bf16 v[54:57], v[160:163], v[214:217], v[54:57]
	v_mfma_f32_16x16x32_bf16 v[46:49], v[168:171], v[214:217], v[46:49]
	v_mfma_f32_16x16x32_bf16 v[38:41], v[160:163], v[222:225], v[38:41]
	v_mfma_f32_16x16x32_bf16 v[30:33], v[168:171], v[222:225], v[30:33]
	v_mfma_f32_16x16x32_bf16 v[22:25], v[160:163], v[230:233], v[22:25]
	v_mfma_f32_16x16x32_bf16 v[14:17], v[168:171], v[230:233], v[14:17]
	s_setprio 0
	s_setprio 1
	v_mfma_f32_16x16x32_bf16 v[50:53], v[172:175], v[188:191], v[50:53]
	v_mfma_f32_16x16x32_bf16 v[42:45], v[180:183], v[188:191], v[42:45]
	v_mfma_f32_16x16x32_bf16 v[34:37], v[172:175], v[210:213], v[34:37]
	v_mfma_f32_16x16x32_bf16 v[26:29], v[180:183], v[210:213], v[26:29]
	v_mfma_f32_16x16x32_bf16 v[18:21], v[172:175], v[218:221], v[18:21]
	v_mfma_f32_16x16x32_bf16 v[10:13], v[180:183], v[218:221], v[10:13]
	v_mfma_f32_16x16x32_bf16 v[6:9], v[172:175], v[226:229], v[6:9]
	v_mfma_f32_16x16x32_bf16 v[2:5], v[180:183], v[226:229], v[2:5]
	v_mfma_f32_16x16x32_bf16 v[50:53], v[176:179], v[192:195], v[50:53]
	v_mfma_f32_16x16x32_bf16 v[42:45], v[184:187], v[192:195], v[42:45]
	v_mfma_f32_16x16x32_bf16 v[34:37], v[176:179], v[214:217], v[34:37]
	v_mfma_f32_16x16x32_bf16 v[26:29], v[184:187], v[214:217], v[26:29]
	v_mfma_f32_16x16x32_bf16 v[18:21], v[176:179], v[222:225], v[18:21]
	v_mfma_f32_16x16x32_bf16 v[10:13], v[184:187], v[222:225], v[10:13]
	v_mfma_f32_16x16x32_bf16 v[6:9], v[176:179], v[230:233], v[6:9]
	v_mfma_f32_16x16x32_bf16 v[2:5], v[184:187], v[230:233], v[2:5]
	s_setprio 0
	s_barrier
	s_add_i32 s82, s82, 2
	s_add_u32 s79, s79, 0x100
	s_addc_u32 s92, s92, 0
	s_cmpk_gt_u32 s82, 0x55
	s_mov_b64 s[44:45], s[46:47]
	s_cbranch_scc0 .LBB0_370

; __device__ __forceinline__ unsigned cvt_pk_bf16(float lo, float hi) { unsigned r; asm volatile("v_cvt_pk_bf16_f32 %0, %1, %2" : "=v"(r) : "v"(lo), "v"(hi)); return r; }
; #define PG8_BAR __builtin_amdgcn_s_barrier()
;     __device__ __forceinline__ void operator()(const f32x4 (&acc)[2][2][4][2], const Unit& u, int wr, int wc, int fr, int fq) const {
;         const int row0 = u.pm * BM + wr * 64 + fr, col0 = u.pn * BM + wc * 32 + 8 * fq;
; #pragma unroll
;         for (int ai = 0; ai < 2; ++ai)
; #pragma unroll
;             for (int m = 0; m < 4; ++m) { bf16_t* rowp = O + (size_t)(row0 + ai * HALF + m * 16) * ldc + col0;
; #pragma unroll
;                 for (int bj = 0; bj < 2; ++bj) { const f32x4 v0 = acc[ai][bj][m][0], v1 = acc[ai][bj][m][1];
;                     u32x4 w; w.x = cvt_pk_bf16(v0[0], v0[1]); w.y = cvt_pk_bf16(v0[2], v0[3]); w.z = cvt_pk_bf16(v1[0], v1[1]); w.w = cvt_pk_bf16(v1[2], v1[3]);
;                     *(u32x4*)(rowp + bj * HALF) = w; } }
;     }
; template <class Epi, class Sched = StaticOrder, bool ALIGN_EPI = true>
; __device__ __forceinline__ void gemm_phase(LAS unsigned char* lds, const Gemm g, const Sched& S, const Epi& E) {
;     ...
;         if constexpr (ALIGN_EPI) { if (wr == 0) PG8_BAR; }
;         E(acc, cur, wr, wc, fr, fq);
;         if (!has_next) break;
; #pragma unroll
;         for (int a = 0; a < 2; ++a)
; #pragma unroll
;             for (int b = 0; b < 2; ++b)
; #pragma unroll
;                 for (int m = 0; m < 4; ++m)
; #pragma unroll
;                     for (int n = 0; n < 2; ++n) acc[a][b][m][n] = (f32x4){0.f, 0.f, 0.f, 0.f};
;         cur = nxt; cA = nA; cB = nB; ++ui;
;         if constexpr (ALIGN_EPI) { if (wr == 1) PG8_BAR; }
.LBB0_373:
	v_lshl_add_u32 v148, s49, 8, v1
	v_lshl_or_b32 v142, s70, 8, v145
	v_ashrrev_i32_e32 v149, 31, v148
	v_readlane_b32 s84, v253, 58
	v_ashrrev_i32_e32 v143, 31, v142
	v_lshlrev_b64 v[150:151], 12, v[148:149]
	v_readlane_b32 s88, v253, 62
	v_readlane_b32 s89, v253, 63
	v_lshlrev_b64 v[152:153], 1, v[142:143]
	v_cvt_pk_bf16_f32 v126, v126, v127
	v_cvt_pk_bf16_f32 v127, v128, v129
	v_cvt_pk_bf16_f32 v128, v122, v123
	v_cvt_pk_bf16_f32 v129, v124, v125
	s_nop 0
	v_lshl_add_u64 v[150:151], s[88:89], 0, v[150:151]
	v_lshl_add_u64 v[142:143], v[150:151], 0, v[152:153]
	global_store_dwordx4 v[142:143], v[126:129], off
	v_cvt_pk_bf16_f32 v114, v114, v115
	v_cvt_pk_bf16_f32 v115, v116, v117
	v_cvt_pk_bf16_f32 v116, v106, v107
	v_or_b32_e32 v106, 16, v148
	v_ashrrev_i32_e32 v107, 31, v106
	v_lshlrev_b64 v[106:107], 12, v[106:107]
	v_lshl_add_u64 v[106:107], s[88:89], 0, v[106:107]
	v_cvt_pk_bf16_f32 v117, v108, v109
	global_store_dwordx4 v[142:143], v[114:117], off offset:256
	s_mov_b64 s[0:1], 0x80000
	v_readlane_b32 s82, v254, 41
	v_lshl_add_u64 v[114:115], v[106:107], 0, v[152:153]
	v_cvt_pk_bf16_f32 v106, v118, v119
	v_cvt_pk_bf16_f32 v107, v120, v121
	v_cvt_pk_bf16_f32 v108, v110, v111
	v_cvt_pk_bf16_f32 v109, v112, v113
	global_store_dwordx4 v[114:115], v[106:109], off
	v_cvt_pk_bf16_f32 v98, v98, v99
	v_cvt_pk_bf16_f32 v99, v100, v101
	v_cvt_pk_bf16_f32 v100, v90, v91
	v_or_b32_e32 v90, 32, v148
	v_ashrrev_i32_e32 v91, 31, v90
	v_lshlrev_b64 v[90:91], 12, v[90:91]
	v_lshl_add_u64 v[90:91], s[88:89], 0, v[90:91]
	v_cvt_pk_bf16_f32 v101, v92, v93
	global_store_dwordx4 v[114:115], v[98:101], off offset:256
	s_cmp_eq_u64 s[20:21], 0
	s_cbranch_scc1 .Lmy_al_370
	s_barrier
.Lmy_al_370:
	v_readlane_b32 s16, v254, 43
	s_mov_b32 s96, s82
	v_lshl_add_u64 v[98:99], v[90:91], 0, v[152:153]
	v_cvt_pk_bf16_f32 v90, v102, v103
	v_cvt_pk_bf16_f32 v91, v104, v105
	v_cvt_pk_bf16_f32 v92, v94, v95
	v_cvt_pk_bf16_f32 v93, v96, v97
	global_store_dwordx4 v[98:99], v[90:93], off
	v_cvt_pk_bf16_f32 v86, v86, v87
	v_cvt_pk_bf16_f32 v87, v88, v89
	v_cvt_pk_bf16_f32 v88, v78, v79
	v_or_b32_e32 v78, 48, v148
	v_ashrrev_i32_e32 v79, 31, v78
	v_lshlrev_b64 v[78:79], 12, v[78:79]
	v_lshl_add_u64 v[78:79], s[88:89], 0, v[78:79]
	v_cvt_pk_bf16_f32 v89, v80, v81
	global_store_dwordx4 v[98:99], v[86:89], off offset:256
	v_readlane_b32 s17, v254, 44
	s_movk_i32 s79, 0x4000
	v_lshl_add_u64 v[86:87], v[78:79], 0, v[152:153]
	v_cvt_pk_bf16_f32 v78, v82, v83
	v_cvt_pk_bf16_f32 v79, v84, v85
	v_cvt_pk_bf16_f32 v80, v74, v75
	v_cvt_pk_bf16_f32 v81, v76, v77
	global_store_dwordx4 v[86:87], v[78:81], off
	v_cvt_pk_bf16_f32 v70, v70, v71
	v_cvt_pk_bf16_f32 v71, v72, v73
	v_cvt_pk_bf16_f32 v72, v66, v67
	v_lshl_add_u64 v[66:67], v[142:143], 0, s[0:1]
	s_mov_b32 s0, 0x80000
	v_cvt_pk_bf16_f32 v73, v68, v69
	global_store_dwordx4 v[86:87], v[70:73], off offset:256
	v_cvt_pk_bf16_f32 v62, v62, v63
	v_cvt_pk_bf16_f32 v63, v64, v65
	v_cvt_pk_bf16_f32 v64, v58, v59
	v_add_co_u32_e32 v58, vcc, s0, v142
	v_cvt_pk_bf16_f32 v65, v60, v61
	s_mov_b64 s[0:1], 0x90000
	s_nop 0
	v_addc_co_u32_e32 v59, vcc, 0, v143, vcc
	global_store_dwordx4 v[58:59], v[62:65], off
	v_cvt_pk_bf16_f32 v50, v50, v51
	v_cvt_pk_bf16_f32 v51, v52, v53
	v_cvt_pk_bf16_f32 v52, v42, v43
	v_cvt_pk_bf16_f32 v53, v44, v45
	global_store_dwordx4 v[66:67], v[50:53], off offset:256
	v_cvt_pk_bf16_f32 v42, v54, v55
	v_cvt_pk_bf16_f32 v43, v56, v57
	v_cvt_pk_bf16_f32 v44, v46, v47
	v_cvt_pk_bf16_f32 v45, v48, v49
	v_readlane_b32 s85, v253, 59
	s_nop 0
	v_lshl_add_u64 v[50:51], v[142:143], 0, s[0:1]
	s_mov_b32 s0, 0x90000
	v_add_co_u32_e32 v46, vcc, s0, v142
	s_mov_b64 s[0:1], 0xa0000
	s_nop 0
	v_addc_co_u32_e32 v47, vcc, 0, v143, vcc
	global_store_dwordx4 v[46:47], v[42:45], off
	v_cvt_pk_bf16_f32 v34, v34, v35
	v_cvt_pk_bf16_f32 v35, v36, v37
	v_cvt_pk_bf16_f32 v36, v26, v27
	v_cvt_pk_bf16_f32 v37, v28, v29
	global_store_dwordx4 v[50:51], v[34:37], off offset:256
	v_cvt_pk_bf16_f32 v26, v38, v39
	v_cvt_pk_bf16_f32 v27, v40, v41
	v_cvt_pk_bf16_f32 v28, v30, v31
	v_cvt_pk_bf16_f32 v29, v32, v33
	v_readlane_b32 s86, v253, 60
	s_nop 0
	v_lshl_add_u64 v[34:35], v[142:143], 0, s[0:1]
	s_mov_b32 s0, 0xa0000
	v_add_co_u32_e32 v30, vcc, s0, v142
	s_mov_b64 s[0:1], 0xb0000
	s_nop 0
	v_addc_co_u32_e32 v31, vcc, 0, v143, vcc
	global_store_dwordx4 v[30:31], v[26:29], off
	v_cvt_pk_bf16_f32 v18, v18, v19
	v_cvt_pk_bf16_f32 v19, v20, v21
	v_cvt_pk_bf16_f32 v20, v10, v11
	v_cvt_pk_bf16_f32 v21, v12, v13
	global_store_dwordx4 v[34:35], v[18:21], off offset:256
	v_cvt_pk_bf16_f32 v10, v22, v23
	v_cvt_pk_bf16_f32 v11, v24, v25
	v_cvt_pk_bf16_f32 v12, v14, v15
	v_readlane_b32 s87, v253, 61
	v_readlane_b32 s90, v254, 0
	v_lshl_add_u64 v[18:19], v[142:143], 0, s[0:1]
	s_mov_b32 s0, 0xb0000
	v_add_co_u32_e32 v14, vcc, s0, v142
	s_mov_b64 s[0:1], -1
	s_nop 0
	v_addc_co_u32_e32 v15, vcc, 0, v143, vcc
	s_and_b64 vcc, exec, s[40:41]
	v_readlane_b32 s91, v254, 1
	v_cvt_pk_bf16_f32 v13, v16, v17
	global_store_dwordx4 v[14:15], v[10:13], off
	v_cvt_pk_bf16_f32 v6, v6, v7
	v_cvt_pk_bf16_f32 v7, v8, v9
	v_cvt_pk_bf16_f32 v8, v2, v3
	v_cvt_pk_bf16_f32 v9, v4, v5
	global_store_dwordx4 v[18:19], v[6:9], off offset:256
	v_readlane_b32 s83, v254, 42
	s_cbranch_vccnz .LBB0_362
	s_branch .LBB0_361

; #define PG8_STAGE(bufoff, gbase, voff) do { _Pragma("unroll") for (int _i = 0; _i < 2; ++_i) \
;         __builtin_amdgcn_global_load_lds((const unsigned*)((const char*)(gbase) + (voff)[_i]), (LAS unsigned*)(lds + (bufoff) + ldsw + _i * 8192), 16, 0, 0); } while (0)
; #define PG8_LDA(dst, b, h) do { _Pragma("unroll") for (int m = 0; m < 4; ++m) _Pragma("unroll") for (int k = 0; k < 2; ++k) dst[m][k] = *(const LAS bf16x8*)(lds + PG8_SA(b, h) + aoff + m * 2048 + k * 1024); } while (0)
; #define PG8_LDB(dst, b, h) do { _Pragma("unroll") for (int n = 0; n < 2; ++n) _Pragma("unroll") for (int k = 0; k < 2; ++k) dst[n][k] = *(const LAS bf16x8*)(lds + PG8_SB(b, h) + boff + n * 2048 + k * 1024); } while (0)
; #define PG8_WAIT_V(n) asm volatile("s_waitcnt vmcnt(" #n ")" ::: "memory")
; #define PG8_WAIT_L(n) asm volatile("s_waitcnt lgkmcnt(" #n ")" ::: "memory")
; #define PG8_BAR __builtin_amdgcn_s_barrier()
; template <class Epi, class Sched = StaticOrder, bool ALIGN_EPI = true>
; __device__ __forceinline__ void gemm_phase(LAS unsigned char* lds, const Gemm g, const Sched& S, const Epi& E) {
;     ...
;         for (int t = 0; t < nt; t += 2) {
;             const bool last = (t == nt - 2);
;             const char* a1 = cA + (size_t)(t + 1) * kstep;
;             const char* a2 = last ? nA : cA + (size_t)(t + 2) * kstep; const char* b2 = last ? nB : cB + (size_t)(t + 2) * kstep;
;             const char* a3 = a2 + kstep; const char* b3 = b2 + kstep;
;             PG8_LDB(B0, 0, 0); PG8_LDB(B1, 0, 1); PG8_SCHED; PG8_LDA(At, 0, 0); PG8_STAGE(PG8_SA(1, 1), a1 + hstep, voffA);
;             PG8_WAIT_V(8); PG8_WAIT_L(0); PG8_BAR; PG8_MMA(0, 0, At, B0); PG8_MMA(0, 1, At, B1); PG8_BAR; PG8_SCHED;
;             PG8_LDA(At, 0, 1); PG8_STAGE(PG8_SB(0, 0), b2, voffB); PG8_STAGE(PG8_SB(0, 1), b2 + hstep, voffB); PG8_STAGE(PG8_SA(0, 0), a2, voffA);
;             PG8_WAIT_V(8); PG8_WAIT_L(0); PG8_BAR; PG8_MMA(1, 0, At, B0); PG8_MMA(1, 1, At, B1); PG8_BAR; PG8_SCHED;
;     ...
; #pragma unroll
;         for (int a = 0; a < 2; ++a)
; #pragma unroll
;             for (int b = 0; b < 2; ++b)
; #pragma unroll
;                 for (int m = 0; m < 4; ++m)
; #pragma unroll
;                     for (int n = 0; n < 2; ++n) acc[a][b][m][n] = (f32x4){0.f, 0.f, 0.f, 0.f};
;         cur = nxt; cA = nA; cB = nB; ++ui;
;         if constexpr (ALIGN_EPI) { if (wr == 1) PG8_BAR; }
.LBB0_391:
	s_add_u32 s79, s0, 0x100
	s_addc_u32 s92, s1, 0
	s_mov_b32 s82, -2
	s_waitcnt vmcnt(0)
	s_waitcnt vmcnt(0)
	s_cmp_eq_u32 s22, 1
	s_cbranch_scc1 .Lmy_nb_392
	s_cmp_eq_u64 s[12:13], 0
	s_cbranch_scc1 .Lmy_nb_392
	s_barrier
.Lmy_nb_392:
	s_add_u32 s46, s44, 0x100
	s_addc_u32 s47, s45, 0
	s_add_i32 s16, 0, 0x10000
	s_cmpk_eq_i32 s82, 0x54
	s_cselect_b32 s31, s37, s47
	s_cselect_b32 s30, s36, s46
	v_add_u32_e32 v152, s16, v135
	s_cselect_b32 s1, s43, s92
	s_cselect_b32 s0, s42, s79
	s_add_i32 s33, 0, 0x14000
	ds_read_b128 v[140:143], v152
	ds_read_b128 v[144:147], v152 offset:1024
	ds_read_b128 v[148:151], v152 offset:2048
	ds_read_b128 v[160:163], v152 offset:3072
	v_add_u32_e32 v152, s33, v135
	ds_read_b128 v[164:167], v152
	ds_read_b128 v[172:175], v152 offset:1024
	ds_read_b128 v[176:179], v152 offset:2048
	ds_read_b128 v[180:183], v152 offset:3072
	v_lshl_add_u64 v[152:153], s[44:45], 0, v[136:137]
	s_add_i32 m0, s6, 0xc000
	ds_read_b128 v[184:187], v170
	ds_read_b128 v[188:191], v170 offset:1024
	ds_read_b128 v[192:195], v170 offset:2048
	ds_read_b128 v[210:213], v170 offset:3072
	ds_read_b128 v[214:217], v170 offset:4096
	ds_read_b128 v[218:221], v170 offset:5120
	ds_read_b128 v[222:225], v170 offset:6144
	ds_read_b128 v[226:229], v170 offset:7168
	global_load_lds_dwordx4 v[152:153], off
	v_lshl_add_u64 v[152:153], s[44:45], 0, v[138:139]
	s_add_i32 m0, s6, 0xe000
	s_nop 0
	global_load_lds_dwordx4 v[152:153], off
	s_waitcnt vmcnt(8)
	s_waitcnt lgkmcnt(0)
	s_barrier
	s_setprio 1
	s_waitcnt lgkmcnt(0)
	v_mfma_f32_16x16x32_bf16 v[126:129], v[140:143], v[184:187], 0
	v_mfma_f32_16x16x32_bf16 v[122:125], v[148:151], v[184:187], 0
	v_mfma_f32_16x16x32_bf16 v[118:121], v[140:143], v[192:195], 0
	v_mfma_f32_16x16x32_bf16 v[106:109], v[148:151], v[192:195], 0
	v_mfma_f32_16x16x32_bf16 v[98:101], v[140:143], v[214:217], 0
	v_mfma_f32_16x16x32_bf16 v[90:93], v[148:151], v[214:217], 0
	v_mfma_f32_16x16x32_bf16 v[82:85], v[140:143], v[222:225], 0
	v_mfma_f32_16x16x32_bf16 v[74:77], v[148:151], v[222:225], 0
	v_mfma_f32_16x16x32_bf16 v[126:129], v[144:147], v[188:191], v[126:129]
	v_mfma_f32_16x16x32_bf16 v[122:125], v[160:163], v[188:191], v[122:125]
	v_mfma_f32_16x16x32_bf16 v[118:121], v[144:147], v[210:213], v[118:121]
	v_mfma_f32_16x16x32_bf16 v[106:109], v[160:163], v[210:213], v[106:109]
	v_mfma_f32_16x16x32_bf16 v[98:101], v[144:147], v[218:221], v[98:101]
	v_mfma_f32_16x16x32_bf16 v[90:93], v[160:163], v[218:221], v[90:93]
	v_mfma_f32_16x16x32_bf16 v[82:85], v[144:147], v[226:229], v[82:85]
	v_mfma_f32_16x16x32_bf16 v[74:77], v[160:163], v[226:229], v[74:77]
	s_setprio 0
	s_setprio 1
	v_mfma_f32_16x16x32_bf16 v[114:117], v[164:167], v[184:187], 0
	v_mfma_f32_16x16x32_bf16 v[110:113], v[176:179], v[184:187], 0
	v_mfma_f32_16x16x32_bf16 v[102:105], v[164:167], v[192:195], 0
	v_mfma_f32_16x16x32_bf16 v[94:97], v[176:179], v[192:195], 0
	v_mfma_f32_16x16x32_bf16 v[86:89], v[164:167], v[214:217], 0
	v_mfma_f32_16x16x32_bf16 v[78:81], v[176:179], v[214:217], 0
	v_mfma_f32_16x16x32_bf16 v[70:73], v[164:167], v[222:225], 0
	v_mfma_f32_16x16x32_bf16 v[66:69], v[176:179], v[222:225], 0
	v_mfma_f32_16x16x32_bf16 v[114:117], v[172:175], v[188:191], v[114:117]
	v_mfma_f32_16x16x32_bf16 v[110:113], v[180:183], v[188:191], v[110:113]
	v_mfma_f32_16x16x32_bf16 v[102:105], v[172:175], v[210:213], v[102:105]
	v_mfma_f32_16x16x32_bf16 v[94:97], v[180:183], v[210:213], v[94:97]
	v_mfma_f32_16x16x32_bf16 v[86:89], v[172:175], v[218:221], v[86:89]
	v_mfma_f32_16x16x32_bf16 v[78:81], v[180:183], v[218:221], v[78:81]
	v_mfma_f32_16x16x32_bf16 v[70:73], v[172:175], v[226:229], v[70:73]
	v_mfma_f32_16x16x32_bf16 v[66:69], v[180:183], v[226:229], v[66:69]
	s_setprio 0
	s_barrier
	s_add_i32 s16, s16, s4
	v_lshl_add_u64 v[152:153], s[0:1], 0, v[132:133]
	s_mov_b32 m0, s16
	ds_read_b128 v[184:187], v170 offset:16384
	ds_read_b128 v[188:191], v170 offset:17408
	ds_read_b128 v[192:195], v170 offset:18432
	ds_read_b128 v[210:213], v170 offset:19456
	ds_read_b128 v[214:217], v170 offset:20480
	ds_read_b128 v[218:221], v170 offset:21504
	ds_read_b128 v[222:225], v170 offset:22528
	ds_read_b128 v[226:229], v170 offset:23552
	global_load_lds_dwordx4 v[152:153], off
	s_add_i32 m0, s16, 0x2000
	s_add_u32 s16, s0, 0x160000
	v_lshl_add_u64 v[168:169], s[0:1], 0, v[130:131]
	s_addc_u32 s17, s1, 0
	s_add_i32 s33, s33, s4
	global_load_lds_dwordx4 v[168:169], off
	v_lshl_add_u64 v[196:197], s[16:17], 0, v[132:133]
	s_mov_b32 m0, s33
	v_lshl_add_u64 v[230:231], s[30:31], 0, v[130:131]
	global_load_lds_dwordx4 v[196:197], off
	v_lshl_add_u64 v[196:197], s[16:17], 0, v[130:131]
	s_add_i32 m0, s33, 0x2000
	s_nop 0
	global_load_lds_dwordx4 v[196:197], off
	v_lshl_add_u64 v[196:197], s[30:31], 0, v[132:133]
	s_mov_b32 m0, s6
	s_nop 0
	global_load_lds_dwordx4 v[196:197], off
	s_mov_b32 m0, s7
	s_nop 0
	global_load_lds_dwordx4 v[230:231], off
	s_waitcnt vmcnt(8)
	s_waitcnt lgkmcnt(0)
	s_barrier
; #define PG8_STAGE(bufoff, gbase, voff) do { _Pragma("unroll") for (int _i = 0; _i < 2; ++_i) \
;         __builtin_amdgcn_global_load_lds((const unsigned*)((const char*)(gbase) + (voff)[_i]), (LAS unsigned*)(lds + (bufoff) + ldsw + _i * 8192), 16, 0, 0); } while (0)
; #define PG8_LDA(dst, b, h) do { _Pragma("unroll") for (int m = 0; m < 4; ++m) _Pragma("unroll") for (int k = 0; k < 2; ++k) dst[m][k] = *(const LAS bf16x8*)(lds + PG8_SA(b, h) + aoff + m * 2048 + k * 1024); } while (0)
; #define PG8_LDB(dst, b, h) do { _Pragma("unroll") for (int n = 0; n < 2; ++n) _Pragma("unroll") for (int k = 0; k < 2; ++k) dst[n][k] = *(const LAS bf16x8*)(lds + PG8_SB(b, h) + boff + n * 2048 + k * 1024); } while (0)
; #define PG8_MMA(ai, bj, At, Bt) do { __builtin_amdgcn_s_setprio(1); _Pragma("unroll") for (int m = 0; m < 4; ++m) _Pragma("unroll") for (int n = 0; n < 2; ++n) _Pragma("unroll") for (int k = 0; k < 2; ++k) \
;         acc[ai][bj][m][n] = __builtin_amdgcn_mfma_f32_16x16x32_bf16(Bt[n][k], At[m][k], acc[ai][bj][m][n], 0, 0, 0); __builtin_amdgcn_s_setprio(0); } while (0)
; #define PG8_WAIT_V(n) asm volatile("s_waitcnt vmcnt(" #n ")" ::: "memory")
; #define PG8_WAIT_L(n) asm volatile("s_waitcnt lgkmcnt(" #n ")" ::: "memory")
; #define PG8_BAR __builtin_amdgcn_s_barrier()
; #define PG8_SCHED __builtin_amdgcn_sched_barrier(0)
; template <class Epi, class Sched = StaticOrder, bool ALIGN_EPI = true>
; __device__ __forceinline__ void gemm_phase(LAS unsigned char* lds, const Gemm g, const Sched& S, const Epi& E) {
;     ...
;             PG8_WAIT_V(8); PG8_WAIT_L(0); PG8_BAR; PG8_MMA(1, 0, At, B0); PG8_MMA(1, 1, At, B1); PG8_BAR; PG8_SCHED;
;             PG8_LDB(B0, 1, 0); PG8_LDB(B1, 1, 1); PG8_SCHED; PG8_LDA(At, 1, 0); PG8_STAGE(PG8_SA(0, 1), a2 + hstep, voffA);
;             PG8_WAIT_V(8); PG8_WAIT_L(0); PG8_BAR; PG8_MMA(0, 0, At, B0); PG8_MMA(0, 1, At, B1); PG8_BAR; PG8_SCHED;
	s_setprio 1
	s_waitcnt lgkmcnt(0)
	v_mfma_f32_16x16x32_bf16 v[62:65], v[140:143], v[184:187], 0
	v_mfma_f32_16x16x32_bf16 v[58:61], v[148:151], v[184:187], 0
	v_mfma_f32_16x16x32_bf16 v[50:53], v[140:143], v[192:195], 0
	v_mfma_f32_16x16x32_bf16 v[42:45], v[148:151], v[192:195], 0
	v_mfma_f32_16x16x32_bf16 v[34:37], v[140:143], v[214:217], 0
	v_mfma_f32_16x16x32_bf16 v[26:29], v[148:151], v[214:217], 0
	v_mfma_f32_16x16x32_bf16 v[18:21], v[140:143], v[222:225], 0
	v_mfma_f32_16x16x32_bf16 v[10:13], v[148:151], v[222:225], 0
	v_mfma_f32_16x16x32_bf16 v[62:65], v[144:147], v[188:191], v[62:65]
	v_mfma_f32_16x16x32_bf16 v[58:61], v[160:163], v[188:191], v[58:61]
	v_mfma_f32_16x16x32_bf16 v[50:53], v[144:147], v[210:213], v[50:53]
	v_mfma_f32_16x16x32_bf16 v[42:45], v[160:163], v[210:213], v[42:45]
	v_mfma_f32_16x16x32_bf16 v[34:37], v[144:147], v[218:221], v[34:37]
	v_mfma_f32_16x16x32_bf16 v[26:29], v[160:163], v[218:221], v[26:29]
	v_mfma_f32_16x16x32_bf16 v[18:21], v[144:147], v[226:229], v[18:21]
	v_mfma_f32_16x16x32_bf16 v[10:13], v[160:163], v[226:229], v[10:13]
	s_setprio 0
	s_setprio 1
	v_mfma_f32_16x16x32_bf16 v[54:57], v[164:167], v[184:187], 0
	v_mfma_f32_16x16x32_bf16 v[46:49], v[176:179], v[184:187], 0
	v_mfma_f32_16x16x32_bf16 v[38:41], v[164:167], v[192:195], 0
	v_mfma_f32_16x16x32_bf16 v[30:33], v[176:179], v[192:195], 0
	v_mfma_f32_16x16x32_bf16 v[22:25], v[164:167], v[214:217], 0
	v_mfma_f32_16x16x32_bf16 v[14:17], v[176:179], v[214:217], 0
	v_mfma_f32_16x16x32_bf16 v[6:9], v[164:167], v[222:225], 0
	v_mfma_f32_16x16x32_bf16 v[2:5], v[176:179], v[222:225], 0
	v_mfma_f32_16x16x32_bf16 v[54:57], v[172:175], v[188:191], v[54:57]
	v_mfma_f32_16x16x32_bf16 v[46:49], v[180:183], v[188:191], v[46:49]
	v_mfma_f32_16x16x32_bf16 v[38:41], v[172:175], v[210:213], v[38:41]
	v_mfma_f32_16x16x32_bf16 v[30:33], v[180:183], v[210:213], v[30:33]
	v_mfma_f32_16x16x32_bf16 v[22:25], v[172:175], v[218:221], v[22:25]
	v_mfma_f32_16x16x32_bf16 v[14:17], v[180:183], v[218:221], v[14:17]
	v_mfma_f32_16x16x32_bf16 v[6:9], v[172:175], v[226:229], v[6:9]
	v_mfma_f32_16x16x32_bf16 v[2:5], v[180:183], v[226:229], v[2:5]
	s_setprio 0
	s_barrier
	s_add_i32 s33, 0, 0x18000
	s_add_i32 s44, 0, 0x1c000
	v_add_u32_e32 v160, s33, v135
	v_add_u32_e32 v171, s44, v135
	ds_read_b128 v[140:143], v160
	ds_read_b128 v[144:147], v160 offset:1024
	ds_read_b128 v[148:151], v160 offset:2048
	ds_read_b128 v[160:163], v160 offset:3072
	ds_read_b128 v[164:167], v171
	ds_read_b128 v[172:175], v171 offset:1024
	ds_read_b128 v[176:179], v171 offset:2048
	ds_read_b128 v[180:183], v171 offset:3072
	s_add_u32 s16, s30, 0x160000
	s_addc_u32 s17, s31, 0
	s_mov_b32 m0, s8
	v_lshl_add_u64 v[232:233], s[16:17], 0, v[132:133]
	ds_read_b128 v[184:187], v170 offset:32768
	ds_read_b128 v[188:191], v170 offset:33792
	ds_read_b128 v[192:195], v170 offset:34816
	ds_read_b128 v[210:213], v170 offset:35840
	ds_read_b128 v[214:217], v170 offset:36864
	ds_read_b128 v[218:221], v170 offset:37888
	ds_read_b128 v[222:225], v170 offset:38912
	ds_read_b128 v[226:229], v170 offset:39936
	global_load_lds_dwordx4 v[232:233], off
	v_lshl_add_u64 v[232:233], s[16:17], 0, v[130:131]
	s_mov_b32 m0, s9
	s_nop 0
	global_load_lds_dwordx4 v[232:233], off
	s_waitcnt vmcnt(8)
	s_waitcnt lgkmcnt(0)
	s_barrier
	s_setprio 1
	s_waitcnt lgkmcnt(0)
	v_mfma_f32_16x16x32_bf16 v[126:129], v[140:143], v[184:187], v[126:129]
	v_mfma_f32_16x16x32_bf16 v[122:125], v[148:151], v[184:187], v[122:125]
	v_mfma_f32_16x16x32_bf16 v[118:121], v[140:143], v[192:195], v[118:121]
	v_mfma_f32_16x16x32_bf16 v[106:109], v[148:151], v[192:195], v[106:109]
	v_mfma_f32_16x16x32_bf16 v[98:101], v[140:143], v[214:217], v[98:101]
	v_mfma_f32_16x16x32_bf16 v[90:93], v[148:151], v[214:217], v[90:93]
	v_mfma_f32_16x16x32_bf16 v[82:85], v[140:143], v[222:225], v[82:85]
	v_mfma_f32_16x16x32_bf16 v[74:77], v[148:151], v[222:225], v[74:77]
	v_mfma_f32_16x16x32_bf16 v[126:129], v[144:147], v[188:191], v[126:129]
	v_mfma_f32_16x16x32_bf16 v[122:125], v[160:163], v[188:191], v[122:125]
	v_mfma_f32_16x16x32_bf16 v[118:121], v[144:147], v[210:213], v[118:121]
	v_mfma_f32_16x16x32_bf16 v[106:109], v[160:163], v[210:213], v[106:109]
	v_mfma_f32_16x16x32_bf16 v[98:101], v[144:147], v[218:221], v[98:101]
	v_mfma_f32_16x16x32_bf16 v[90:93], v[160:163], v[218:221], v[90:93]
	v_mfma_f32_16x16x32_bf16 v[82:85], v[144:147], v[226:229], v[82:85]
	v_mfma_f32_16x16x32_bf16 v[74:77], v[160:163], v[226:229], v[74:77]
	s_setprio 0
	s_setprio 1
	v_mfma_f32_16x16x32_bf16 v[114:117], v[164:167], v[184:187], v[114:117]
	v_mfma_f32_16x16x32_bf16 v[110:113], v[176:179], v[184:187], v[110:113]
	v_mfma_f32_16x16x32_bf16 v[102:105], v[164:167], v[192:195], v[102:105]
	v_mfma_f32_16x16x32_bf16 v[94:97], v[176:179], v[192:195], v[94:97]
	v_mfma_f32_16x16x32_bf16 v[86:89], v[164:167], v[214:217], v[86:89]
	v_mfma_f32_16x16x32_bf16 v[78:81], v[176:179], v[214:217], v[78:81]
	v_mfma_f32_16x16x32_bf16 v[70:73], v[164:167], v[222:225], v[70:73]
	v_mfma_f32_16x16x32_bf16 v[66:69], v[176:179], v[222:225], v[66:69]
	v_mfma_f32_16x16x32_bf16 v[114:117], v[172:175], v[188:191], v[114:117]
	v_mfma_f32_16x16x32_bf16 v[110:113], v[180:183], v[188:191], v[110:113]
	v_mfma_f32_16x16x32_bf16 v[102:105], v[172:175], v[210:213], v[102:105]
	v_mfma_f32_16x16x32_bf16 v[94:97], v[180:183], v[210:213], v[94:97]
	v_mfma_f32_16x16x32_bf16 v[86:89], v[172:175], v[218:221], v[86:89]
	v_mfma_f32_16x16x32_bf16 v[78:81], v[180:183], v[218:221], v[78:81]
	v_mfma_f32_16x16x32_bf16 v[70:73], v[172:175], v[226:229], v[70:73]
	v_mfma_f32_16x16x32_bf16 v[66:69], v[180:183], v[226:229], v[66:69]
	s_setprio 0
	s_barrier
; #define PG8_STAGE(bufoff, gbase, voff) do { _Pragma("unroll") for (int _i = 0; _i < 2; ++_i) \
;         __builtin_amdgcn_global_load_lds((const unsigned*)((const char*)(gbase) + (voff)[_i]), (LAS unsigned*)(lds + (bufoff) + ldsw + _i * 8192), 16, 0, 0); } while (0)
; #define PG8_LDA(dst, b, h) do { _Pragma("unroll") for (int m = 0; m < 4; ++m) _Pragma("unroll") for (int k = 0; k < 2; ++k) dst[m][k] = *(const LAS bf16x8*)(lds + PG8_SA(b, h) + aoff + m * 2048 + k * 1024); } while (0)
; #define PG8_MMA(ai, bj, At, Bt) do { __builtin_amdgcn_s_setprio(1); _Pragma("unroll") for (int m = 0; m < 4; ++m) _Pragma("unroll") for (int n = 0; n < 2; ++n) _Pragma("unroll") for (int k = 0; k < 2; ++k) \
;         acc[ai][bj][m][n] = __builtin_amdgcn_mfma_f32_16x16x32_bf16(Bt[n][k], At[m][k], acc[ai][bj][m][n], 0, 0, 0); __builtin_amdgcn_s_setprio(0); } while (0)
; #define PG8_WAIT_V(n) asm volatile("s_waitcnt vmcnt(" #n ")" ::: "memory")
; #define PG8_WAIT_L(n) asm volatile("s_waitcnt lgkmcnt(" #n ")" ::: "memory")
; #define PG8_BAR __builtin_amdgcn_s_barrier()
; #define PG8_SCHED __builtin_amdgcn_sched_barrier(0)
; template <class Epi, class Sched = StaticOrder, bool ALIGN_EPI = true>
; __device__ __forceinline__ void gemm_phase(LAS unsigned char* lds, const Gemm g, const Sched& S, const Epi& E) {
;     ...
;             PG8_LDA(At, 1, 1); PG8_STAGE(PG8_SB(1, 0), b3, voffB); PG8_STAGE(PG8_SB(1, 1), b3 + hstep, voffB); PG8_STAGE(PG8_SA(1, 0), a3, voffA);
;             PG8_WAIT_V(8); PG8_WAIT_L(0); PG8_BAR; PG8_MMA(1, 0, At, B0); PG8_MMA(1, 1, At, B1); PG8_BAR; PG8_SCHED;
;         }
	s_add_i32 s16, s33, s4
	v_lshl_add_u64 v[152:153], v[152:153], 0, s[34:35]
	s_mov_b32 m0, s16
	ds_read_b128 v[184:187], v170 offset:49152
	ds_read_b128 v[188:191], v170 offset:50176
	ds_read_b128 v[192:195], v170 offset:51200
	ds_read_b128 v[210:213], v170 offset:52224
	ds_read_b128 v[214:217], v170 offset:53248
	ds_read_b128 v[218:221], v170 offset:54272
	ds_read_b128 v[222:225], v170 offset:55296
	ds_read_b128 v[226:229], v170 offset:56320
	global_load_lds_dwordx4 v[152:153], off
	s_add_i32 m0, s16, 0x2000
	s_add_u32 s0, s0, 0x160080
	v_lshl_add_u64 v[152:153], v[168:169], 0, s[34:35]
	s_addc_u32 s1, s1, 0
	s_add_i32 s16, s44, s4
	global_load_lds_dwordx4 v[152:153], off
	v_lshl_add_u64 v[152:153], s[0:1], 0, v[132:133]
	s_mov_b32 m0, s16
	s_nop 0
	global_load_lds_dwordx4 v[152:153], off
	v_lshl_add_u64 v[152:153], s[0:1], 0, v[130:131]
	s_add_i32 m0, s16, 0x2000
	s_nop 0
	global_load_lds_dwordx4 v[152:153], off
	v_lshl_add_u64 v[152:153], v[196:197], 0, s[34:35]
	s_mov_b32 m0, s10
	s_nop 0
	global_load_lds_dwordx4 v[152:153], off
	v_lshl_add_u64 v[152:153], v[230:231], 0, s[34:35]
	s_mov_b32 m0, s11
	s_nop 0
	global_load_lds_dwordx4 v[152:153], off
	s_waitcnt vmcnt(8)
	s_waitcnt lgkmcnt(0)
	s_barrier
	s_setprio 1
	s_waitcnt lgkmcnt(0)
	v_mfma_f32_16x16x32_bf16 v[62:65], v[140:143], v[184:187], v[62:65]
	v_mfma_f32_16x16x32_bf16 v[58:61], v[148:151], v[184:187], v[58:61]
	v_mfma_f32_16x16x32_bf16 v[50:53], v[140:143], v[192:195], v[50:53]
	v_mfma_f32_16x16x32_bf16 v[42:45], v[148:151], v[192:195], v[42:45]
	v_mfma_f32_16x16x32_bf16 v[34:37], v[140:143], v[214:217], v[34:37]
	v_mfma_f32_16x16x32_bf16 v[26:29], v[148:151], v[214:217], v[26:29]
	v_mfma_f32_16x16x32_bf16 v[18:21], v[140:143], v[222:225], v[18:21]
	v_mfma_f32_16x16x32_bf16 v[10:13], v[148:151], v[222:225], v[10:13]
	v_mfma_f32_16x16x32_bf16 v[62:65], v[144:147], v[188:191], v[62:65]
	v_mfma_f32_16x16x32_bf16 v[58:61], v[160:163], v[188:191], v[58:61]
	v_mfma_f32_16x16x32_bf16 v[50:53], v[144:147], v[210:213], v[50:53]
	v_mfma_f32_16x16x32_bf16 v[42:45], v[160:163], v[210:213], v[42:45]
	v_mfma_f32_16x16x32_bf16 v[34:37], v[144:147], v[218:221], v[34:37]
	v_mfma_f32_16x16x32_bf16 v[26:29], v[160:163], v[218:221], v[26:29]
	v_mfma_f32_16x16x32_bf16 v[18:21], v[144:147], v[226:229], v[18:21]
	v_mfma_f32_16x16x32_bf16 v[10:13], v[160:163], v[226:229], v[10:13]
	s_setprio 0
	s_setprio 1
	v_mfma_f32_16x16x32_bf16 v[54:57], v[164:167], v[184:187], v[54:57]
	v_mfma_f32_16x16x32_bf16 v[46:49], v[176:179], v[184:187], v[46:49]
	v_mfma_f32_16x16x32_bf16 v[38:41], v[164:167], v[192:195], v[38:41]
	v_mfma_f32_16x16x32_bf16 v[30:33], v[176:179], v[192:195], v[30:33]
	v_mfma_f32_16x16x32_bf16 v[22:25], v[164:167], v[214:217], v[22:25]
	v_mfma_f32_16x16x32_bf16 v[14:17], v[176:179], v[214:217], v[14:17]
	v_mfma_f32_16x16x32_bf16 v[6:9], v[164:167], v[222:225], v[6:9]
	v_mfma_f32_16x16x32_bf16 v[2:5], v[176:179], v[222:225], v[2:5]
	v_mfma_f32_16x16x32_bf16 v[54:57], v[172:175], v[188:191], v[54:57]
	v_mfma_f32_16x16x32_bf16 v[46:49], v[180:183], v[188:191], v[46:49]
	v_mfma_f32_16x16x32_bf16 v[38:41], v[172:175], v[210:213], v[38:41]
	v_mfma_f32_16x16x32_bf16 v[30:33], v[180:183], v[210:213], v[30:33]
	v_mfma_f32_16x16x32_bf16 v[22:25], v[172:175], v[218:221], v[22:25]
	v_mfma_f32_16x16x32_bf16 v[14:17], v[180:183], v[218:221], v[14:17]
	v_mfma_f32_16x16x32_bf16 v[6:9], v[172:175], v[226:229], v[6:9]
	v_mfma_f32_16x16x32_bf16 v[2:5], v[180:183], v[226:229], v[2:5]
	s_setprio 0
	s_barrier
	s_add_i32 s82, s82, 2
	s_add_u32 s79, s79, 0x100
	s_addc_u32 s92, s92, 0
	s_cmpk_gt_u32 s82, 0x55
	s_mov_b64 s[44:45], s[46:47]
	s_cbranch_scc0 .LBB0_392

; __device__ __forceinline__ float bf_lo(unsigned w) { return __uint_as_float(w << 16); }
; __device__ __forceinline__ float bf_hi(unsigned w) { return __uint_as_float(w & 0xffff0000u); }
; #define PG8_BAR __builtin_amdgcn_s_barrier()
;     __device__ __forceinline__ void operator()(const f32x4 (&acc)[2][2][4][2], const Unit& u, int wr, int wc, int fr, int fq) const {
;         const size_t off0 = (size_t)(u.pm * BM + wr * 64 + fr) * D + u.pn * BM + wc * 32 + 4 * fq;
; #pragma unroll
;         for (int ai = 0; ai < 2; ++ai) {
;             u32x2 hv[4][2][2];
; #pragma unroll
;             for (int m = 0; m < 4; ++m)
; #pragma unroll
;                 for (int bj = 0; bj < 2; ++bj)
; #pragma unroll
;                     for (int n = 0; n < 2; ++n) hv[m][bj][n] = *(const u32x2*)(H + off0 + (size_t)(ai * HALF + m * 16) * D + bj * HALF + n * 16);
; #pragma unroll
;             for (int m = 0; m < 4; ++m)
; #pragma unroll
;                 for (int bj = 0; bj < 2; ++bj)
; #pragma unroll
;                     for (int n = 0; n < 2; ++n) { const u32x2 w = hv[m][bj][n]; const f32x4 h4 = {bf_lo(w.x), bf_hi(w.x), bf_lo(w.y), bf_hi(w.y)};
;                         *(f32x4*)(Z + off0 + (size_t)(ai * HALF + m * 16) * D + bj * HALF + n * 16) = h4 * ALPHA + acc[ai][bj][m][n] * 0.5f; }
; template <class Epi, class Sched = StaticOrder, bool ALIGN_EPI = true>
; __device__ __forceinline__ void gemm_phase(LAS unsigned char* lds, const Gemm g, const Sched& S, const Epi& E) {
;     ...
;         if constexpr (ALIGN_EPI) { if (wr == 0) PG8_BAR; }
.LBB0_395:
	v_lshl_add_u32 v140, s49, 8, v1
	v_ashrrev_i32_e32 v141, 31, v140
	s_lshl_b32 s0, s70, 8
	v_lshlrev_b64 v[140:141], 11, v[140:141]
	s_ashr_i32 s1, s0, 31
	v_lshl_add_u64 v[176:177], v[140:141], 0, s[0:1]
	v_readlane_b32 s0, v252, 0
	v_or_b32_e32 v176, v176, v134
	v_readlane_b32 s1, v252, 1
	v_readlane_b32 s84, v253, 58
	v_readlane_b32 s88, v253, 62
	v_lshl_add_u64 v[140:141], v[176:177], 1, s[0:1]
	global_load_dwordx2 v[172:173], v[140:141], off
	global_load_dwordx2 v[178:179], v[140:141], off offset:32
	global_load_dwordx2 v[180:181], v[140:141], off offset:256
	global_load_dwordx2 v[182:183], v[140:141], off offset:288
	s_mov_b32 s0, 0x10000
	v_add_co_u32_e32 v142, vcc, s0, v140
	s_mov_b32 s1, 0x20000
	s_nop 0
	v_addc_co_u32_e32 v143, vcc, 0, v141, vcc
	global_load_dwordx2 v[184:185], v[142:143], off
	global_load_dwordx2 v[168:169], v[142:143], off offset:32
	global_load_dwordx2 v[166:167], v[142:143], off offset:256
	global_load_dwordx2 v[164:165], v[142:143], off offset:288
	v_add_co_u32_e32 v142, vcc, s1, v140
	s_mov_b32 s0, 0x30000
	s_nop 0
	v_addc_co_u32_e32 v143, vcc, 0, v141, vcc
	global_load_dwordx2 v[162:163], v[142:143], off
	global_load_dwordx2 v[160:161], v[142:143], off offset:32
	global_load_dwordx2 v[152:153], v[142:143], off offset:256
	global_load_dwordx2 v[150:151], v[142:143], off offset:288
	v_add_co_u32_e32 v142, vcc, s0, v140
	v_readlane_b32 s89, v253, 63
	s_nop 0
	v_addc_co_u32_e32 v143, vcc, 0, v141, vcc
	global_load_dwordx2 v[148:149], v[142:143], off
	global_load_dwordx2 v[146:147], v[142:143], off offset:32
	global_load_dwordx2 v[144:145], v[142:143], off offset:256
	s_nop 0
	global_load_dwordx2 v[142:143], v[142:143], off offset:288
	s_cmp_eq_u64 s[20:21], 0
	s_cbranch_scc1 .Lmy_al_392
	s_barrier
.Lmy_al_392:
	s_mov_b32 s0, 0x40000
	v_readlane_b32 s82, v254, 41
	s_mov_b32 s96, s82
	s_movk_i32 s79, 0x4000
	v_readlane_b32 s85, v253, 59
	v_readlane_b32 s86, v253, 60
	v_readlane_b32 s87, v253, 61
	v_readlane_b32 s90, v254, 0
	v_readlane_b32 s91, v254, 1
	v_readlane_b32 s83, v254, 42
	s_waitcnt vmcnt(0)
	v_lshlrev_b32_e32 v174, 16, v172
	v_and_b32_e32 v175, 0xffff0000, v172
	v_lshlrev_b32_e32 v172, 16, v173
	v_and_b32_e32 v173, 0xffff0000, v173
	v_pk_mul_f32 v[186:187], v[174:175], s[24:25] op_sel_hi:[1,0]
	v_pk_mul_f32 v[172:173], v[172:173], s[24:25] op_sel_hi:[1,0]
	s_nop 0
	v_pk_fma_f32 v[174:175], v[128:129], 0.5, v[172:173] op_sel_hi:[1,0,1]
	v_pk_fma_f32 v[172:173], v[126:127], 0.5, v[186:187] op_sel_hi:[1,0,1]
	v_lshl_add_u64 v[126:127], v[176:177], 2, s[88:89]
	global_store_dwordx4 v[126:127], v[172:175], off
	v_lshlrev_b32_e32 v128, 16, v178
	v_and_b32_e32 v129, 0xffff0000, v178
	v_lshlrev_b32_e32 v172, 16, v179
	v_and_b32_e32 v173, 0xffff0000, v179
	v_pk_mul_f32 v[128:129], v[128:129], s[24:25] op_sel_hi:[1,0]
	v_pk_mul_f32 v[172:173], v[172:173], s[24:25] op_sel_hi:[1,0]
	v_pk_fma_f32 v[122:123], v[122:123], 0.5, v[128:129] op_sel_hi:[1,0,1]
	v_pk_fma_f32 v[124:125], v[124:125], 0.5, v[172:173] op_sel_hi:[1,0,1]
	global_store_dwordx4 v[126:127], v[122:125], off offset:64
	s_nop 1
	v_lshlrev_b32_e32 v122, 16, v180
	v_and_b32_e32 v123, 0xffff0000, v180
	v_lshlrev_b32_e32 v124, 16, v181
	v_and_b32_e32 v125, 0xffff0000, v181
	v_pk_mul_f32 v[122:123], v[122:123], s[24:25] op_sel_hi:[1,0]
	v_pk_mul_f32 v[124:125], v[124:125], s[24:25] op_sel_hi:[1,0]
	v_pk_fma_f32 v[114:115], v[114:115], 0.5, v[122:123] op_sel_hi:[1,0,1]
	v_pk_fma_f32 v[116:117], v[116:117], 0.5, v[124:125] op_sel_hi:[1,0,1]
	global_store_dwordx4 v[126:127], v[114:117], off offset:512
	s_nop 1
	v_lshlrev_b32_e32 v114, 16, v182
	v_and_b32_e32 v115, 0xffff0000, v182
	v_lshlrev_b32_e32 v116, 16, v183
	v_and_b32_e32 v117, 0xffff0000, v183
	v_pk_mul_f32 v[114:115], v[114:115], s[24:25] op_sel_hi:[1,0]
	v_pk_mul_f32 v[116:117], v[116:117], s[24:25] op_sel_hi:[1,0]
	v_pk_fma_f32 v[110:111], v[110:111], 0.5, v[114:115] op_sel_hi:[1,0,1]
	v_pk_fma_f32 v[112:113], v[112:113], 0.5, v[116:117] op_sel_hi:[1,0,1]
	global_store_dwordx4 v[126:127], v[110:113], off offset:576
	s_nop 1
	v_lshlrev_b32_e32 v110, 16, v184
	v_and_b32_e32 v111, 0xffff0000, v184
	v_lshlrev_b32_e32 v112, 16, v185
	v_and_b32_e32 v113, 0xffff0000, v185
	v_pk_mul_f32 v[110:111], v[110:111], s[24:25] op_sel_hi:[1,0]
	v_pk_mul_f32 v[112:113], v[112:113], s[24:25] op_sel_hi:[1,0]
	s_nop 0
	v_pk_fma_f32 v[114:115], v[120:121], 0.5, v[112:113] op_sel_hi:[1,0,1]
	v_pk_fma_f32 v[112:113], v[118:119], 0.5, v[110:111] op_sel_hi:[1,0,1]
	v_add_co_u32_e32 v110, vcc, s1, v126
	s_nop 1
	v_addc_co_u32_e32 v111, vcc, 0, v127, vcc
	global_store_dwordx4 v[110:111], v[112:115], off
	s_nop 1
	v_lshlrev_b32_e32 v112, 16, v168
	v_and_b32_e32 v113, 0xffff0000, v168
	v_lshlrev_b32_e32 v114, 16, v169
	v_and_b32_e32 v115, 0xffff0000, v169
	v_pk_mul_f32 v[112:113], v[112:113], s[24:25] op_sel_hi:[1,0]
	v_pk_mul_f32 v[114:115], v[114:115], s[24:25] op_sel_hi:[1,0]
	v_pk_fma_f32 v[106:107], v[106:107], 0.5, v[112:113] op_sel_hi:[1,0,1]
	v_pk_fma_f32 v[108:109], v[108:109], 0.5, v[114:115] op_sel_hi:[1,0,1]
	global_store_dwordx4 v[110:111], v[106:109], off offset:64
	s_nop 1
	v_lshlrev_b32_e32 v106, 16, v166
	v_and_b32_e32 v107, 0xffff0000, v166
	v_lshlrev_b32_e32 v108, 16, v167
	v_and_b32_e32 v109, 0xffff0000, v167
	v_pk_mul_f32 v[106:107], v[106:107], s[24:25] op_sel_hi:[1,0]
	v_pk_mul_f32 v[108:109], v[108:109], s[24:25] op_sel_hi:[1,0]
	v_pk_fma_f32 v[102:103], v[102:103], 0.5, v[106:107] op_sel_hi:[1,0,1]
	v_pk_fma_f32 v[104:105], v[104:105], 0.5, v[108:109] op_sel_hi:[1,0,1]
	global_store_dwordx4 v[110:111], v[102:105], off offset:512
	s_nop 1
	v_lshlrev_b32_e32 v102, 16, v164
; __device__ __forceinline__ float bf_lo(unsigned w) { return __uint_as_float(w << 16); }
; __device__ __forceinline__ float bf_hi(unsigned w) { return __uint_as_float(w & 0xffff0000u); }
;     __device__ __forceinline__ void operator()(const f32x4 (&acc)[2][2][4][2], const Unit& u, int wr, int wc, int fr, int fq) const {
;     ...
;                     for (int n = 0; n < 2; ++n) hv[m][bj][n] = *(const u32x2*)(H + off0 + (size_t)(ai * HALF + m * 16) * D + bj * HALF + n * 16);
; #pragma unroll
;             for (int m = 0; m < 4; ++m)
; #pragma unroll
;                 for (int bj = 0; bj < 2; ++bj)
; #pragma unroll
;                     for (int n = 0; n < 2; ++n) { const u32x2 w = hv[m][bj][n]; const f32x4 h4 = {bf_lo(w.x), bf_hi(w.x), bf_lo(w.y), bf_hi(w.y)};
;                         *(f32x4*)(Z + off0 + (size_t)(ai * HALF + m * 16) * D + bj * HALF + n * 16) = h4 * ALPHA + acc[ai][bj][m][n] * 0.5f; }
	v_and_b32_e32 v103, 0xffff0000, v164
	v_lshlrev_b32_e32 v104, 16, v165
	v_and_b32_e32 v105, 0xffff0000, v165
	v_pk_mul_f32 v[102:103], v[102:103], s[24:25] op_sel_hi:[1,0]
	v_pk_mul_f32 v[104:105], v[104:105], s[24:25] op_sel_hi:[1,0]
	v_pk_fma_f32 v[94:95], v[94:95], 0.5, v[102:103] op_sel_hi:[1,0,1]
	v_pk_fma_f32 v[96:97], v[96:97], 0.5, v[104:105] op_sel_hi:[1,0,1]
	global_store_dwordx4 v[110:111], v[94:97], off offset:576
	s_nop 1
	v_lshlrev_b32_e32 v94, 16, v162
	v_and_b32_e32 v95, 0xffff0000, v162
	v_lshlrev_b32_e32 v96, 16, v163
	v_and_b32_e32 v97, 0xffff0000, v163
	v_pk_mul_f32 v[94:95], v[94:95], s[24:25] op_sel_hi:[1,0]
	v_pk_mul_f32 v[96:97], v[96:97], s[24:25] op_sel_hi:[1,0]
	v_pk_fma_f32 v[94:95], v[98:99], 0.5, v[94:95] op_sel_hi:[1,0,1]
	v_add_co_u32_e32 v98, vcc, s0, v126
	v_pk_fma_f32 v[96:97], v[100:101], 0.5, v[96:97] op_sel_hi:[1,0,1]
	s_nop 0
	v_addc_co_u32_e32 v99, vcc, 0, v127, vcc
	global_store_dwordx4 v[98:99], v[94:97], off
	s_mov_b32 s0, 0x60000
	s_nop 0
	v_lshlrev_b32_e32 v94, 16, v160
	v_and_b32_e32 v95, 0xffff0000, v160
	v_lshlrev_b32_e32 v96, 16, v161
	v_and_b32_e32 v97, 0xffff0000, v161
	v_pk_mul_f32 v[94:95], v[94:95], s[24:25] op_sel_hi:[1,0]
	v_pk_mul_f32 v[96:97], v[96:97], s[24:25] op_sel_hi:[1,0]
	v_pk_fma_f32 v[90:91], v[90:91], 0.5, v[94:95] op_sel_hi:[1,0,1]
	v_pk_fma_f32 v[92:93], v[92:93], 0.5, v[96:97] op_sel_hi:[1,0,1]
	global_store_dwordx4 v[98:99], v[90:93], off offset:64
	s_nop 1
	v_lshlrev_b32_e32 v90, 16, v152
	v_and_b32_e32 v91, 0xffff0000, v152
	v_lshlrev_b32_e32 v92, 16, v153
	v_and_b32_e32 v93, 0xffff0000, v153
	v_pk_mul_f32 v[90:91], v[90:91], s[24:25] op_sel_hi:[1,0]
	v_pk_mul_f32 v[92:93], v[92:93], s[24:25] op_sel_hi:[1,0]
	v_pk_fma_f32 v[86:87], v[86:87], 0.5, v[90:91] op_sel_hi:[1,0,1]
	v_pk_fma_f32 v[88:89], v[88:89], 0.5, v[92:93] op_sel_hi:[1,0,1]
	global_store_dwordx4 v[98:99], v[86:89], off offset:512
	s_nop 1
	v_lshlrev_b32_e32 v86, 16, v150
	v_and_b32_e32 v87, 0xffff0000, v150
	v_lshlrev_b32_e32 v88, 16, v151
	v_and_b32_e32 v89, 0xffff0000, v151
	v_pk_mul_f32 v[86:87], v[86:87], s[24:25] op_sel_hi:[1,0]
	v_pk_mul_f32 v[88:89], v[88:89], s[24:25] op_sel_hi:[1,0]
	v_pk_fma_f32 v[78:79], v[78:79], 0.5, v[86:87] op_sel_hi:[1,0,1]
	v_pk_fma_f32 v[80:81], v[80:81], 0.5, v[88:89] op_sel_hi:[1,0,1]
	global_store_dwordx4 v[98:99], v[78:81], off offset:576
	s_nop 1
	v_lshlrev_b32_e32 v78, 16, v148
	v_and_b32_e32 v79, 0xffff0000, v148
	v_lshlrev_b32_e32 v80, 16, v149
	v_and_b32_e32 v81, 0xffff0000, v149
	v_pk_mul_f32 v[78:79], v[78:79], s[24:25] op_sel_hi:[1,0]
	v_pk_mul_f32 v[80:81], v[80:81], s[24:25] op_sel_hi:[1,0]
	v_pk_fma_f32 v[78:79], v[82:83], 0.5, v[78:79] op_sel_hi:[1,0,1]
	v_add_co_u32_e32 v82, vcc, s0, v126
	v_pk_fma_f32 v[80:81], v[84:85], 0.5, v[80:81] op_sel_hi:[1,0,1]
	s_nop 0
	v_addc_co_u32_e32 v83, vcc, 0, v127, vcc
	global_store_dwordx4 v[82:83], v[78:81], off
	s_mov_b32 s0, 0x80000
	s_nop 0
	v_lshlrev_b32_e32 v78, 16, v146
	v_and_b32_e32 v79, 0xffff0000, v146
	v_lshlrev_b32_e32 v80, 16, v147
	v_and_b32_e32 v81, 0xffff0000, v147
	v_pk_mul_f32 v[78:79], v[78:79], s[24:25] op_sel_hi:[1,0]
	v_pk_mul_f32 v[80:81], v[80:81], s[24:25] op_sel_hi:[1,0]
	v_pk_fma_f32 v[74:75], v[74:75], 0.5, v[78:79] op_sel_hi:[1,0,1]
	v_pk_fma_f32 v[76:77], v[76:77], 0.5, v[80:81] op_sel_hi:[1,0,1]
	global_store_dwordx4 v[82:83], v[74:77], off offset:64
	s_nop 1
	v_lshlrev_b32_e32 v74, 16, v144
	v_and_b32_e32 v75, 0xffff0000, v144
	v_lshlrev_b32_e32 v76, 16, v145
	v_and_b32_e32 v77, 0xffff0000, v145
	v_pk_mul_f32 v[74:75], v[74:75], s[24:25] op_sel_hi:[1,0]
	v_pk_mul_f32 v[76:77], v[76:77], s[24:25] op_sel_hi:[1,0]
	v_pk_fma_f32 v[70:71], v[70:71], 0.5, v[74:75] op_sel_hi:[1,0,1]
	v_pk_fma_f32 v[72:73], v[72:73], 0.5, v[76:77] op_sel_hi:[1,0,1]
	global_store_dwordx4 v[82:83], v[70:73], off offset:512
	s_nop 1
	v_lshlrev_b32_e32 v70, 16, v142
	v_and_b32_e32 v71, 0xffff0000, v142
	v_lshlrev_b32_e32 v72, 16, v143
	v_and_b32_e32 v73, 0xffff0000, v143
	v_pk_mul_f32 v[70:71], v[70:71], s[24:25] op_sel_hi:[1,0]
	v_pk_mul_f32 v[72:73], v[72:73], s[24:25] op_sel_hi:[1,0]
	v_pk_fma_f32 v[66:67], v[66:67], 0.5, v[70:71] op_sel_hi:[1,0,1]
	v_pk_fma_f32 v[68:69], v[68:69], 0.5, v[72:73] op_sel_hi:[1,0,1]
	global_store_dwordx4 v[82:83], v[66:69], off offset:576
	s_nop 1
	v_add_co_u32_e32 v66, vcc, s0, v140
	s_mov_b32 s0, 0x90000
	s_nop 0
	v_addc_co_u32_e32 v67, vcc, 0, v141, vcc
	global_load_dwordx2 v[72:73], v[66:67], off
	global_load_dwordx2 v[74:75], v[66:67], off offset:32
	global_load_dwordx2 v[76:77], v[66:67], off offset:256
	global_load_dwordx2 v[78:79], v[66:67], off offset:288
	v_add_co_u32_e32 v66, vcc, s0, v140
	s_mov_b32 s0, 0xa0000
	s_nop 0
	v_addc_co_u32_e32 v67, vcc, 0, v141, vcc
	global_load_dwordx2 v[80:81], v[66:67], off
	global_load_dwordx2 v[82:83], v[66:67], off offset:32
	global_load_dwordx2 v[84:85], v[66:67], off offset:256
	global_load_dwordx2 v[86:87], v[66:67], off offset:288
	v_add_co_u32_e32 v66, vcc, s0, v140
	s_mov_b32 s0, 0xb0000
	s_nop 0
	v_addc_co_u32_e32 v67, vcc, 0, v141, vcc
	global_load_dwordx2 v[88:89], v[66:67], off
	global_load_dwordx2 v[90:91], v[66:67], off offset:32
	global_load_dwordx2 v[92:93], v[66:67], off offset:256
	global_load_dwordx2 v[94:95], v[66:67], off offset:288
	v_add_co_u32_e32 v66, vcc, s0, v140
	s_mov_b32 s0, 0x100000
	s_nop 0
	v_addc_co_u32_e32 v67, vcc, 0, v141, vcc
	global_load_dwordx2 v[96:97], v[66:67], off
	global_load_dwordx2 v[70:71], v[66:67], off offset:32
	global_load_dwordx2 v[68:69], v[66:67], off offset:256
	s_nop 0
	global_load_dwordx2 v[66:67], v[66:67], off offset:288
	s_waitcnt vmcnt(15)
; __device__ __forceinline__ float bf_lo(unsigned w) { return __uint_as_float(w << 16); }
; __device__ __forceinline__ float bf_hi(unsigned w) { return __uint_as_float(w & 0xffff0000u); }
;     __device__ __forceinline__ void operator()(const f32x4 (&acc)[2][2][4][2], const Unit& u, int wr, int wc, int fr, int fq) const {
;     ...
;                     for (int n = 0; n < 2; ++n) hv[m][bj][n] = *(const u32x2*)(H + off0 + (size_t)(ai * HALF + m * 16) * D + bj * HALF + n * 16);
; #pragma unroll
;             for (int m = 0; m < 4; ++m)
; #pragma unroll
;                 for (int bj = 0; bj < 2; ++bj)
; #pragma unroll
;                     for (int n = 0; n < 2; ++n) { const u32x2 w = hv[m][bj][n]; const f32x4 h4 = {bf_lo(w.x), bf_hi(w.x), bf_lo(w.y), bf_hi(w.y)};
;                         *(f32x4*)(Z + off0 + (size_t)(ai * HALF + m * 16) * D + bj * HALF + n * 16) = h4 * ALPHA + acc[ai][bj][m][n] * 0.5f; }
	v_lshlrev_b32_e32 v98, 16, v72
	v_and_b32_e32 v99, 0xffff0000, v72
	v_lshlrev_b32_e32 v72, 16, v73
	v_and_b32_e32 v73, 0xffff0000, v73
	v_pk_mul_f32 v[72:73], v[72:73], s[24:25] op_sel_hi:[1,0]
	v_pk_mul_f32 v[98:99], v[98:99], s[24:25] op_sel_hi:[1,0]
	v_pk_fma_f32 v[64:65], v[64:65], 0.5, v[72:73] op_sel_hi:[1,0,1]
	v_add_co_u32_e32 v72, vcc, s0, v126
	v_pk_fma_f32 v[62:63], v[62:63], 0.5, v[98:99] op_sel_hi:[1,0,1]
	s_nop 0
	v_addc_co_u32_e32 v73, vcc, 0, v127, vcc
	global_store_dwordx4 v[72:73], v[62:65], off
	s_mov_b32 s0, 0x120000
	s_waitcnt vmcnt(15)
	v_lshlrev_b32_e32 v62, 16, v74
	v_and_b32_e32 v63, 0xffff0000, v74
	v_lshlrev_b32_e32 v64, 16, v75
	v_and_b32_e32 v65, 0xffff0000, v75
	v_pk_mul_f32 v[62:63], v[62:63], s[24:25] op_sel_hi:[1,0]
	v_pk_mul_f32 v[64:65], v[64:65], s[24:25] op_sel_hi:[1,0]
	v_pk_fma_f32 v[58:59], v[58:59], 0.5, v[62:63] op_sel_hi:[1,0,1]
	v_pk_fma_f32 v[60:61], v[60:61], 0.5, v[64:65] op_sel_hi:[1,0,1]
	global_store_dwordx4 v[72:73], v[58:61], off offset:64
	s_waitcnt vmcnt(15)
	s_nop 0
	v_lshlrev_b32_e32 v58, 16, v76
	v_and_b32_e32 v59, 0xffff0000, v76
	v_lshlrev_b32_e32 v60, 16, v77
	v_and_b32_e32 v61, 0xffff0000, v77
	v_pk_mul_f32 v[58:59], v[58:59], s[24:25] op_sel_hi:[1,0]
	v_pk_mul_f32 v[60:61], v[60:61], s[24:25] op_sel_hi:[1,0]
	v_pk_fma_f32 v[54:55], v[54:55], 0.5, v[58:59] op_sel_hi:[1,0,1]
	v_pk_fma_f32 v[56:57], v[56:57], 0.5, v[60:61] op_sel_hi:[1,0,1]
	global_store_dwordx4 v[72:73], v[54:57], off offset:512
	s_waitcnt vmcnt(15)
	s_nop 0
	v_lshlrev_b32_e32 v54, 16, v78
	v_and_b32_e32 v55, 0xffff0000, v78
	v_lshlrev_b32_e32 v56, 16, v79
	v_and_b32_e32 v57, 0xffff0000, v79
	v_pk_mul_f32 v[54:55], v[54:55], s[24:25] op_sel_hi:[1,0]
	v_pk_mul_f32 v[56:57], v[56:57], s[24:25] op_sel_hi:[1,0]
	v_pk_fma_f32 v[46:47], v[46:47], 0.5, v[54:55] op_sel_hi:[1,0,1]
	v_pk_fma_f32 v[48:49], v[48:49], 0.5, v[56:57] op_sel_hi:[1,0,1]
	global_store_dwordx4 v[72:73], v[46:49], off offset:576
	s_waitcnt vmcnt(15)
	s_nop 0
	v_lshlrev_b32_e32 v46, 16, v80
	v_and_b32_e32 v47, 0xffff0000, v80
	v_lshlrev_b32_e32 v48, 16, v81
	v_and_b32_e32 v49, 0xffff0000, v81
	v_pk_mul_f32 v[46:47], v[46:47], s[24:25] op_sel_hi:[1,0]
	v_pk_mul_f32 v[48:49], v[48:49], s[24:25] op_sel_hi:[1,0]
	v_pk_fma_f32 v[46:47], v[50:51], 0.5, v[46:47] op_sel_hi:[1,0,1]
	v_add_co_u32_e32 v50, vcc, s0, v126
	v_pk_fma_f32 v[48:49], v[52:53], 0.5, v[48:49] op_sel_hi:[1,0,1]
	s_nop 0
	v_addc_co_u32_e32 v51, vcc, 0, v127, vcc
	global_store_dwordx4 v[50:51], v[46:49], off
	s_mov_b32 s0, 0x140000
	s_waitcnt vmcnt(15)
	v_lshlrev_b32_e32 v46, 16, v82
	v_and_b32_e32 v47, 0xffff0000, v82
	v_lshlrev_b32_e32 v48, 16, v83
	v_and_b32_e32 v49, 0xffff0000, v83
	v_pk_mul_f32 v[46:47], v[46:47], s[24:25] op_sel_hi:[1,0]
	v_pk_mul_f32 v[48:49], v[48:49], s[24:25] op_sel_hi:[1,0]
	v_pk_fma_f32 v[42:43], v[42:43], 0.5, v[46:47] op_sel_hi:[1,0,1]
	v_pk_fma_f32 v[44:45], v[44:45], 0.5, v[48:49] op_sel_hi:[1,0,1]
	global_store_dwordx4 v[50:51], v[42:45], off offset:64
	s_waitcnt vmcnt(15)
	s_nop 0
	v_lshlrev_b32_e32 v42, 16, v84
	v_and_b32_e32 v43, 0xffff0000, v84
	v_lshlrev_b32_e32 v44, 16, v85
	v_and_b32_e32 v45, 0xffff0000, v85
	v_pk_mul_f32 v[42:43], v[42:43], s[24:25] op_sel_hi:[1,0]
	v_pk_mul_f32 v[44:45], v[44:45], s[24:25] op_sel_hi:[1,0]
	v_pk_fma_f32 v[38:39], v[38:39], 0.5, v[42:43] op_sel_hi:[1,0,1]
	v_pk_fma_f32 v[40:41], v[40:41], 0.5, v[44:45] op_sel_hi:[1,0,1]
	global_store_dwordx4 v[50:51], v[38:41], off offset:512
	s_waitcnt vmcnt(15)
	s_nop 0
	v_lshlrev_b32_e32 v38, 16, v86
	v_and_b32_e32 v39, 0xffff0000, v86
	v_lshlrev_b32_e32 v40, 16, v87
	v_and_b32_e32 v41, 0xffff0000, v87
	v_pk_mul_f32 v[38:39], v[38:39], s[24:25] op_sel_hi:[1,0]
	v_pk_mul_f32 v[40:41], v[40:41], s[24:25] op_sel_hi:[1,0]
	v_pk_fma_f32 v[30:31], v[30:31], 0.5, v[38:39] op_sel_hi:[1,0,1]
	v_pk_fma_f32 v[32:33], v[32:33], 0.5, v[40:41] op_sel_hi:[1,0,1]
	global_store_dwordx4 v[50:51], v[30:33], off offset:576
	s_waitcnt vmcnt(15)
; __device__ __forceinline__ float bf_lo(unsigned w) { return __uint_as_float(w << 16); }
; __device__ __forceinline__ float bf_hi(unsigned w) { return __uint_as_float(w & 0xffff0000u); }
; #define PG8_BAR __builtin_amdgcn_s_barrier()
;     __device__ __forceinline__ void operator()(const f32x4 (&acc)[2][2][4][2], const Unit& u, int wr, int wc, int fr, int fq) const {
;     ...
;                     for (int n = 0; n < 2; ++n) hv[m][bj][n] = *(const u32x2*)(H + off0 + (size_t)(ai * HALF + m * 16) * D + bj * HALF + n * 16);
; #pragma unroll
;             for (int m = 0; m < 4; ++m)
; #pragma unroll
;                 for (int bj = 0; bj < 2; ++bj)
; #pragma unroll
;                     for (int n = 0; n < 2; ++n) { const u32x2 w = hv[m][bj][n]; const f32x4 h4 = {bf_lo(w.x), bf_hi(w.x), bf_lo(w.y), bf_hi(w.y)};
;                         *(f32x4*)(Z + off0 + (size_t)(ai * HALF + m * 16) * D + bj * HALF + n * 16) = h4 * ALPHA + acc[ai][bj][m][n] * 0.5f; }
; template <class Epi, class Sched = StaticOrder, bool ALIGN_EPI = true>
; __device__ __forceinline__ void gemm_phase(LAS unsigned char* lds, const Gemm g, const Sched& S, const Epi& E) {
;     ...
;         if (!has_next) break;
; #pragma unroll
;         for (int a = 0; a < 2; ++a)
; #pragma unroll
;             for (int b = 0; b < 2; ++b)
; #pragma unroll
;                 for (int m = 0; m < 4; ++m)
; #pragma unroll
;                     for (int n = 0; n < 2; ++n) acc[a][b][m][n] = (f32x4){0.f, 0.f, 0.f, 0.f};
;         cur = nxt; cA = nA; cB = nB; ++ui;
;         if constexpr (ALIGN_EPI) { if (wr == 1) PG8_BAR; }
	s_nop 0
	v_lshlrev_b32_e32 v30, 16, v88
	v_and_b32_e32 v31, 0xffff0000, v88
	v_lshlrev_b32_e32 v32, 16, v89
	v_and_b32_e32 v33, 0xffff0000, v89
	v_pk_mul_f32 v[30:31], v[30:31], s[24:25] op_sel_hi:[1,0]
	v_pk_mul_f32 v[32:33], v[32:33], s[24:25] op_sel_hi:[1,0]
	v_pk_fma_f32 v[30:31], v[34:35], 0.5, v[30:31] op_sel_hi:[1,0,1]
	v_add_co_u32_e32 v34, vcc, s0, v126
	v_pk_fma_f32 v[32:33], v[36:37], 0.5, v[32:33] op_sel_hi:[1,0,1]
	s_nop 0
	v_addc_co_u32_e32 v35, vcc, 0, v127, vcc
	global_store_dwordx4 v[34:35], v[30:33], off
	s_mov_b32 s0, 0x160000
	s_waitcnt vmcnt(15)
	v_lshlrev_b32_e32 v30, 16, v90
	v_and_b32_e32 v31, 0xffff0000, v90
	v_lshlrev_b32_e32 v32, 16, v91
	v_and_b32_e32 v33, 0xffff0000, v91
	v_pk_mul_f32 v[30:31], v[30:31], s[24:25] op_sel_hi:[1,0]
	v_pk_mul_f32 v[32:33], v[32:33], s[24:25] op_sel_hi:[1,0]
	v_pk_fma_f32 v[26:27], v[26:27], 0.5, v[30:31] op_sel_hi:[1,0,1]
	v_pk_fma_f32 v[28:29], v[28:29], 0.5, v[32:33] op_sel_hi:[1,0,1]
	global_store_dwordx4 v[34:35], v[26:29], off offset:64
	s_waitcnt vmcnt(15)
	s_nop 0
	v_lshlrev_b32_e32 v26, 16, v92
	v_and_b32_e32 v27, 0xffff0000, v92
	v_lshlrev_b32_e32 v28, 16, v93
	v_and_b32_e32 v29, 0xffff0000, v93
	v_pk_mul_f32 v[26:27], v[26:27], s[24:25] op_sel_hi:[1,0]
	v_pk_mul_f32 v[28:29], v[28:29], s[24:25] op_sel_hi:[1,0]
	v_pk_fma_f32 v[22:23], v[22:23], 0.5, v[26:27] op_sel_hi:[1,0,1]
	v_pk_fma_f32 v[24:25], v[24:25], 0.5, v[28:29] op_sel_hi:[1,0,1]
	global_store_dwordx4 v[34:35], v[22:25], off offset:512
	s_waitcnt vmcnt(15)
	s_nop 0
	v_lshlrev_b32_e32 v22, 16, v94
	v_and_b32_e32 v23, 0xffff0000, v94
	v_lshlrev_b32_e32 v24, 16, v95
	v_and_b32_e32 v25, 0xffff0000, v95
	v_pk_mul_f32 v[22:23], v[22:23], s[24:25] op_sel_hi:[1,0]
	v_pk_mul_f32 v[24:25], v[24:25], s[24:25] op_sel_hi:[1,0]
	v_pk_fma_f32 v[14:15], v[14:15], 0.5, v[22:23] op_sel_hi:[1,0,1]
	v_pk_fma_f32 v[16:17], v[16:17], 0.5, v[24:25] op_sel_hi:[1,0,1]
	global_store_dwordx4 v[34:35], v[14:17], off offset:576
	s_waitcnt vmcnt(15)
	s_nop 0
	v_lshlrev_b32_e32 v14, 16, v96
	v_and_b32_e32 v15, 0xffff0000, v96
	v_lshlrev_b32_e32 v16, 16, v97
	v_and_b32_e32 v17, 0xffff0000, v97
	v_pk_mul_f32 v[14:15], v[14:15], s[24:25] op_sel_hi:[1,0]
	v_pk_mul_f32 v[16:17], v[16:17], s[24:25] op_sel_hi:[1,0]
	v_pk_fma_f32 v[14:15], v[18:19], 0.5, v[14:15] op_sel_hi:[1,0,1]
	v_add_co_u32_e32 v18, vcc, s0, v126
	v_pk_fma_f32 v[16:17], v[20:21], 0.5, v[16:17] op_sel_hi:[1,0,1]
	s_nop 0
	v_addc_co_u32_e32 v19, vcc, 0, v127, vcc
	global_store_dwordx4 v[18:19], v[14:17], off
	s_mov_b64 s[0:1], -1
	s_and_b64 vcc, exec, s[40:41]
	s_waitcnt vmcnt(15)
	v_lshlrev_b32_e32 v14, 16, v70
	v_and_b32_e32 v15, 0xffff0000, v70
	v_lshlrev_b32_e32 v16, 16, v71
	v_and_b32_e32 v17, 0xffff0000, v71
	v_pk_mul_f32 v[14:15], v[14:15], s[24:25] op_sel_hi:[1,0]
	v_pk_mul_f32 v[16:17], v[16:17], s[24:25] op_sel_hi:[1,0]
	v_pk_fma_f32 v[10:11], v[10:11], 0.5, v[14:15] op_sel_hi:[1,0,1]
	v_pk_fma_f32 v[12:13], v[12:13], 0.5, v[16:17] op_sel_hi:[1,0,1]
	global_store_dwordx4 v[18:19], v[10:13], off offset:64
	s_waitcnt vmcnt(15)
	s_nop 0
	v_lshlrev_b32_e32 v10, 16, v68
	v_and_b32_e32 v11, 0xffff0000, v68
	v_lshlrev_b32_e32 v12, 16, v69
	v_and_b32_e32 v13, 0xffff0000, v69
	v_pk_mul_f32 v[10:11], v[10:11], s[24:25] op_sel_hi:[1,0]
	v_pk_mul_f32 v[12:13], v[12:13], s[24:25] op_sel_hi:[1,0]
	v_pk_fma_f32 v[6:7], v[6:7], 0.5, v[10:11] op_sel_hi:[1,0,1]
	v_pk_fma_f32 v[8:9], v[8:9], 0.5, v[12:13] op_sel_hi:[1,0,1]
	global_store_dwordx4 v[18:19], v[6:9], off offset:512
	s_waitcnt vmcnt(15)
	s_nop 0
	v_lshlrev_b32_e32 v6, 16, v66
	v_and_b32_e32 v7, 0xffff0000, v66
	v_lshlrev_b32_e32 v8, 16, v67
	v_and_b32_e32 v9, 0xffff0000, v67
	v_pk_mul_f32 v[6:7], v[6:7], s[24:25] op_sel_hi:[1,0]
	v_pk_mul_f32 v[8:9], v[8:9], s[24:25] op_sel_hi:[1,0]
	v_pk_fma_f32 v[2:3], v[2:3], 0.5, v[6:7] op_sel_hi:[1,0,1]
	v_pk_fma_f32 v[4:5], v[4:5], 0.5, v[8:9] op_sel_hi:[1,0,1]
	global_store_dwordx4 v[18:19], v[2:5], off offset:576
	s_cbranch_vccnz .LBB0_384
	s_branch .LBB0_383

; __device__ __forceinline__ int ltid() { int t = threadIdx.x; asm volatile("" : "+v"(t)); return t; }
; __device__ __forceinline__ int lbid() { int b = blockIdx.x; asm volatile("" : "+s"(b)); return b; }
; template <int NR>
; __device__ __forceinline__ void ln_comb(bf16_t* h, const bf16_t* sb, float scale, const float* g, const float* b, int lane) {
;     u32x4 hv[NR][4], sv[NR][4]; f32x4 v[NR][4][2]; float sm[NR];
; #pragma unroll
;     for (int i = 0; i < NR; ++i)
; #pragma unroll
;         for (int j = 0; j < 4; ++j) { hv[i][j] = *(const u32x4*)(h + (size_t)i * D + 8 * lane + 512 * j); sv[i][j] = *(const u32x4*)(sb + (size_t)i * D + 8 * lane + 512 * j); }
; template <int MODE>
; __device__ __forceinline__ void ln_phase(const Args& a, const float* g, const float* b, int nrows, float scale) {
;     const int tid = ltid(), lane = tid & 63, gw = lbid() * 8 + (tid >> 6), NGW = gridDim.x * 8;
;     bf16_t* hb = (bf16_t*)(a.ws + WS_HB); f32x2* st = (f32x2*)(a.ws + WS_ST);
;     if (MODE == 2) {
;         for (int r = 4 * gw; r < NTOK; r += 4 * NGW) { float* x = a.out + (size_t)r * D; const float* const sp[4] = {x, x + D, x + 2 * D, x + 3 * D};
;             ln_rows<2, false, 4>(sp, false, x, nullptr, st, g, b, lane, nullptr, nullptr, nullptr, 0.f); }
;     } else {
;         const bf16_t* sbuf = (const bf16_t*)a.out;
;         for (int r = 3 * gw; r < NTOK; r += 3 * NGW) ln_comb<3>(hb + (size_t)r * D, sbuf + (size_t)r * D, scale, g, b, lane);
.LBB0_421:
	v_readlane_b32 s92, v254, 63
	s_andn2_b64 vcc, exec, s[0:1]
	v_readlane_b32 s93, v251, 0
	s_cbranch_vccnz .LBB0_457
	v_readlane_b32 s2, v251, 4
	v_readlane_b32 s3, v251, 5
	s_mov_b64 s[0:1], -1
	s_and_b64 vcc, exec, s[2:3]
	s_cbranch_vccz .LBB0_451
	v_readlane_b32 s0, v251, 6
	v_readlane_b32 s1, v251, 7
	s_lshl_b64 s[0:1], s[0:1], 2
	v_readlane_b32 s4, v253, 58
	v_readlane_b32 s5, v253, 59
	s_add_u32 s12, s4, s0
	v_readlane_b32 s6, v253, 60
	s_addc_u32 s13, s5, s1
	v_readlane_b32 s7, v253, 61
	s_add_u32 s30, s6, s0
	v_mov_b32_e32 v1, v155
	s_mov_b32 s0, s22
	s_addc_u32 s31, s7, s1
	s_lshl_b32 s36, s0, 3
	v_ashrrev_i32_e32 v42, 6, v1
	v_and_b32_e32 v109, 63, v1
	v_add_u32_e32 v43, s36, v42
	v_cmp_gt_i32_e32 vcc, s79, v43
	v_lshlrev_b32_e32 v44, 4, v109
	v_readlane_b32 s8, v253, 62
	v_readlane_b32 s9, v253, 63
	v_readlane_b32 s10, v254, 0
	v_readlane_b32 s11, v254, 1
	v_lshlrev_b32_e32 v2, 4, v155
	global_load_dwordx4 v[6:9], v2, s[12:13]
	global_load_dwordx4 v[14:17], v2, s[30:31]
	v_add_u32_e32 v2, 0x20000, v2
	s_waitcnt vmcnt(0)
	ds_write_b128 v2, v[6:9]
	ds_write_b128 v2, v[14:17] offset:8192
	s_waitcnt lgkmcnt(0)
	s_barrier
	s_and_saveexec_b64 s[42:43], vcc
	s_cbranch_execz .LBB0_426
	v_xor_b32_e32 v1, 1, v201
	v_cmp_lt_i32_e32 vcc, v1, v202
	v_lshl_add_u32 v46, v43, 1, v43
	v_lshlrev_b32_e32 v2, 5, v109
	v_cndmask_b32_e32 v1, v201, v1, vcc
	v_lshlrev_b32_e32 v111, 2, v1
	v_xor_b32_e32 v1, 2, v201
	v_cmp_lt_i32_e32 vcc, v1, v202
	v_mov_b32_e32 v3, v0
	v_add_u32_e32 v48, 0x20000, v2
	v_cndmask_b32_e32 v1, v201, v1, vcc
	v_lshlrev_b32_e32 v113, 2, v1
	v_xor_b32_e32 v1, 4, v201
	v_cmp_lt_i32_e32 vcc, v1, v202
	v_or_b32_e32 v4, 0x1000, v2
	v_cndmask_b32_e32 v1, v201, v1, vcc
	v_lshlrev_b32_e32 v148, 2, v1
	v_xor_b32_e32 v1, 8, v201
	v_cmp_lt_i32_e32 vcc, v1, v202
	v_or_b32_e32 v2, 0x1800, v2
	v_ashrrev_i32_e32 v47, 31, v46
	v_cndmask_b32_e32 v1, v201, v1, vcc
	v_lshlrev_b32_e32 v149, 2, v1
	v_xor_b32_e32 v1, 16, v201
	v_cmp_lt_i32_e32 vcc, v1, v202
	v_readlane_b32 s0, v253, 58
	v_mov_b32_e32 v5, v0
	v_cndmask_b32_e32 v1, v201, v1, vcc
	v_lshlrev_b32_e32 v150, 2, v1
	v_xor_b32_e32 v1, 32, v201
	v_cmp_lt_i32_e32 vcc, v1, v202
	s_waitcnt vmcnt(0)
	v_cndmask_b32_e32 v1, v201, v1, vcc
	v_lshlrev_b64 v[2:3], 12, v[46:47]
	v_readlane_b32 s4, v253, 62
	v_readlane_b32 s5, v253, 63
	v_readlane_b32 s6, v254, 0
	v_readlane_b32 s7, v254, 1
	v_lshlrev_b32_e32 v151, 2, v1
	v_mov_b32_e32 v45, v0
	v_lshl_add_u64 v[60:61], s[6:7], 0, v[2:3]
	v_lshl_add_u64 v[62:63], s[4:5], 0, v[2:3]
	s_mov_b64 s[20:21], 0
	v_readlane_b32 s1, v253, 59
	v_readlane_b32 s2, v253, 60
	v_readlane_b32 s3, v253, 61
